# v16 plus loop-edge rotation: the trip's scalar address-selection block and the pointer/counter increments moved from the loop top / loop end into the previous trip's P8 load phase
# speedup vs baseline: 1.0025x; 1.0025x over previous
; #define PG8_STAGE(bufoff, gbase, voff) do { _Pragma("unroll") for (int _i = 0; _i < 2; ++_i) \
;         __builtin_amdgcn_global_load_lds((const unsigned*)((const char*)(gbase) + (voff)[_i]), (LAS unsigned*)(lds + (bufoff) + ldsw + _i * 8192), 16, 0, 0); } while (0)
; #define PG8_LDA(dst, b, h) do { _Pragma("unroll") for (int m = 0; m < 4; ++m) _Pragma("unroll") for (int k = 0; k < 2; ++k) dst[m][k] = *(const LAS bf16x8*)(lds + PG8_SA(b, h) + aoff + m * 2048 + k * 1024); } while (0)
; #define PG8_LDB(dst, b, h) do { _Pragma("unroll") for (int n = 0; n < 2; ++n) _Pragma("unroll") for (int k = 0; k < 2; ++k) dst[n][k] = *(const LAS bf16x8*)(lds + PG8_SB(b, h) + boff + n * 2048 + k * 1024); } while (0)
; #define PG8_MMA(ai, bj, At, Bt) do { __builtin_amdgcn_s_setprio(1); _Pragma("unroll") for (int m = 0; m < 4; ++m) _Pragma("unroll") for (int n = 0; n < 2; ++n) _Pragma("unroll") for (int k = 0; k < 2; ++k) \
;         acc[ai][bj][m][n] = __builtin_amdgcn_mfma_f32_16x16x32_bf16(Bt[n][k], At[m][k], acc[ai][bj][m][n], 0, 0, 0); __builtin_amdgcn_s_setprio(0); } while (0)
; #define PG8_WAIT_L(n) asm volatile("s_waitcnt lgkmcnt(" #n ")" ::: "memory")
; template <class Epi, class Sched>
; __device__ __forceinline__ void gemm_phase(LAS unsigned char* lds, const Gemm g, const Sched& S, const Epi& E) {
;     ...
;         const bool has_next = S.next(ui + 1, nxt);
;         const char* nA = has_next ? PG8_APANEL(nxt.pm) : cA; const char* nB = has_next ? (const char*)g.Bt + (size_t)nxt.pn * tstep : cB;
;         for (int t = 0; t < nt; t += 2) {
;             const bool last = (t == nt - 2);
;             const char* a1 = cA + (size_t)(t + 1) * kstep;
;             const char* a2 = last ? nA : cA + (size_t)(t + 2) * kstep; const char* b2 = last ? nB : cB + (size_t)(t + 2) * kstep;
;             const char* a3 = a2 + kstep; const char* b3 = b2 + kstep;
;             PG8_LDB(B0, 0, 0); PG8_SCHED; PG8_LDA(At, 0, 0); PG8_STAGE(PG8_SA(1, 1), a1 + hstep, voffA);
;             PG8_WAIT_L(8); PG8_BAR; PG8_WAIT_L(0); PG8_MMA(0, 0, At, B0); PG8_BAR; PG8_SCHED;
;             PG8_LDB(B1, 0, 1); PG8_STAGE(PG8_SB(0, 0), b2, voffB);
;             PG8_BAR; PG8_WAIT_L(0); PG8_MMA(0, 1, At, B1); PG8_BAR;
;             PG8_LDA(At, 0, 1); PG8_STAGE(PG8_SA(0, 0), a2, voffA);
;             PG8_BAR; PG8_WAIT_L(0); PG8_MMA(1, 0, At, B0); PG8_BAR; PG8_SCHED;
.LBB0_164:
	s_cmp_lt_i32 s44, 0x100000
	s_cselect_b32 s24, s20, 0xffffff80
	s_cselect_b32 s25, s11, 0
	s_ashr_i32 s45, s44, 31
	s_lshl_b64 s[34:35], s[44:45], 19
	v_cmp_lt_i64_e32 vcc, s[46:47], v[152:153]
	s_add_u32 s46, s25, s34
	s_addc_u32 s47, s24, s35
	s_and_b64 s[34:35], vcc, exec
	s_cselect_b32 s34, s47, s49
	s_cselect_b32 s45, s46, s48
	s_ashr_i32 s43, s42, 31
	s_lshl_b64 s[60:61], s[42:43], 19
	s_add_u32 s76, s16, s60
	s_addc_u32 s77, s92, s61
	s_and_b64 s[60:61], vcc, exec
	s_cselect_b32 s43, s77, s39
	s_cselect_b32 s79, s76, s38
	s_add_u32 vcc_lo, s38, 0x100
	s_addc_u32 s35, s39, 0
	s_add_u32 s38, s48, 0x40080
	s_addc_u32 s39, s49, 0
	s_mov_b32 s50, -2
	v_add_u32_e32 v249, 0x10000, v167
	ds_read_b128 v[142:145], v249
	ds_read_b128 v[162:165], v249 offset:1024
	ds_read_b128 v[182:185], v249 offset:2048
	ds_read_b128 v[186:189], v249 offset:3072
	ds_read_b128 v[190:193], v169
	ds_read_b128 v[194:197], v169 offset:1024
	ds_read_b128 v[198:201], v169 offset:2048
	ds_read_b128 v[202:205], v169 offset:3072
	ds_read_b128 v[206:209], v169 offset:4096
	ds_read_b128 v[210:213], v169 offset:5120
	s_add_u32 s24, s38, 0xfffc0080
	s_addc_u32 s25, s39, -1
	s_add_i32 vcc_hi, 0, 0x10000
	s_cmp_eq_u32 s50, 12
	s_cselect_b32 s61, s34, s25
	s_cselect_b32 s60, s45, s24
	s_cselect_b32 s49, s43, s35
	s_cselect_b32 s48, s79, vcc_lo
	s_add_i32 m0, s93, 0xc000
	ds_read_b128 v[214:217], v169 offset:6144
	ds_read_b128 v[218:221], v169 offset:7168
	global_load_lds_dwordx4 v140, s[38:39]
	s_add_i32 m0, s93, 0xe000
	s_nop 0
	global_load_lds_dwordx4 v138, s[38:39]
	s_waitcnt lgkmcnt(8)
	s_barrier
	s_waitcnt lgkmcnt(0)
	s_setprio 1
	s_waitcnt lgkmcnt(0)
	v_mfma_f32_16x16x32_bf16 v[126:129], v[142:145], v[190:193], 0
	v_mfma_f32_16x16x32_bf16 v[126:129], v[162:165], v[194:197], v[126:129]
	v_mfma_f32_16x16x32_bf16 v[122:125], v[182:185], v[190:193], 0
	v_mfma_f32_16x16x32_bf16 v[122:125], v[186:189], v[194:197], v[122:125]
	v_mfma_f32_16x16x32_bf16 v[110:113], v[142:145], v[198:201], 0
	v_mfma_f32_16x16x32_bf16 v[110:113], v[162:165], v[202:205], v[110:113]
	v_mfma_f32_16x16x32_bf16 v[106:109], v[182:185], v[198:201], 0
	v_mfma_f32_16x16x32_bf16 v[106:109], v[186:189], v[202:205], v[106:109]
	v_mfma_f32_16x16x32_bf16 v[94:97], v[142:145], v[206:209], 0
	v_mfma_f32_16x16x32_bf16 v[94:97], v[162:165], v[210:213], v[94:97]
	v_mfma_f32_16x16x32_bf16 v[90:93], v[182:185], v[206:209], 0
	v_mfma_f32_16x16x32_bf16 v[90:93], v[186:189], v[210:213], v[90:93]
	v_mfma_f32_16x16x32_bf16 v[78:81], v[142:145], v[214:217], 0
	v_mfma_f32_16x16x32_bf16 v[78:81], v[162:165], v[218:221], v[78:81]
	v_mfma_f32_16x16x32_bf16 v[74:77], v[182:185], v[214:217], 0
	s_barrier
	v_mfma_f32_16x16x32_bf16 v[74:77], v[186:189], v[218:221], v[74:77]
	s_setprio 0
	s_add_i32 s51, 0, 0x14000
	s_add_i32 s24, vcc_hi, s86
	s_mov_b32 m0, s24
	ds_read_b128 v[222:225], v249 offset:16384
	ds_read_b128 v[226:229], v249 offset:17408
	ds_read_b128 v[230:233], v249 offset:18432
	ds_read_b128 v[234:237], v249 offset:19456
	global_load_lds_dwordx4 v134, s[48:49]
	s_add_i32 m0, s24, 0x2000
	s_nop 0
	global_load_lds_dwordx4 v130, s[48:49]
	s_barrier
	s_waitcnt lgkmcnt(0)
	s_setprio 1
	s_waitcnt lgkmcnt(0)
	v_mfma_f32_16x16x32_bf16 v[118:121], v[222:225], v[190:193], 0
	v_mfma_f32_16x16x32_bf16 v[118:121], v[226:229], v[194:197], v[118:121]
	v_mfma_f32_16x16x32_bf16 v[114:117], v[230:233], v[190:193], 0
	v_mfma_f32_16x16x32_bf16 v[114:117], v[234:237], v[194:197], v[114:117]
	v_mfma_f32_16x16x32_bf16 v[102:105], v[222:225], v[198:201], 0
	v_mfma_f32_16x16x32_bf16 v[102:105], v[226:229], v[202:205], v[102:105]
	v_mfma_f32_16x16x32_bf16 v[98:101], v[230:233], v[198:201], 0
	v_mfma_f32_16x16x32_bf16 v[98:101], v[234:237], v[202:205], v[98:101]
	v_mfma_f32_16x16x32_bf16 v[86:89], v[222:225], v[206:209], 0
	v_mfma_f32_16x16x32_bf16 v[86:89], v[226:229], v[210:213], v[86:89]
	v_mfma_f32_16x16x32_bf16 v[82:85], v[230:233], v[206:209], 0
	v_mfma_f32_16x16x32_bf16 v[82:85], v[234:237], v[210:213], v[82:85]
	v_mfma_f32_16x16x32_bf16 v[70:73], v[222:225], v[214:217], 0
	v_mfma_f32_16x16x32_bf16 v[70:73], v[226:229], v[218:221], v[70:73]
	v_mfma_f32_16x16x32_bf16 v[66:69], v[230:233], v[214:217], 0
	s_barrier
	v_mfma_f32_16x16x32_bf16 v[66:69], v[234:237], v[218:221], v[66:69]
	s_setprio 0
	s_mov_b32 m0, s93
	s_mov_b64 s[100:101], s[60:61]
	ds_read_b128 v[190:193], v169 offset:16384
	ds_read_b128 v[194:197], v169 offset:17408
	ds_read_b128 v[198:201], v169 offset:18432
	ds_read_b128 v[202:205], v169 offset:19456
	ds_read_b128 v[206:209], v169 offset:20480
	ds_read_b128 v[210:213], v169 offset:21504
	ds_read_b128 v[214:217], v169 offset:22528
	ds_read_b128 v[218:221], v169 offset:23552
	global_load_lds_dwordx4 v136, s[60:61]
	s_mov_b64 s[100:101], s[60:61]
	s_mov_b32 m0, s98
	s_nop 0
	global_load_lds_dwordx4 v132, s[60:61]
	s_waitcnt vmcnt(8)
	s_barrier
	s_waitcnt lgkmcnt(0)
	s_setprio 1
	s_waitcnt lgkmcnt(0)
	v_mfma_f32_16x16x32_bf16 v[62:65], v[142:145], v[190:193], 0
	v_mfma_f32_16x16x32_bf16 v[62:65], v[162:165], v[194:197], v[62:65]
	v_mfma_f32_16x16x32_bf16 v[58:61], v[182:185], v[190:193], 0
	v_mfma_f32_16x16x32_bf16 v[58:61], v[186:189], v[194:197], v[58:61]
	v_mfma_f32_16x16x32_bf16 v[46:49], v[142:145], v[198:201], 0
	v_mfma_f32_16x16x32_bf16 v[46:49], v[162:165], v[202:205], v[46:49]
	v_mfma_f32_16x16x32_bf16 v[42:45], v[182:185], v[198:201], 0
	v_mfma_f32_16x16x32_bf16 v[42:45], v[186:189], v[202:205], v[42:45]
	v_mfma_f32_16x16x32_bf16 v[30:33], v[142:145], v[206:209], 0
	v_mfma_f32_16x16x32_bf16 v[30:33], v[162:165], v[210:213], v[30:33]
	v_mfma_f32_16x16x32_bf16 v[26:29], v[182:185], v[206:209], 0
	v_mfma_f32_16x16x32_bf16 v[26:29], v[186:189], v[210:213], v[26:29]
	v_mfma_f32_16x16x32_bf16 v[14:17], v[142:145], v[214:217], 0
	v_mfma_f32_16x16x32_bf16 v[14:17], v[162:165], v[218:221], v[14:17]
	v_mfma_f32_16x16x32_bf16 v[10:13], v[182:185], v[214:217], 0
	s_barrier
; #define PG8_STAGE(bufoff, gbase, voff) do { _Pragma("unroll") for (int _i = 0; _i < 2; ++_i) \
;         __builtin_amdgcn_global_load_lds((const unsigned*)((const char*)(gbase) + (voff)[_i]), (LAS unsigned*)(lds + (bufoff) + ldsw + _i * 8192), 16, 0, 0); } while (0)
; #define PG8_LDA(dst, b, h) do { _Pragma("unroll") for (int m = 0; m < 4; ++m) _Pragma("unroll") for (int k = 0; k < 2; ++k) dst[m][k] = *(const LAS bf16x8*)(lds + PG8_SA(b, h) + aoff + m * 2048 + k * 1024); } while (0)
; #define PG8_LDB(dst, b, h) do { _Pragma("unroll") for (int n = 0; n < 2; ++n) _Pragma("unroll") for (int k = 0; k < 2; ++k) dst[n][k] = *(const LAS bf16x8*)(lds + PG8_SB(b, h) + boff + n * 2048 + k * 1024); } while (0)
; #define PG8_MMA(ai, bj, At, Bt) do { __builtin_amdgcn_s_setprio(1); _Pragma("unroll") for (int m = 0; m < 4; ++m) _Pragma("unroll") for (int n = 0; n < 2; ++n) _Pragma("unroll") for (int k = 0; k < 2; ++k) \
;         acc[ai][bj][m][n] = __builtin_amdgcn_mfma_f32_16x16x32_bf16(Bt[n][k], At[m][k], acc[ai][bj][m][n], 0, 0, 0); __builtin_amdgcn_s_setprio(0); } while (0)
; #define PG8_WAIT_V(n) asm volatile("s_waitcnt vmcnt(" #n ")" ::: "memory")
; #define PG8_WAIT_L(n) asm volatile("s_waitcnt lgkmcnt(" #n ")" ::: "memory")
; #define PG8_BAR __builtin_amdgcn_s_barrier()
; #define PG8_SCHED __builtin_amdgcn_sched_barrier(0)
; template <class Epi, class Sched>
; __device__ __forceinline__ void gemm_phase(LAS unsigned char* lds, const Gemm g, const Sched& S, const Epi& E) {
;     ...
;             PG8_STAGE(PG8_SB(0, 1), b2 + hstep, voffB);
;             PG8_WAIT_V(6); PG8_BAR; PG8_MMA(1, 1, At, B1); PG8_BAR;
;             PG8_LDB(B0, 1, 0); PG8_SCHED; PG8_LDA(At, 1, 0); PG8_STAGE(PG8_SA(0, 1), a2 + hstep, voffA);
;             PG8_WAIT_L(8); PG8_BAR; PG8_WAIT_L(0); PG8_MMA(0, 0, At, B0); PG8_BAR; PG8_SCHED;
;             PG8_LDB(B1, 1, 1); PG8_STAGE(PG8_SB(1, 0), b3, voffB);
;             PG8_BAR; PG8_WAIT_L(0); PG8_MMA(0, 1, At, B1); PG8_BAR;
;             PG8_LDA(At, 1, 1); PG8_STAGE(PG8_SA(1, 0), a3, voffA);
;             PG8_BAR; PG8_WAIT_L(0); PG8_MMA(1, 0, At, B0); PG8_BAR; PG8_SCHED;
	v_mfma_f32_16x16x32_bf16 v[10:13], v[186:189], v[218:221], v[10:13]
	s_setprio 0
	s_add_u32 s24, s48, 0x40000
	s_addc_u32 s25, s49, 0
	s_add_i32 s51, s51, s86
	s_mov_b32 m0, s51
	s_nop 0
	global_load_lds_dwordx4 v134, s[24:25]
	s_add_i32 m0, s51, 0x2000
	s_nop 0
	global_load_lds_dwordx4 v130, s[24:25]
	s_waitcnt vmcnt(6)
	s_barrier
	s_setprio 1
	v_mfma_f32_16x16x32_bf16 v[54:57], v[222:225], v[190:193], 0
	ds_read_b128 v[142:145], v249 offset:32768
	ds_read_b128 v[162:165], v249 offset:33792
	v_mfma_f32_16x16x32_bf16 v[54:57], v[226:229], v[194:197], v[54:57]
	ds_read_b128 v[182:185], v249 offset:34816
	ds_read_b128 v[186:189], v249 offset:35840
	v_mfma_f32_16x16x32_bf16 v[50:53], v[230:233], v[190:193], 0
	ds_read_b128 v[190:193], v169 offset:32768
	v_mfma_f32_16x16x32_bf16 v[50:53], v[234:237], v[194:197], v[50:53]
	ds_read_b128 v[194:197], v169 offset:33792
	v_mfma_f32_16x16x32_bf16 v[38:41], v[222:225], v[198:201], 0
	v_mfma_f32_16x16x32_bf16 v[38:41], v[226:229], v[202:205], v[38:41]
	v_mfma_f32_16x16x32_bf16 v[34:37], v[230:233], v[198:201], 0
	ds_read_b128 v[198:201], v169 offset:34816
	v_mfma_f32_16x16x32_bf16 v[34:37], v[234:237], v[202:205], v[34:37]
	ds_read_b128 v[202:205], v169 offset:35840
	v_mfma_f32_16x16x32_bf16 v[22:25], v[222:225], v[206:209], 0
	v_mfma_f32_16x16x32_bf16 v[22:25], v[226:229], v[210:213], v[22:25]
	v_mfma_f32_16x16x32_bf16 v[18:21], v[230:233], v[206:209], 0
	ds_read_b128 v[206:209], v169 offset:36864
	v_mfma_f32_16x16x32_bf16 v[18:21], v[234:237], v[210:213], v[18:21]
	ds_read_b128 v[210:213], v169 offset:37888
	v_mfma_f32_16x16x32_bf16 v[6:9], v[222:225], v[214:217], 0
	v_mfma_f32_16x16x32_bf16 v[6:9], v[226:229], v[218:221], v[6:9]
	v_mfma_f32_16x16x32_bf16 v[2:5], v[230:233], v[214:217], 0
	s_barrier
	v_mfma_f32_16x16x32_bf16 v[2:5], v[234:237], v[218:221], v[2:5]
	s_setprio 0
	s_add_i32 s51, 0, 0x18000
	s_add_u32 s24, s60, 0x40000
	s_addc_u32 s25, s61, 0
	s_mov_b32 m0, s99
	ds_read_b128 v[214:217], v169 offset:38912
	ds_read_b128 v[218:221], v169 offset:39936
	global_load_lds_dwordx4 v136, s[24:25]
	s_mov_b32 m0, s94
	s_nop 0
	global_load_lds_dwordx4 v132, s[24:25]
	s_waitcnt lgkmcnt(8)
	s_barrier
	s_waitcnt lgkmcnt(0)
	s_setprio 1
	s_waitcnt lgkmcnt(0)
	v_mfma_f32_16x16x32_bf16 v[126:129], v[142:145], v[190:193], v[126:129]
	v_mfma_f32_16x16x32_bf16 v[126:129], v[162:165], v[194:197], v[126:129]
	v_mfma_f32_16x16x32_bf16 v[122:125], v[182:185], v[190:193], v[122:125]
	v_mfma_f32_16x16x32_bf16 v[122:125], v[186:189], v[194:197], v[122:125]
	v_mfma_f32_16x16x32_bf16 v[110:113], v[142:145], v[198:201], v[110:113]
	v_mfma_f32_16x16x32_bf16 v[110:113], v[162:165], v[202:205], v[110:113]
	v_mfma_f32_16x16x32_bf16 v[106:109], v[182:185], v[198:201], v[106:109]
	v_mfma_f32_16x16x32_bf16 v[106:109], v[186:189], v[202:205], v[106:109]
	v_mfma_f32_16x16x32_bf16 v[94:97], v[142:145], v[206:209], v[94:97]
	v_mfma_f32_16x16x32_bf16 v[94:97], v[162:165], v[210:213], v[94:97]
	v_mfma_f32_16x16x32_bf16 v[90:93], v[182:185], v[206:209], v[90:93]
	v_mfma_f32_16x16x32_bf16 v[90:93], v[186:189], v[210:213], v[90:93]
	v_mfma_f32_16x16x32_bf16 v[78:81], v[142:145], v[214:217], v[78:81]
	v_mfma_f32_16x16x32_bf16 v[78:81], v[162:165], v[218:221], v[78:81]
	v_mfma_f32_16x16x32_bf16 v[74:77], v[182:185], v[214:217], v[74:77]
	s_barrier
	v_mfma_f32_16x16x32_bf16 v[74:77], v[186:189], v[218:221], v[74:77]
	s_setprio 0
	s_add_i32 s60, 0, 0x1c000
	s_add_i32 s24, s51, s86
	s_add_i32 m0, s24, 0xffffff80
	ds_read_b128 v[222:225], v249 offset:49152
	ds_read_b128 v[226:229], v249 offset:50176
	ds_read_b128 v[230:233], v249 offset:51200
	ds_read_b128 v[234:237], v249 offset:52224
	global_load_lds_dwordx4 v134, s[48:49] offset:128
	s_add_i32 m0, s24, 0x1f80
	s_nop 0
	global_load_lds_dwordx4 v130, s[48:49] offset:128
	s_barrier
	s_waitcnt lgkmcnt(0)
	s_setprio 1
	s_waitcnt lgkmcnt(0)
	v_mfma_f32_16x16x32_bf16 v[118:121], v[222:225], v[190:193], v[118:121]
	v_mfma_f32_16x16x32_bf16 v[118:121], v[226:229], v[194:197], v[118:121]
	v_mfma_f32_16x16x32_bf16 v[114:117], v[230:233], v[190:193], v[114:117]
	v_mfma_f32_16x16x32_bf16 v[114:117], v[234:237], v[194:197], v[114:117]
	v_mfma_f32_16x16x32_bf16 v[102:105], v[222:225], v[198:201], v[102:105]
	v_mfma_f32_16x16x32_bf16 v[102:105], v[226:229], v[202:205], v[102:105]
	v_mfma_f32_16x16x32_bf16 v[98:101], v[230:233], v[198:201], v[98:101]
	v_mfma_f32_16x16x32_bf16 v[98:101], v[234:237], v[202:205], v[98:101]
	v_mfma_f32_16x16x32_bf16 v[86:89], v[222:225], v[206:209], v[86:89]
	v_mfma_f32_16x16x32_bf16 v[86:89], v[226:229], v[210:213], v[86:89]
	v_mfma_f32_16x16x32_bf16 v[82:85], v[230:233], v[206:209], v[82:85]
	v_mfma_f32_16x16x32_bf16 v[82:85], v[234:237], v[210:213], v[82:85]
	v_mfma_f32_16x16x32_bf16 v[70:73], v[222:225], v[214:217], v[70:73]
	v_mfma_f32_16x16x32_bf16 v[70:73], v[226:229], v[218:221], v[70:73]
	v_mfma_f32_16x16x32_bf16 v[66:69], v[230:233], v[214:217], v[66:69]
	s_barrier
	v_mfma_f32_16x16x32_bf16 v[66:69], v[234:237], v[218:221], v[66:69]
	s_setprio 0
	s_add_i32 m0, s95, 0xffffff80
	ds_read_b128 v[190:193], v169 offset:49152
	ds_read_b128 v[194:197], v169 offset:50176
	ds_read_b128 v[198:201], v169 offset:51200
	ds_read_b128 v[202:205], v169 offset:52224
	ds_read_b128 v[206:209], v169 offset:53248
	ds_read_b128 v[210:213], v169 offset:54272
	ds_read_b128 v[214:217], v169 offset:55296
	ds_read_b128 v[218:221], v169 offset:56320
	global_load_lds_dwordx4 v136, s[100:101] offset:128
	s_add_i32 m0, s96, 0xffffff80
	s_nop 0
	global_load_lds_dwordx4 v132, s[100:101] offset:128
	s_waitcnt vmcnt(8)
	s_barrier
; #define PG8_STAGE(bufoff, gbase, voff) do { _Pragma("unroll") for (int _i = 0; _i < 2; ++_i) \
;         __builtin_amdgcn_global_load_lds((const unsigned*)((const char*)(gbase) + (voff)[_i]), (LAS unsigned*)(lds + (bufoff) + ldsw + _i * 8192), 16, 0, 0); } while (0)
; #define PG8_LDA(dst, b, h) do { _Pragma("unroll") for (int m = 0; m < 4; ++m) _Pragma("unroll") for (int k = 0; k < 2; ++k) dst[m][k] = *(const LAS bf16x8*)(lds + PG8_SA(b, h) + aoff + m * 2048 + k * 1024); } while (0)
; #define PG8_LDB(dst, b, h) do { _Pragma("unroll") for (int n = 0; n < 2; ++n) _Pragma("unroll") for (int k = 0; k < 2; ++k) dst[n][k] = *(const LAS bf16x8*)(lds + PG8_SB(b, h) + boff + n * 2048 + k * 1024); } while (0)
; #define PG8_MMA(ai, bj, At, Bt) do { __builtin_amdgcn_s_setprio(1); _Pragma("unroll") for (int m = 0; m < 4; ++m) _Pragma("unroll") for (int n = 0; n < 2; ++n) _Pragma("unroll") for (int k = 0; k < 2; ++k) \
;         acc[ai][bj][m][n] = __builtin_amdgcn_mfma_f32_16x16x32_bf16(Bt[n][k], At[m][k], acc[ai][bj][m][n], 0, 0, 0); __builtin_amdgcn_s_setprio(0); } while (0)
; #define PG8_WAIT_V(n) asm volatile("s_waitcnt vmcnt(" #n ")" ::: "memory")
; #define PG8_WAIT_L(n) asm volatile("s_waitcnt lgkmcnt(" #n ")" ::: "memory")
; #define PG8_BAR __builtin_amdgcn_s_barrier()
; #define PG8_SCHED __builtin_amdgcn_sched_barrier(0)
; template <class Epi, class Sched>
; __device__ __forceinline__ void gemm_phase(LAS unsigned char* lds, const Gemm g, const Sched& S, const Epi& E) {
;     ...
;         for (int t = 0; t < nt; t += 2) {
;             const bool last = (t == nt - 2);
;             const char* a1 = cA + (size_t)(t + 1) * kstep;
;             const char* a2 = last ? nA : cA + (size_t)(t + 2) * kstep; const char* b2 = last ? nB : cB + (size_t)(t + 2) * kstep;
;             const char* a3 = a2 + kstep; const char* b3 = b2 + kstep;
;             PG8_LDB(B0, 0, 0); PG8_SCHED; PG8_LDA(At, 0, 0); PG8_STAGE(PG8_SA(1, 1), a1 + hstep, voffA);
;             PG8_WAIT_L(8); PG8_BAR; PG8_WAIT_L(0); PG8_MMA(0, 0, At, B0); PG8_BAR; PG8_SCHED;
;             PG8_LDB(B1, 0, 1); PG8_STAGE(PG8_SB(0, 0), b2, voffB);
;     ...
;             PG8_BAR; PG8_WAIT_L(0); PG8_MMA(1, 0, At, B0); PG8_BAR; PG8_SCHED;
;             PG8_STAGE(PG8_SB(1, 1), b3 + hstep, voffB);
;             PG8_WAIT_V(6); PG8_BAR; PG8_MMA(1, 1, At, B1); PG8_BAR;
	s_waitcnt lgkmcnt(0)
	s_setprio 1
	s_waitcnt lgkmcnt(0)
	v_mfma_f32_16x16x32_bf16 v[62:65], v[142:145], v[190:193], v[62:65]
	v_mfma_f32_16x16x32_bf16 v[62:65], v[162:165], v[194:197], v[62:65]
	v_mfma_f32_16x16x32_bf16 v[58:61], v[182:185], v[190:193], v[58:61]
	v_mfma_f32_16x16x32_bf16 v[58:61], v[186:189], v[194:197], v[58:61]
	v_mfma_f32_16x16x32_bf16 v[46:49], v[142:145], v[198:201], v[46:49]
	v_mfma_f32_16x16x32_bf16 v[46:49], v[162:165], v[202:205], v[46:49]
	v_mfma_f32_16x16x32_bf16 v[42:45], v[182:185], v[198:201], v[42:45]
	v_mfma_f32_16x16x32_bf16 v[42:45], v[186:189], v[202:205], v[42:45]
	v_mfma_f32_16x16x32_bf16 v[30:33], v[142:145], v[206:209], v[30:33]
	v_mfma_f32_16x16x32_bf16 v[30:33], v[162:165], v[210:213], v[30:33]
	v_mfma_f32_16x16x32_bf16 v[26:29], v[182:185], v[206:209], v[26:29]
	v_mfma_f32_16x16x32_bf16 v[26:29], v[186:189], v[210:213], v[26:29]
	v_mfma_f32_16x16x32_bf16 v[14:17], v[142:145], v[214:217], v[14:17]
	v_mfma_f32_16x16x32_bf16 v[14:17], v[162:165], v[218:221], v[14:17]
	v_mfma_f32_16x16x32_bf16 v[10:13], v[182:185], v[214:217], v[10:13]
	s_barrier
	v_mfma_f32_16x16x32_bf16 v[10:13], v[186:189], v[218:221], v[10:13]
	s_setprio 0
	s_add_u32 s24, s48, 0x40080
	s_addc_u32 s25, s49, 0
	s_add_i32 s48, s60, s86
	s_mov_b32 m0, s48
	s_nop 0
	global_load_lds_dwordx4 v134, s[24:25]
	s_add_i32 m0, s48, 0x2000
	s_nop 0
	global_load_lds_dwordx4 v130, s[24:25]
	s_add_i32 s50, s50, 2
	s_add_u32 vcc_lo, vcc_lo, 0x100
	s_addc_u32 s35, s35, 0
	s_add_u32 s38, s38, 0x100
	s_addc_u32 s39, s39, 0
	s_add_u32 s24, s38, 0xfffc0080
	s_addc_u32 s25, s39, -1
	s_add_i32 vcc_hi, 0, 0x10000
	s_cmp_eq_u32 s50, 12
	s_cselect_b32 s61, s34, s25
	s_cselect_b32 s60, s45, s24
	s_cselect_b32 s49, s43, s35
	s_cselect_b32 s48, s79, vcc_lo
	s_waitcnt vmcnt(6)
	s_barrier
	s_setprio 1
	v_mfma_f32_16x16x32_bf16 v[54:57], v[222:225], v[190:193], v[54:57]
	ds_read_b128 v[142:145], v249
	ds_read_b128 v[162:165], v249 offset:1024
	v_mfma_f32_16x16x32_bf16 v[54:57], v[226:229], v[194:197], v[54:57]
	ds_read_b128 v[182:185], v249 offset:2048
	ds_read_b128 v[186:189], v249 offset:3072
	v_mfma_f32_16x16x32_bf16 v[50:53], v[230:233], v[190:193], v[50:53]
	ds_read_b128 v[190:193], v169
	v_mfma_f32_16x16x32_bf16 v[50:53], v[234:237], v[194:197], v[50:53]
	ds_read_b128 v[194:197], v169 offset:1024
	v_mfma_f32_16x16x32_bf16 v[38:41], v[222:225], v[198:201], v[38:41]
	v_mfma_f32_16x16x32_bf16 v[38:41], v[226:229], v[202:205], v[38:41]
	v_mfma_f32_16x16x32_bf16 v[34:37], v[230:233], v[198:201], v[34:37]
	ds_read_b128 v[198:201], v169 offset:2048
	v_mfma_f32_16x16x32_bf16 v[34:37], v[234:237], v[202:205], v[34:37]
	ds_read_b128 v[202:205], v169 offset:3072
	v_mfma_f32_16x16x32_bf16 v[22:25], v[222:225], v[206:209], v[22:25]
	v_mfma_f32_16x16x32_bf16 v[22:25], v[226:229], v[210:213], v[22:25]
	v_mfma_f32_16x16x32_bf16 v[18:21], v[230:233], v[206:209], v[18:21]
	ds_read_b128 v[206:209], v169 offset:4096
	v_mfma_f32_16x16x32_bf16 v[18:21], v[234:237], v[210:213], v[18:21]
	ds_read_b128 v[210:213], v169 offset:5120
	v_mfma_f32_16x16x32_bf16 v[6:9], v[222:225], v[214:217], v[6:9]
	v_mfma_f32_16x16x32_bf16 v[6:9], v[226:229], v[218:221], v[6:9]
	v_mfma_f32_16x16x32_bf16 v[2:5], v[230:233], v[214:217], v[2:5]
	s_barrier
	v_mfma_f32_16x16x32_bf16 v[2:5], v[234:237], v[218:221], v[2:5]
	s_setprio 0
	s_cmp_gt_u32 s50, 13
.LBB0_165:
	s_add_i32 m0, s93, 0xc000
	ds_read_b128 v[214:217], v169 offset:6144
	ds_read_b128 v[218:221], v169 offset:7168
	global_load_lds_dwordx4 v140, s[38:39]
	s_add_i32 m0, s93, 0xe000
	s_nop 0
	global_load_lds_dwordx4 v138, s[38:39]
	s_waitcnt lgkmcnt(8)
	s_barrier
	s_waitcnt lgkmcnt(0)
	s_setprio 1
	s_waitcnt lgkmcnt(0)
	v_mfma_f32_16x16x32_bf16 v[126:129], v[142:145], v[190:193], v[126:129]
	v_mfma_f32_16x16x32_bf16 v[126:129], v[162:165], v[194:197], v[126:129]
	v_mfma_f32_16x16x32_bf16 v[122:125], v[182:185], v[190:193], v[122:125]
	v_mfma_f32_16x16x32_bf16 v[122:125], v[186:189], v[194:197], v[122:125]
	v_mfma_f32_16x16x32_bf16 v[110:113], v[142:145], v[198:201], v[110:113]
	v_mfma_f32_16x16x32_bf16 v[110:113], v[162:165], v[202:205], v[110:113]
	v_mfma_f32_16x16x32_bf16 v[106:109], v[182:185], v[198:201], v[106:109]
	v_mfma_f32_16x16x32_bf16 v[106:109], v[186:189], v[202:205], v[106:109]
	v_mfma_f32_16x16x32_bf16 v[94:97], v[142:145], v[206:209], v[94:97]
	v_mfma_f32_16x16x32_bf16 v[94:97], v[162:165], v[210:213], v[94:97]
	v_mfma_f32_16x16x32_bf16 v[90:93], v[182:185], v[206:209], v[90:93]
	v_mfma_f32_16x16x32_bf16 v[90:93], v[186:189], v[210:213], v[90:93]
	v_mfma_f32_16x16x32_bf16 v[78:81], v[142:145], v[214:217], v[78:81]
	v_mfma_f32_16x16x32_bf16 v[78:81], v[162:165], v[218:221], v[78:81]
	v_mfma_f32_16x16x32_bf16 v[74:77], v[182:185], v[214:217], v[74:77]
	s_barrier
	v_mfma_f32_16x16x32_bf16 v[74:77], v[186:189], v[218:221], v[74:77]
	s_setprio 0
	s_add_i32 s51, 0, 0x14000
	s_add_i32 s24, vcc_hi, s86
	s_mov_b32 m0, s24
	ds_read_b128 v[222:225], v249 offset:16384
	ds_read_b128 v[226:229], v249 offset:17408
	ds_read_b128 v[230:233], v249 offset:18432
	ds_read_b128 v[234:237], v249 offset:19456
	global_load_lds_dwordx4 v134, s[48:49]
	s_add_i32 m0, s24, 0x2000
	s_nop 0
	global_load_lds_dwordx4 v130, s[48:49]
	s_barrier
; #define PG8_STAGE(bufoff, gbase, voff) do { _Pragma("unroll") for (int _i = 0; _i < 2; ++_i) \
;         __builtin_amdgcn_global_load_lds((const unsigned*)((const char*)(gbase) + (voff)[_i]), (LAS unsigned*)(lds + (bufoff) + ldsw + _i * 8192), 16, 0, 0); } while (0)
; #define PG8_LDA(dst, b, h) do { _Pragma("unroll") for (int m = 0; m < 4; ++m) _Pragma("unroll") for (int k = 0; k < 2; ++k) dst[m][k] = *(const LAS bf16x8*)(lds + PG8_SA(b, h) + aoff + m * 2048 + k * 1024); } while (0)
; #define PG8_LDB(dst, b, h) do { _Pragma("unroll") for (int n = 0; n < 2; ++n) _Pragma("unroll") for (int k = 0; k < 2; ++k) dst[n][k] = *(const LAS bf16x8*)(lds + PG8_SB(b, h) + boff + n * 2048 + k * 1024); } while (0)
; #define PG8_MMA(ai, bj, At, Bt) do { __builtin_amdgcn_s_setprio(1); _Pragma("unroll") for (int m = 0; m < 4; ++m) _Pragma("unroll") for (int n = 0; n < 2; ++n) _Pragma("unroll") for (int k = 0; k < 2; ++k) \
;         acc[ai][bj][m][n] = __builtin_amdgcn_mfma_f32_16x16x32_bf16(Bt[n][k], At[m][k], acc[ai][bj][m][n], 0, 0, 0); __builtin_amdgcn_s_setprio(0); } while (0)
; #define PG8_WAIT_V(n) asm volatile("s_waitcnt vmcnt(" #n ")" ::: "memory")
; #define PG8_WAIT_L(n) asm volatile("s_waitcnt lgkmcnt(" #n ")" ::: "memory")
; #define PG8_BAR __builtin_amdgcn_s_barrier()
; #define PG8_SCHED __builtin_amdgcn_sched_barrier(0)
; template <class Epi, class Sched>
; __device__ __forceinline__ void gemm_phase(LAS unsigned char* lds, const Gemm g, const Sched& S, const Epi& E) {
;     ...
;             PG8_BAR; PG8_WAIT_L(0); PG8_MMA(0, 1, At, B1); PG8_BAR;
;             PG8_LDA(At, 0, 1); PG8_STAGE(PG8_SA(0, 0), a2, voffA);
;             PG8_BAR; PG8_WAIT_L(0); PG8_MMA(1, 0, At, B0); PG8_BAR; PG8_SCHED;
;             PG8_STAGE(PG8_SB(0, 1), b2 + hstep, voffB);
;             PG8_WAIT_V(6); PG8_BAR; PG8_MMA(1, 1, At, B1); PG8_BAR;
;             PG8_LDB(B0, 1, 0); PG8_SCHED; PG8_LDA(At, 1, 0); PG8_STAGE(PG8_SA(0, 1), a2 + hstep, voffA);
;             PG8_WAIT_L(8); PG8_BAR; PG8_WAIT_L(0); PG8_MMA(0, 0, At, B0); PG8_BAR; PG8_SCHED;
	s_waitcnt lgkmcnt(0)
	s_setprio 1
	s_waitcnt lgkmcnt(0)
	v_mfma_f32_16x16x32_bf16 v[118:121], v[222:225], v[190:193], v[118:121]
	v_mfma_f32_16x16x32_bf16 v[118:121], v[226:229], v[194:197], v[118:121]
	v_mfma_f32_16x16x32_bf16 v[114:117], v[230:233], v[190:193], v[114:117]
	v_mfma_f32_16x16x32_bf16 v[114:117], v[234:237], v[194:197], v[114:117]
	v_mfma_f32_16x16x32_bf16 v[102:105], v[222:225], v[198:201], v[102:105]
	v_mfma_f32_16x16x32_bf16 v[102:105], v[226:229], v[202:205], v[102:105]
	v_mfma_f32_16x16x32_bf16 v[98:101], v[230:233], v[198:201], v[98:101]
	v_mfma_f32_16x16x32_bf16 v[98:101], v[234:237], v[202:205], v[98:101]
	v_mfma_f32_16x16x32_bf16 v[86:89], v[222:225], v[206:209], v[86:89]
	v_mfma_f32_16x16x32_bf16 v[86:89], v[226:229], v[210:213], v[86:89]
	v_mfma_f32_16x16x32_bf16 v[82:85], v[230:233], v[206:209], v[82:85]
	v_mfma_f32_16x16x32_bf16 v[82:85], v[234:237], v[210:213], v[82:85]
	v_mfma_f32_16x16x32_bf16 v[70:73], v[222:225], v[214:217], v[70:73]
	v_mfma_f32_16x16x32_bf16 v[70:73], v[226:229], v[218:221], v[70:73]
	v_mfma_f32_16x16x32_bf16 v[66:69], v[230:233], v[214:217], v[66:69]
	s_barrier
	v_mfma_f32_16x16x32_bf16 v[66:69], v[234:237], v[218:221], v[66:69]
	s_setprio 0
	s_mov_b32 m0, s93
	s_mov_b64 s[100:101], s[60:61]
	ds_read_b128 v[190:193], v169 offset:16384
	ds_read_b128 v[194:197], v169 offset:17408
	ds_read_b128 v[198:201], v169 offset:18432
	ds_read_b128 v[202:205], v169 offset:19456
	ds_read_b128 v[206:209], v169 offset:20480
	ds_read_b128 v[210:213], v169 offset:21504
	ds_read_b128 v[214:217], v169 offset:22528
	ds_read_b128 v[218:221], v169 offset:23552
	global_load_lds_dwordx4 v136, s[60:61]
	s_mov_b64 s[100:101], s[60:61]
	s_mov_b32 m0, s98
	s_nop 0
	global_load_lds_dwordx4 v132, s[60:61]
	s_waitcnt vmcnt(8)
	s_barrier
	s_waitcnt lgkmcnt(0)
	s_setprio 1
	s_waitcnt lgkmcnt(0)
	v_mfma_f32_16x16x32_bf16 v[62:65], v[142:145], v[190:193], v[62:65]
	v_mfma_f32_16x16x32_bf16 v[62:65], v[162:165], v[194:197], v[62:65]
	v_mfma_f32_16x16x32_bf16 v[58:61], v[182:185], v[190:193], v[58:61]
	v_mfma_f32_16x16x32_bf16 v[58:61], v[186:189], v[194:197], v[58:61]
	v_mfma_f32_16x16x32_bf16 v[46:49], v[142:145], v[198:201], v[46:49]
	v_mfma_f32_16x16x32_bf16 v[46:49], v[162:165], v[202:205], v[46:49]
	v_mfma_f32_16x16x32_bf16 v[42:45], v[182:185], v[198:201], v[42:45]
	v_mfma_f32_16x16x32_bf16 v[42:45], v[186:189], v[202:205], v[42:45]
	v_mfma_f32_16x16x32_bf16 v[30:33], v[142:145], v[206:209], v[30:33]
	v_mfma_f32_16x16x32_bf16 v[30:33], v[162:165], v[210:213], v[30:33]
	v_mfma_f32_16x16x32_bf16 v[26:29], v[182:185], v[206:209], v[26:29]
	v_mfma_f32_16x16x32_bf16 v[26:29], v[186:189], v[210:213], v[26:29]
	v_mfma_f32_16x16x32_bf16 v[14:17], v[142:145], v[214:217], v[14:17]
	v_mfma_f32_16x16x32_bf16 v[14:17], v[162:165], v[218:221], v[14:17]
	v_mfma_f32_16x16x32_bf16 v[10:13], v[182:185], v[214:217], v[10:13]
	s_barrier
	v_mfma_f32_16x16x32_bf16 v[10:13], v[186:189], v[218:221], v[10:13]
	s_setprio 0
	s_add_u32 s24, s48, 0x40000
	s_addc_u32 s25, s49, 0
	s_add_i32 s51, s51, s86
	s_mov_b32 m0, s51
	s_nop 0
	global_load_lds_dwordx4 v134, s[24:25]
	s_add_i32 m0, s51, 0x2000
	s_nop 0
	global_load_lds_dwordx4 v130, s[24:25]
	s_waitcnt vmcnt(6)
	s_barrier
	s_setprio 1
	v_mfma_f32_16x16x32_bf16 v[54:57], v[222:225], v[190:193], v[54:57]
	ds_read_b128 v[142:145], v249 offset:32768
	ds_read_b128 v[162:165], v249 offset:33792
	v_mfma_f32_16x16x32_bf16 v[54:57], v[226:229], v[194:197], v[54:57]
	ds_read_b128 v[182:185], v249 offset:34816
	ds_read_b128 v[186:189], v249 offset:35840
	v_mfma_f32_16x16x32_bf16 v[50:53], v[230:233], v[190:193], v[50:53]
	ds_read_b128 v[190:193], v169 offset:32768
	v_mfma_f32_16x16x32_bf16 v[50:53], v[234:237], v[194:197], v[50:53]
	ds_read_b128 v[194:197], v169 offset:33792
	v_mfma_f32_16x16x32_bf16 v[38:41], v[222:225], v[198:201], v[38:41]
	v_mfma_f32_16x16x32_bf16 v[38:41], v[226:229], v[202:205], v[38:41]
	v_mfma_f32_16x16x32_bf16 v[34:37], v[230:233], v[198:201], v[34:37]
	ds_read_b128 v[198:201], v169 offset:34816
	v_mfma_f32_16x16x32_bf16 v[34:37], v[234:237], v[202:205], v[34:37]
	ds_read_b128 v[202:205], v169 offset:35840
	v_mfma_f32_16x16x32_bf16 v[22:25], v[222:225], v[206:209], v[22:25]
	v_mfma_f32_16x16x32_bf16 v[22:25], v[226:229], v[210:213], v[22:25]
	v_mfma_f32_16x16x32_bf16 v[18:21], v[230:233], v[206:209], v[18:21]
	ds_read_b128 v[206:209], v169 offset:36864
	v_mfma_f32_16x16x32_bf16 v[18:21], v[234:237], v[210:213], v[18:21]
	ds_read_b128 v[210:213], v169 offset:37888
	v_mfma_f32_16x16x32_bf16 v[6:9], v[222:225], v[214:217], v[6:9]
	v_mfma_f32_16x16x32_bf16 v[6:9], v[226:229], v[218:221], v[6:9]
	v_mfma_f32_16x16x32_bf16 v[2:5], v[230:233], v[214:217], v[2:5]
	s_barrier
	v_mfma_f32_16x16x32_bf16 v[2:5], v[234:237], v[218:221], v[2:5]
	s_setprio 0
	s_add_i32 s51, 0, 0x18000
	s_add_u32 s24, s60, 0x40000
	s_addc_u32 s25, s61, 0
	s_mov_b32 m0, s99
	ds_read_b128 v[214:217], v169 offset:38912
	ds_read_b128 v[218:221], v169 offset:39936
	global_load_lds_dwordx4 v136, s[24:25]
	s_mov_b32 m0, s94
	s_nop 0
	global_load_lds_dwordx4 v132, s[24:25]
	s_waitcnt lgkmcnt(8)
	s_barrier
; #define PG8_STAGE(bufoff, gbase, voff) do { _Pragma("unroll") for (int _i = 0; _i < 2; ++_i) \
;         __builtin_amdgcn_global_load_lds((const unsigned*)((const char*)(gbase) + (voff)[_i]), (LAS unsigned*)(lds + (bufoff) + ldsw + _i * 8192), 16, 0, 0); } while (0)
; #define PG8_LDA(dst, b, h) do { _Pragma("unroll") for (int m = 0; m < 4; ++m) _Pragma("unroll") for (int k = 0; k < 2; ++k) dst[m][k] = *(const LAS bf16x8*)(lds + PG8_SA(b, h) + aoff + m * 2048 + k * 1024); } while (0)
; #define PG8_LDB(dst, b, h) do { _Pragma("unroll") for (int n = 0; n < 2; ++n) _Pragma("unroll") for (int k = 0; k < 2; ++k) dst[n][k] = *(const LAS bf16x8*)(lds + PG8_SB(b, h) + boff + n * 2048 + k * 1024); } while (0)
; #define PG8_MMA(ai, bj, At, Bt) do { __builtin_amdgcn_s_setprio(1); _Pragma("unroll") for (int m = 0; m < 4; ++m) _Pragma("unroll") for (int n = 0; n < 2; ++n) _Pragma("unroll") for (int k = 0; k < 2; ++k) \
;         acc[ai][bj][m][n] = __builtin_amdgcn_mfma_f32_16x16x32_bf16(Bt[n][k], At[m][k], acc[ai][bj][m][n], 0, 0, 0); __builtin_amdgcn_s_setprio(0); } while (0)
; #define PG8_WAIT_V(n) asm volatile("s_waitcnt vmcnt(" #n ")" ::: "memory")
; #define PG8_WAIT_L(n) asm volatile("s_waitcnt lgkmcnt(" #n ")" ::: "memory")
; #define PG8_BAR __builtin_amdgcn_s_barrier()
; #define PG8_SCHED __builtin_amdgcn_sched_barrier(0)
; template <class Epi, class Sched>
; __device__ __forceinline__ void gemm_phase(LAS unsigned char* lds, const Gemm g, const Sched& S, const Epi& E) {
;     ...
;             PG8_WAIT_L(8); PG8_BAR; PG8_WAIT_L(0); PG8_MMA(0, 0, At, B0); PG8_BAR; PG8_SCHED;
;             PG8_LDB(B1, 1, 1); PG8_STAGE(PG8_SB(1, 0), b3, voffB);
;             PG8_BAR; PG8_WAIT_L(0); PG8_MMA(0, 1, At, B1); PG8_BAR;
;             PG8_LDA(At, 1, 1); PG8_STAGE(PG8_SA(1, 0), a3, voffA);
;             PG8_BAR; PG8_WAIT_L(0); PG8_MMA(1, 0, At, B0); PG8_BAR; PG8_SCHED;
;             PG8_STAGE(PG8_SB(1, 1), b3 + hstep, voffB);
;             PG8_WAIT_V(6); PG8_BAR; PG8_MMA(1, 1, At, B1); PG8_BAR;
;         }
;         if (wr == 0) PG8_BAR;
	s_waitcnt lgkmcnt(0)
	s_setprio 1
	s_waitcnt lgkmcnt(0)
	v_mfma_f32_16x16x32_bf16 v[126:129], v[142:145], v[190:193], v[126:129]
	v_mfma_f32_16x16x32_bf16 v[126:129], v[162:165], v[194:197], v[126:129]
	v_mfma_f32_16x16x32_bf16 v[122:125], v[182:185], v[190:193], v[122:125]
	v_mfma_f32_16x16x32_bf16 v[122:125], v[186:189], v[194:197], v[122:125]
	v_mfma_f32_16x16x32_bf16 v[110:113], v[142:145], v[198:201], v[110:113]
	v_mfma_f32_16x16x32_bf16 v[110:113], v[162:165], v[202:205], v[110:113]
	v_mfma_f32_16x16x32_bf16 v[106:109], v[182:185], v[198:201], v[106:109]
	v_mfma_f32_16x16x32_bf16 v[106:109], v[186:189], v[202:205], v[106:109]
	v_mfma_f32_16x16x32_bf16 v[94:97], v[142:145], v[206:209], v[94:97]
	v_mfma_f32_16x16x32_bf16 v[94:97], v[162:165], v[210:213], v[94:97]
	v_mfma_f32_16x16x32_bf16 v[90:93], v[182:185], v[206:209], v[90:93]
	v_mfma_f32_16x16x32_bf16 v[90:93], v[186:189], v[210:213], v[90:93]
	v_mfma_f32_16x16x32_bf16 v[78:81], v[142:145], v[214:217], v[78:81]
	v_mfma_f32_16x16x32_bf16 v[78:81], v[162:165], v[218:221], v[78:81]
	v_mfma_f32_16x16x32_bf16 v[74:77], v[182:185], v[214:217], v[74:77]
	s_barrier
	v_mfma_f32_16x16x32_bf16 v[74:77], v[186:189], v[218:221], v[74:77]
	s_setprio 0
	s_add_i32 s60, 0, 0x1c000
	s_add_i32 s24, s51, s86
	s_add_i32 m0, s24, 0xffffff80
	ds_read_b128 v[222:225], v249 offset:49152
	ds_read_b128 v[226:229], v249 offset:50176
	ds_read_b128 v[230:233], v249 offset:51200
	ds_read_b128 v[234:237], v249 offset:52224
	global_load_lds_dwordx4 v134, s[48:49] offset:128
	s_add_i32 m0, s24, 0x1f80
	s_nop 0
	global_load_lds_dwordx4 v130, s[48:49] offset:128
	s_barrier
	s_waitcnt lgkmcnt(0)
	s_setprio 1
	s_waitcnt lgkmcnt(0)
	v_mfma_f32_16x16x32_bf16 v[118:121], v[222:225], v[190:193], v[118:121]
	v_mfma_f32_16x16x32_bf16 v[118:121], v[226:229], v[194:197], v[118:121]
	v_mfma_f32_16x16x32_bf16 v[114:117], v[230:233], v[190:193], v[114:117]
	v_mfma_f32_16x16x32_bf16 v[114:117], v[234:237], v[194:197], v[114:117]
	v_mfma_f32_16x16x32_bf16 v[102:105], v[222:225], v[198:201], v[102:105]
	v_mfma_f32_16x16x32_bf16 v[102:105], v[226:229], v[202:205], v[102:105]
	v_mfma_f32_16x16x32_bf16 v[98:101], v[230:233], v[198:201], v[98:101]
	v_mfma_f32_16x16x32_bf16 v[98:101], v[234:237], v[202:205], v[98:101]
	v_mfma_f32_16x16x32_bf16 v[86:89], v[222:225], v[206:209], v[86:89]
	v_mfma_f32_16x16x32_bf16 v[86:89], v[226:229], v[210:213], v[86:89]
	v_mfma_f32_16x16x32_bf16 v[82:85], v[230:233], v[206:209], v[82:85]
	v_mfma_f32_16x16x32_bf16 v[82:85], v[234:237], v[210:213], v[82:85]
	v_mfma_f32_16x16x32_bf16 v[70:73], v[222:225], v[214:217], v[70:73]
	v_mfma_f32_16x16x32_bf16 v[70:73], v[226:229], v[218:221], v[70:73]
	v_mfma_f32_16x16x32_bf16 v[66:69], v[230:233], v[214:217], v[66:69]
	s_barrier
	v_mfma_f32_16x16x32_bf16 v[66:69], v[234:237], v[218:221], v[66:69]
	s_setprio 0
	s_add_i32 m0, s95, 0xffffff80
	ds_read_b128 v[190:193], v169 offset:49152
	ds_read_b128 v[194:197], v169 offset:50176
	ds_read_b128 v[198:201], v169 offset:51200
	ds_read_b128 v[202:205], v169 offset:52224
	ds_read_b128 v[206:209], v169 offset:53248
	ds_read_b128 v[210:213], v169 offset:54272
	ds_read_b128 v[214:217], v169 offset:55296
	ds_read_b128 v[218:221], v169 offset:56320
	global_load_lds_dwordx4 v136, s[100:101] offset:128
	s_add_i32 m0, s96, 0xffffff80
	s_nop 0
	global_load_lds_dwordx4 v132, s[100:101] offset:128
	s_waitcnt vmcnt(8)
	s_barrier
	s_waitcnt lgkmcnt(0)
	s_setprio 1
	s_waitcnt lgkmcnt(0)
	v_mfma_f32_16x16x32_bf16 v[62:65], v[142:145], v[190:193], v[62:65]
	v_mfma_f32_16x16x32_bf16 v[62:65], v[162:165], v[194:197], v[62:65]
	v_mfma_f32_16x16x32_bf16 v[58:61], v[182:185], v[190:193], v[58:61]
	v_mfma_f32_16x16x32_bf16 v[58:61], v[186:189], v[194:197], v[58:61]
	v_mfma_f32_16x16x32_bf16 v[46:49], v[142:145], v[198:201], v[46:49]
	v_mfma_f32_16x16x32_bf16 v[46:49], v[162:165], v[202:205], v[46:49]
	v_mfma_f32_16x16x32_bf16 v[42:45], v[182:185], v[198:201], v[42:45]
	v_mfma_f32_16x16x32_bf16 v[42:45], v[186:189], v[202:205], v[42:45]
	v_mfma_f32_16x16x32_bf16 v[30:33], v[142:145], v[206:209], v[30:33]
	v_mfma_f32_16x16x32_bf16 v[30:33], v[162:165], v[210:213], v[30:33]
	v_mfma_f32_16x16x32_bf16 v[26:29], v[182:185], v[206:209], v[26:29]
	v_mfma_f32_16x16x32_bf16 v[26:29], v[186:189], v[210:213], v[26:29]
	v_mfma_f32_16x16x32_bf16 v[14:17], v[142:145], v[214:217], v[14:17]
	v_mfma_f32_16x16x32_bf16 v[14:17], v[162:165], v[218:221], v[14:17]
	v_mfma_f32_16x16x32_bf16 v[10:13], v[182:185], v[214:217], v[10:13]
	s_barrier
	v_mfma_f32_16x16x32_bf16 v[10:13], v[186:189], v[218:221], v[10:13]
	s_setprio 0
	s_add_u32 s24, s48, 0x40080
	s_addc_u32 s25, s49, 0
	s_add_i32 s48, s60, s86
	s_mov_b32 m0, s48
	s_nop 0
	global_load_lds_dwordx4 v134, s[24:25]
	s_add_i32 m0, s48, 0x2000
	s_nop 0
	global_load_lds_dwordx4 v130, s[24:25]
	s_add_i32 s50, s50, 2
	s_add_u32 vcc_lo, vcc_lo, 0x100
	s_addc_u32 s35, s35, 0
	s_add_u32 s38, s38, 0x100
	s_addc_u32 s39, s39, 0
	s_add_u32 s24, s38, 0xfffc0080
	s_addc_u32 s25, s39, -1
	s_add_i32 vcc_hi, 0, 0x10000
	s_cmp_eq_u32 s50, 12
	s_cselect_b32 s61, s34, s25
	s_cselect_b32 s60, s45, s24
	s_cselect_b32 s49, s43, s35
	s_cselect_b32 s48, s79, vcc_lo
	s_waitcnt vmcnt(6)
	s_barrier
	s_setprio 1
	v_mfma_f32_16x16x32_bf16 v[54:57], v[222:225], v[190:193], v[54:57]
	ds_read_b128 v[142:145], v249
	ds_read_b128 v[162:165], v249 offset:1024
	v_mfma_f32_16x16x32_bf16 v[54:57], v[226:229], v[194:197], v[54:57]
	ds_read_b128 v[182:185], v249 offset:2048
	ds_read_b128 v[186:189], v249 offset:3072
	v_mfma_f32_16x16x32_bf16 v[50:53], v[230:233], v[190:193], v[50:53]
	ds_read_b128 v[190:193], v169
	v_mfma_f32_16x16x32_bf16 v[50:53], v[234:237], v[194:197], v[50:53]
	ds_read_b128 v[194:197], v169 offset:1024
	v_mfma_f32_16x16x32_bf16 v[38:41], v[222:225], v[198:201], v[38:41]
	v_mfma_f32_16x16x32_bf16 v[38:41], v[226:229], v[202:205], v[38:41]
	v_mfma_f32_16x16x32_bf16 v[34:37], v[230:233], v[198:201], v[34:37]
	ds_read_b128 v[198:201], v169 offset:2048
	v_mfma_f32_16x16x32_bf16 v[34:37], v[234:237], v[202:205], v[34:37]
	ds_read_b128 v[202:205], v169 offset:3072
	v_mfma_f32_16x16x32_bf16 v[22:25], v[222:225], v[206:209], v[22:25]
	v_mfma_f32_16x16x32_bf16 v[22:25], v[226:229], v[210:213], v[22:25]
	v_mfma_f32_16x16x32_bf16 v[18:21], v[230:233], v[206:209], v[18:21]
	ds_read_b128 v[206:209], v169 offset:4096
	v_mfma_f32_16x16x32_bf16 v[18:21], v[234:237], v[210:213], v[18:21]
	ds_read_b128 v[210:213], v169 offset:5120
	v_mfma_f32_16x16x32_bf16 v[6:9], v[222:225], v[214:217], v[6:9]
	v_mfma_f32_16x16x32_bf16 v[6:9], v[226:229], v[218:221], v[6:9]
	v_mfma_f32_16x16x32_bf16 v[2:5], v[230:233], v[214:217], v[2:5]
	s_barrier
	v_mfma_f32_16x16x32_bf16 v[2:5], v[234:237], v[218:221], v[2:5]
	s_setprio 0
	s_cmp_gt_u32 s50, 13
	s_cbranch_scc0 .LBB0_165
	s_waitcnt lgkmcnt(0)
	s_and_b64 vcc, exec, s[40:41]
	s_cbranch_vccz .LBB0_168
	s_barrier

; #define PG8_STAGE(bufoff, gbase, voff) do { _Pragma("unroll") for (int _i = 0; _i < 2; ++_i) \
;         __builtin_amdgcn_global_load_lds((const unsigned*)((const char*)(gbase) + (voff)[_i]), (LAS unsigned*)(lds + (bufoff) + ldsw + _i * 8192), 16, 0, 0); } while (0)
; #define PG8_LDA(dst, b, h) do { _Pragma("unroll") for (int m = 0; m < 4; ++m) _Pragma("unroll") for (int k = 0; k < 2; ++k) dst[m][k] = *(const LAS bf16x8*)(lds + PG8_SA(b, h) + aoff + m * 2048 + k * 1024); } while (0)
; #define PG8_LDB(dst, b, h) do { _Pragma("unroll") for (int n = 0; n < 2; ++n) _Pragma("unroll") for (int k = 0; k < 2; ++k) dst[n][k] = *(const LAS bf16x8*)(lds + PG8_SB(b, h) + boff + n * 2048 + k * 1024); } while (0)
; #define PG8_MMA(ai, bj, At, Bt) do { __builtin_amdgcn_s_setprio(1); _Pragma("unroll") for (int m = 0; m < 4; ++m) _Pragma("unroll") for (int n = 0; n < 2; ++n) _Pragma("unroll") for (int k = 0; k < 2; ++k) \
;         acc[ai][bj][m][n] = __builtin_amdgcn_mfma_f32_16x16x32_bf16(Bt[n][k], At[m][k], acc[ai][bj][m][n], 0, 0, 0); __builtin_amdgcn_s_setprio(0); } while (0)
; #define PG8_WAIT_L(n) asm volatile("s_waitcnt lgkmcnt(" #n ")" ::: "memory")
; template <class Epi, class Sched>
; __device__ __forceinline__ void gemm_phase(LAS unsigned char* lds, const Gemm g, const Sched& S, const Epi& E) {
;     ...
;         const bool has_next = S.next(ui + 1, nxt);
;         const char* nA = has_next ? PG8_APANEL(nxt.pm) : cA; const char* nB = has_next ? (const char*)g.Bt + (size_t)nxt.pn * tstep : cB;
;         for (int t = 0; t < nt; t += 2) {
;             const bool last = (t == nt - 2);
;             const char* a1 = cA + (size_t)(t + 1) * kstep;
;             const char* a2 = last ? nA : cA + (size_t)(t + 2) * kstep; const char* b2 = last ? nB : cB + (size_t)(t + 2) * kstep;
;             const char* a3 = a2 + kstep; const char* b3 = b2 + kstep;
;             PG8_LDB(B0, 0, 0); PG8_SCHED; PG8_LDA(At, 0, 0); PG8_STAGE(PG8_SA(1, 1), a1 + hstep, voffA);
;             PG8_WAIT_L(8); PG8_BAR; PG8_WAIT_L(0); PG8_MMA(0, 0, At, B0); PG8_BAR; PG8_SCHED;
;             PG8_LDB(B1, 0, 1); PG8_STAGE(PG8_SB(0, 0), b2, voffB);
;             PG8_BAR; PG8_WAIT_L(0); PG8_MMA(0, 1, At, B1); PG8_BAR;
;             PG8_LDA(At, 0, 1); PG8_STAGE(PG8_SA(0, 0), a2, voffA);
;             PG8_BAR; PG8_WAIT_L(0); PG8_MMA(1, 0, At, B0); PG8_BAR; PG8_SCHED;
.LBB0_415:
	s_ashr_i32 s47, s46, 31
	s_lshl_b64 s[24:25], s[46:47], 19
	s_add_u32 s48, s82, s24
	s_addc_u32 s49, s83, s25
	s_and_b64 s[0:1], s[0:1], exec
	s_cselect_b32 s47, s49, s37
	s_cselect_b32 s61, s48, s36
	s_add_u32 s35, s36, 0x100
	s_addc_u32 s50, s37, 0
	s_add_u32 s0, s38, 0x40080
	s_addc_u32 s1, s39, 0
	s_mov_b32 s38, -2
	v_add_u32_e32 v249, 0x10000, v144
	ds_read_b128 v[164:167], v249
	ds_read_b128 v[182:185], v249 offset:1024
	ds_read_b128 v[186:189], v249 offset:2048
	ds_read_b128 v[190:193], v249 offset:3072
	ds_read_b128 v[194:197], v162
	ds_read_b128 v[198:201], v162 offset:1024
	ds_read_b128 v[202:205], v162 offset:2048
	ds_read_b128 v[206:209], v162 offset:3072
	ds_read_b128 v[210:213], v162 offset:4096
	ds_read_b128 v[214:217], v162 offset:5120
	s_add_u32 s24, s0, 0xfffc0080
	s_addc_u32 s25, s1, -1
	s_add_i32 s39, 0, 0x10000
	s_cmp_eq_u32 s38, 12
	s_cselect_b32 vcc_hi, s77, s25
	s_cselect_b32 vcc_lo, s76, s24
	s_cselect_b32 s37, s47, s50
	s_cselect_b32 s36, s61, s35
	s_add_i32 m0, s93, 0xc000
	ds_read_b128 v[218:221], v162 offset:6144
	ds_read_b128 v[222:225], v162 offset:7168
	global_load_lds_dwordx4 v140, s[0:1]
	s_add_i32 m0, s93, 0xe000
	s_nop 0
	global_load_lds_dwordx4 v138, s[0:1]
	s_waitcnt lgkmcnt(8)
	s_barrier
	s_waitcnt lgkmcnt(0)
	s_setprio 1
	s_waitcnt lgkmcnt(0)
	v_mfma_f32_16x16x32_bf16 v[126:129], v[164:167], v[194:197], 0
	v_mfma_f32_16x16x32_bf16 v[126:129], v[182:185], v[198:201], v[126:129]
	v_mfma_f32_16x16x32_bf16 v[122:125], v[186:189], v[194:197], 0
	v_mfma_f32_16x16x32_bf16 v[122:125], v[190:193], v[198:201], v[122:125]
	v_mfma_f32_16x16x32_bf16 v[118:121], v[164:167], v[202:205], 0
	v_mfma_f32_16x16x32_bf16 v[118:121], v[182:185], v[206:209], v[118:121]
	v_mfma_f32_16x16x32_bf16 v[110:113], v[186:189], v[202:205], 0
	v_mfma_f32_16x16x32_bf16 v[110:113], v[190:193], v[206:209], v[110:113]
	v_mfma_f32_16x16x32_bf16 v[102:105], v[164:167], v[210:213], 0
	v_mfma_f32_16x16x32_bf16 v[102:105], v[182:185], v[214:217], v[102:105]
	v_mfma_f32_16x16x32_bf16 v[94:97], v[186:189], v[210:213], 0
	v_mfma_f32_16x16x32_bf16 v[94:97], v[190:193], v[214:217], v[94:97]
	v_mfma_f32_16x16x32_bf16 v[86:89], v[164:167], v[218:221], 0
	v_mfma_f32_16x16x32_bf16 v[86:89], v[182:185], v[222:225], v[86:89]
	v_mfma_f32_16x16x32_bf16 v[78:81], v[186:189], v[218:221], 0
	s_barrier
	v_mfma_f32_16x16x32_bf16 v[78:81], v[190:193], v[222:225], v[78:81]
	s_setprio 0
	s_add_i32 s51, 0, 0x14000
	s_add_i32 s24, s39, s86
	ds_read_b128 v[226:229], v249 offset:16384
	ds_read_b128 v[230:233], v249 offset:17408
	ds_read_b128 v[234:237], v249 offset:18432
	ds_read_b128 v[238:241], v249 offset:19456
	s_mov_b32 m0, s24
	global_load_lds_dwordx4 v134, s[36:37]
	s_add_i32 m0, s24, 0x2000
	s_nop 0
	global_load_lds_dwordx4 v130, s[36:37]
	s_barrier
	s_waitcnt lgkmcnt(0)
	s_setprio 1
	s_waitcnt lgkmcnt(0)
	v_mfma_f32_16x16x32_bf16 v[114:117], v[226:229], v[194:197], 0
	v_mfma_f32_16x16x32_bf16 v[114:117], v[230:233], v[198:201], v[114:117]
	v_mfma_f32_16x16x32_bf16 v[106:109], v[234:237], v[194:197], 0
	v_mfma_f32_16x16x32_bf16 v[106:109], v[238:241], v[198:201], v[106:109]
	v_mfma_f32_16x16x32_bf16 v[98:101], v[226:229], v[202:205], 0
	v_mfma_f32_16x16x32_bf16 v[98:101], v[230:233], v[206:209], v[98:101]
	v_mfma_f32_16x16x32_bf16 v[90:93], v[234:237], v[202:205], 0
	v_mfma_f32_16x16x32_bf16 v[90:93], v[238:241], v[206:209], v[90:93]
	v_mfma_f32_16x16x32_bf16 v[82:85], v[226:229], v[210:213], 0
	v_mfma_f32_16x16x32_bf16 v[82:85], v[230:233], v[214:217], v[82:85]
	v_mfma_f32_16x16x32_bf16 v[74:77], v[234:237], v[210:213], 0
	v_mfma_f32_16x16x32_bf16 v[74:77], v[238:241], v[214:217], v[74:77]
	v_mfma_f32_16x16x32_bf16 v[70:73], v[226:229], v[218:221], 0
	v_mfma_f32_16x16x32_bf16 v[70:73], v[230:233], v[222:225], v[70:73]
	v_mfma_f32_16x16x32_bf16 v[66:69], v[234:237], v[218:221], 0
	s_barrier
	v_mfma_f32_16x16x32_bf16 v[66:69], v[238:241], v[222:225], v[66:69]
	s_setprio 0
	s_mov_b32 m0, s93
	ds_read_b128 v[194:197], v162 offset:16384
	ds_read_b128 v[198:201], v162 offset:17408
	ds_read_b128 v[202:205], v162 offset:18432
	ds_read_b128 v[206:209], v162 offset:19456
	ds_read_b128 v[210:213], v162 offset:20480
	ds_read_b128 v[214:217], v162 offset:21504
	ds_read_b128 v[218:221], v162 offset:22528
	ds_read_b128 v[222:225], v162 offset:23552
	global_load_lds_dwordx4 v136, vcc
	s_mov_b32 m0, s94
	s_nop 0
	global_load_lds_dwordx4 v132, vcc
	s_waitcnt vmcnt(8)
	s_barrier
	s_waitcnt lgkmcnt(0)
	s_setprio 1
	s_waitcnt lgkmcnt(0)
	v_mfma_f32_16x16x32_bf16 v[62:65], v[164:167], v[194:197], 0
	v_mfma_f32_16x16x32_bf16 v[62:65], v[182:185], v[198:201], v[62:65]
	v_mfma_f32_16x16x32_bf16 v[58:61], v[186:189], v[194:197], 0
	v_mfma_f32_16x16x32_bf16 v[58:61], v[190:193], v[198:201], v[58:61]
	v_mfma_f32_16x16x32_bf16 v[54:57], v[164:167], v[202:205], 0
	v_mfma_f32_16x16x32_bf16 v[54:57], v[182:185], v[206:209], v[54:57]
	v_mfma_f32_16x16x32_bf16 v[46:49], v[186:189], v[202:205], 0
	v_mfma_f32_16x16x32_bf16 v[46:49], v[190:193], v[206:209], v[46:49]
	v_mfma_f32_16x16x32_bf16 v[38:41], v[164:167], v[210:213], 0
	v_mfma_f32_16x16x32_bf16 v[38:41], v[182:185], v[214:217], v[38:41]
	v_mfma_f32_16x16x32_bf16 v[30:33], v[186:189], v[210:213], 0
	v_mfma_f32_16x16x32_bf16 v[30:33], v[190:193], v[214:217], v[30:33]
	v_mfma_f32_16x16x32_bf16 v[22:25], v[164:167], v[218:221], 0
	v_mfma_f32_16x16x32_bf16 v[22:25], v[182:185], v[222:225], v[22:25]
	v_mfma_f32_16x16x32_bf16 v[14:17], v[186:189], v[218:221], 0
	s_barrier
; #define PG8_STAGE(bufoff, gbase, voff) do { _Pragma("unroll") for (int _i = 0; _i < 2; ++_i) \
;         __builtin_amdgcn_global_load_lds((const unsigned*)((const char*)(gbase) + (voff)[_i]), (LAS unsigned*)(lds + (bufoff) + ldsw + _i * 8192), 16, 0, 0); } while (0)
; #define PG8_LDA(dst, b, h) do { _Pragma("unroll") for (int m = 0; m < 4; ++m) _Pragma("unroll") for (int k = 0; k < 2; ++k) dst[m][k] = *(const LAS bf16x8*)(lds + PG8_SA(b, h) + aoff + m * 2048 + k * 1024); } while (0)
; #define PG8_LDB(dst, b, h) do { _Pragma("unroll") for (int n = 0; n < 2; ++n) _Pragma("unroll") for (int k = 0; k < 2; ++k) dst[n][k] = *(const LAS bf16x8*)(lds + PG8_SB(b, h) + boff + n * 2048 + k * 1024); } while (0)
; #define PG8_MMA(ai, bj, At, Bt) do { __builtin_amdgcn_s_setprio(1); _Pragma("unroll") for (int m = 0; m < 4; ++m) _Pragma("unroll") for (int n = 0; n < 2; ++n) _Pragma("unroll") for (int k = 0; k < 2; ++k) \
;         acc[ai][bj][m][n] = __builtin_amdgcn_mfma_f32_16x16x32_bf16(Bt[n][k], At[m][k], acc[ai][bj][m][n], 0, 0, 0); __builtin_amdgcn_s_setprio(0); } while (0)
; #define PG8_WAIT_V(n) asm volatile("s_waitcnt vmcnt(" #n ")" ::: "memory")
; #define PG8_WAIT_L(n) asm volatile("s_waitcnt lgkmcnt(" #n ")" ::: "memory")
; #define PG8_BAR __builtin_amdgcn_s_barrier()
; #define PG8_SCHED __builtin_amdgcn_sched_barrier(0)
; template <class Epi, class Sched>
; __device__ __forceinline__ void gemm_phase(LAS unsigned char* lds, const Gemm g, const Sched& S, const Epi& E) {
;     ...
;             PG8_STAGE(PG8_SB(0, 1), b2 + hstep, voffB);
;             PG8_WAIT_V(6); PG8_BAR; PG8_MMA(1, 1, At, B1); PG8_BAR;
;             PG8_LDB(B0, 1, 0); PG8_SCHED; PG8_LDA(At, 1, 0); PG8_STAGE(PG8_SA(0, 1), a2 + hstep, voffA);
;             PG8_WAIT_L(8); PG8_BAR; PG8_WAIT_L(0); PG8_MMA(0, 0, At, B0); PG8_BAR; PG8_SCHED;
;             PG8_LDB(B1, 1, 1); PG8_STAGE(PG8_SB(1, 0), b3, voffB);
;             PG8_BAR; PG8_WAIT_L(0); PG8_MMA(0, 1, At, B1); PG8_BAR;
;             PG8_LDA(At, 1, 1); PG8_STAGE(PG8_SA(1, 0), a3, voffA);
;             PG8_BAR; PG8_WAIT_L(0); PG8_MMA(1, 0, At, B0); PG8_BAR; PG8_SCHED;
	v_mfma_f32_16x16x32_bf16 v[14:17], v[190:193], v[222:225], v[14:17]
	s_setprio 0
	s_add_u32 s24, s36, 0x40000
	s_addc_u32 s25, s37, 0
	s_add_i32 s39, s51, s86
	s_mov_b32 m0, s39
	s_nop 0
	global_load_lds_dwordx4 v134, s[24:25]
	s_add_i32 m0, s39, 0x2000
	s_nop 0
	global_load_lds_dwordx4 v130, s[24:25]
	s_waitcnt vmcnt(6)
	s_barrier
	s_setprio 1
	v_mfma_f32_16x16x32_bf16 v[50:53], v[226:229], v[194:197], 0
	ds_read_b128 v[164:167], v249 offset:32768
	ds_read_b128 v[182:185], v249 offset:33792
	v_mfma_f32_16x16x32_bf16 v[50:53], v[230:233], v[198:201], v[50:53]
	ds_read_b128 v[186:189], v249 offset:34816
	ds_read_b128 v[190:193], v249 offset:35840
	v_mfma_f32_16x16x32_bf16 v[42:45], v[234:237], v[194:197], 0
	ds_read_b128 v[194:197], v162 offset:32768
	v_mfma_f32_16x16x32_bf16 v[42:45], v[238:241], v[198:201], v[42:45]
	ds_read_b128 v[198:201], v162 offset:33792
	v_mfma_f32_16x16x32_bf16 v[34:37], v[226:229], v[202:205], 0
	v_mfma_f32_16x16x32_bf16 v[34:37], v[230:233], v[206:209], v[34:37]
	v_mfma_f32_16x16x32_bf16 v[26:29], v[234:237], v[202:205], 0
	ds_read_b128 v[202:205], v162 offset:34816
	v_mfma_f32_16x16x32_bf16 v[26:29], v[238:241], v[206:209], v[26:29]
	ds_read_b128 v[206:209], v162 offset:35840
	v_mfma_f32_16x16x32_bf16 v[18:21], v[226:229], v[210:213], 0
	v_mfma_f32_16x16x32_bf16 v[18:21], v[230:233], v[214:217], v[18:21]
	v_mfma_f32_16x16x32_bf16 v[10:13], v[234:237], v[210:213], 0
	ds_read_b128 v[210:213], v162 offset:36864
	v_mfma_f32_16x16x32_bf16 v[10:13], v[238:241], v[214:217], v[10:13]
	ds_read_b128 v[214:217], v162 offset:37888
	v_mfma_f32_16x16x32_bf16 v[6:9], v[226:229], v[218:221], 0
	v_mfma_f32_16x16x32_bf16 v[6:9], v[230:233], v[222:225], v[6:9]
	v_mfma_f32_16x16x32_bf16 v[2:5], v[234:237], v[218:221], 0
	s_barrier
	v_mfma_f32_16x16x32_bf16 v[2:5], v[238:241], v[222:225], v[2:5]
	s_setprio 0
	s_add_i32 s39, 0, 0x18000
	s_add_u32 s24, vcc_lo, 0x40000
	s_addc_u32 s25, vcc_hi, 0
	s_mov_b32 m0, s95
	ds_read_b128 v[218:221], v162 offset:38912
	ds_read_b128 v[222:225], v162 offset:39936
	global_load_lds_dwordx4 v136, s[24:25]
	s_mov_b32 m0, s96
	s_nop 0
	global_load_lds_dwordx4 v132, s[24:25]
	s_waitcnt lgkmcnt(8)
	s_barrier
	s_waitcnt lgkmcnt(0)
	s_setprio 1
	s_waitcnt lgkmcnt(0)
	v_mfma_f32_16x16x32_bf16 v[126:129], v[164:167], v[194:197], v[126:129]
	v_mfma_f32_16x16x32_bf16 v[126:129], v[182:185], v[198:201], v[126:129]
	v_mfma_f32_16x16x32_bf16 v[122:125], v[186:189], v[194:197], v[122:125]
	v_mfma_f32_16x16x32_bf16 v[122:125], v[190:193], v[198:201], v[122:125]
	v_mfma_f32_16x16x32_bf16 v[118:121], v[164:167], v[202:205], v[118:121]
	v_mfma_f32_16x16x32_bf16 v[118:121], v[182:185], v[206:209], v[118:121]
	v_mfma_f32_16x16x32_bf16 v[110:113], v[186:189], v[202:205], v[110:113]
	v_mfma_f32_16x16x32_bf16 v[110:113], v[190:193], v[206:209], v[110:113]
	v_mfma_f32_16x16x32_bf16 v[102:105], v[164:167], v[210:213], v[102:105]
	v_mfma_f32_16x16x32_bf16 v[102:105], v[182:185], v[214:217], v[102:105]
	v_mfma_f32_16x16x32_bf16 v[94:97], v[186:189], v[210:213], v[94:97]
	v_mfma_f32_16x16x32_bf16 v[94:97], v[190:193], v[214:217], v[94:97]
	v_mfma_f32_16x16x32_bf16 v[86:89], v[164:167], v[218:221], v[86:89]
	v_mfma_f32_16x16x32_bf16 v[86:89], v[182:185], v[222:225], v[86:89]
	v_mfma_f32_16x16x32_bf16 v[78:81], v[186:189], v[218:221], v[78:81]
	s_barrier
	v_mfma_f32_16x16x32_bf16 v[78:81], v[190:193], v[222:225], v[78:81]
	s_setprio 0
	s_add_i32 s51, 0, 0x1c000
	s_add_i32 s24, s39, s86
	s_add_i32 m0, s24, 0xffffff80
	ds_read_b128 v[226:229], v249 offset:49152
	ds_read_b128 v[230:233], v249 offset:50176
	ds_read_b128 v[234:237], v249 offset:51200
	ds_read_b128 v[238:241], v249 offset:52224
	global_load_lds_dwordx4 v134, s[36:37] offset:128
	s_add_i32 m0, s24, 0x1f80
	s_nop 0
	global_load_lds_dwordx4 v130, s[36:37] offset:128
	s_barrier
	s_waitcnt lgkmcnt(0)
	s_setprio 1
	s_waitcnt lgkmcnt(0)
	v_mfma_f32_16x16x32_bf16 v[114:117], v[226:229], v[194:197], v[114:117]
	v_mfma_f32_16x16x32_bf16 v[114:117], v[230:233], v[198:201], v[114:117]
	v_mfma_f32_16x16x32_bf16 v[106:109], v[234:237], v[194:197], v[106:109]
	v_mfma_f32_16x16x32_bf16 v[106:109], v[238:241], v[198:201], v[106:109]
	v_mfma_f32_16x16x32_bf16 v[98:101], v[226:229], v[202:205], v[98:101]
	v_mfma_f32_16x16x32_bf16 v[98:101], v[230:233], v[206:209], v[98:101]
	v_mfma_f32_16x16x32_bf16 v[90:93], v[234:237], v[202:205], v[90:93]
	v_mfma_f32_16x16x32_bf16 v[90:93], v[238:241], v[206:209], v[90:93]
	v_mfma_f32_16x16x32_bf16 v[82:85], v[226:229], v[210:213], v[82:85]
	v_mfma_f32_16x16x32_bf16 v[82:85], v[230:233], v[214:217], v[82:85]
	v_mfma_f32_16x16x32_bf16 v[74:77], v[234:237], v[210:213], v[74:77]
	v_mfma_f32_16x16x32_bf16 v[74:77], v[238:241], v[214:217], v[74:77]
	v_mfma_f32_16x16x32_bf16 v[70:73], v[226:229], v[218:221], v[70:73]
	v_mfma_f32_16x16x32_bf16 v[70:73], v[230:233], v[222:225], v[70:73]
	v_mfma_f32_16x16x32_bf16 v[66:69], v[234:237], v[218:221], v[66:69]
	s_barrier
	v_mfma_f32_16x16x32_bf16 v[66:69], v[238:241], v[222:225], v[66:69]
	s_setprio 0
	s_add_i32 m0, s97, 0xffffff80
	ds_read_b128 v[194:197], v162 offset:49152
	ds_read_b128 v[198:201], v162 offset:50176
	ds_read_b128 v[202:205], v162 offset:51200
	ds_read_b128 v[206:209], v162 offset:52224
	ds_read_b128 v[210:213], v162 offset:53248
	ds_read_b128 v[214:217], v162 offset:54272
	ds_read_b128 v[218:221], v162 offset:55296
	ds_read_b128 v[222:225], v162 offset:56320
	global_load_lds_dwordx4 v136, vcc offset:128
	s_add_i32 m0, s98, 0xffffff80
	s_nop 0
	global_load_lds_dwordx4 v132, vcc offset:128
	s_waitcnt vmcnt(8)
	s_barrier
; #define PG8_STAGE(bufoff, gbase, voff) do { _Pragma("unroll") for (int _i = 0; _i < 2; ++_i) \
;         __builtin_amdgcn_global_load_lds((const unsigned*)((const char*)(gbase) + (voff)[_i]), (LAS unsigned*)(lds + (bufoff) + ldsw + _i * 8192), 16, 0, 0); } while (0)
; #define PG8_LDA(dst, b, h) do { _Pragma("unroll") for (int m = 0; m < 4; ++m) _Pragma("unroll") for (int k = 0; k < 2; ++k) dst[m][k] = *(const LAS bf16x8*)(lds + PG8_SA(b, h) + aoff + m * 2048 + k * 1024); } while (0)
; #define PG8_LDB(dst, b, h) do { _Pragma("unroll") for (int n = 0; n < 2; ++n) _Pragma("unroll") for (int k = 0; k < 2; ++k) dst[n][k] = *(const LAS bf16x8*)(lds + PG8_SB(b, h) + boff + n * 2048 + k * 1024); } while (0)
; #define PG8_MMA(ai, bj, At, Bt) do { __builtin_amdgcn_s_setprio(1); _Pragma("unroll") for (int m = 0; m < 4; ++m) _Pragma("unroll") for (int n = 0; n < 2; ++n) _Pragma("unroll") for (int k = 0; k < 2; ++k) \
;         acc[ai][bj][m][n] = __builtin_amdgcn_mfma_f32_16x16x32_bf16(Bt[n][k], At[m][k], acc[ai][bj][m][n], 0, 0, 0); __builtin_amdgcn_s_setprio(0); } while (0)
; #define PG8_WAIT_V(n) asm volatile("s_waitcnt vmcnt(" #n ")" ::: "memory")
; #define PG8_WAIT_L(n) asm volatile("s_waitcnt lgkmcnt(" #n ")" ::: "memory")
; #define PG8_BAR __builtin_amdgcn_s_barrier()
; template <class Epi, class Sched>
; __device__ __forceinline__ void gemm_phase(LAS unsigned char* lds, const Gemm g, const Sched& S, const Epi& E) {
;     ...
;             PG8_LDB(B0, 0, 0); PG8_SCHED; PG8_LDA(At, 0, 0); PG8_STAGE(PG8_SA(1, 1), a1 + hstep, voffA);
;             PG8_WAIT_L(8); PG8_BAR; PG8_WAIT_L(0); PG8_MMA(0, 0, At, B0); PG8_BAR; PG8_SCHED;
;             PG8_LDB(B1, 0, 1); PG8_STAGE(PG8_SB(0, 0), b2, voffB);
;             PG8_BAR; PG8_WAIT_L(0); PG8_MMA(0, 1, At, B1); PG8_BAR;
;     ...
;             PG8_LDB(B0, 1, 0); PG8_SCHED; PG8_LDA(At, 1, 0); PG8_STAGE(PG8_SA(0, 1), a2 + hstep, voffA);
;             PG8_WAIT_L(8); PG8_BAR; PG8_WAIT_L(0); PG8_MMA(0, 0, At, B0); PG8_BAR; PG8_SCHED;
;             PG8_LDB(B1, 1, 1); PG8_STAGE(PG8_SB(1, 0), b3, voffB);
;             PG8_BAR; PG8_WAIT_L(0); PG8_MMA(0, 1, At, B1); PG8_BAR;
;             PG8_LDA(At, 1, 1); PG8_STAGE(PG8_SA(1, 0), a3, voffA);
;             PG8_BAR; PG8_WAIT_L(0); PG8_MMA(1, 0, At, B0); PG8_BAR; PG8_SCHED;
;             PG8_STAGE(PG8_SB(1, 1), b3 + hstep, voffB);
;             PG8_WAIT_V(6); PG8_BAR; PG8_MMA(1, 1, At, B1); PG8_BAR;
	s_waitcnt lgkmcnt(0)
	s_setprio 1
	s_waitcnt lgkmcnt(0)
	v_mfma_f32_16x16x32_bf16 v[62:65], v[164:167], v[194:197], v[62:65]
	v_mfma_f32_16x16x32_bf16 v[62:65], v[182:185], v[198:201], v[62:65]
	v_mfma_f32_16x16x32_bf16 v[58:61], v[186:189], v[194:197], v[58:61]
	v_mfma_f32_16x16x32_bf16 v[58:61], v[190:193], v[198:201], v[58:61]
	v_mfma_f32_16x16x32_bf16 v[54:57], v[164:167], v[202:205], v[54:57]
	v_mfma_f32_16x16x32_bf16 v[54:57], v[182:185], v[206:209], v[54:57]
	v_mfma_f32_16x16x32_bf16 v[46:49], v[186:189], v[202:205], v[46:49]
	v_mfma_f32_16x16x32_bf16 v[46:49], v[190:193], v[206:209], v[46:49]
	v_mfma_f32_16x16x32_bf16 v[38:41], v[164:167], v[210:213], v[38:41]
	v_mfma_f32_16x16x32_bf16 v[38:41], v[182:185], v[214:217], v[38:41]
	v_mfma_f32_16x16x32_bf16 v[30:33], v[186:189], v[210:213], v[30:33]
	v_mfma_f32_16x16x32_bf16 v[30:33], v[190:193], v[214:217], v[30:33]
	v_mfma_f32_16x16x32_bf16 v[22:25], v[164:167], v[218:221], v[22:25]
	v_mfma_f32_16x16x32_bf16 v[22:25], v[182:185], v[222:225], v[22:25]
	v_mfma_f32_16x16x32_bf16 v[14:17], v[186:189], v[218:221], v[14:17]
	s_barrier
	v_mfma_f32_16x16x32_bf16 v[14:17], v[190:193], v[222:225], v[14:17]
	s_setprio 0
	s_add_u32 s24, s36, 0x40080
	s_addc_u32 s25, s37, 0
	s_add_i32 s36, s51, s86
	s_mov_b32 m0, s36
	s_nop 0
	global_load_lds_dwordx4 v134, s[24:25]
	s_add_i32 m0, s36, 0x2000
	s_nop 0
	global_load_lds_dwordx4 v130, s[24:25]
	s_add_i32 s38, s38, 2
	s_add_u32 s35, s35, 0x100
	s_addc_u32 s50, s50, 0
	s_add_u32 s0, s0, 0x100
	s_addc_u32 s1, s1, 0
	s_add_u32 s24, s0, 0xfffc0080
	s_addc_u32 s25, s1, -1
	s_add_i32 s39, 0, 0x10000
	s_cmp_eq_u32 s38, 12
	s_cselect_b32 vcc_hi, s77, s25
	s_cselect_b32 vcc_lo, s76, s24
	s_cselect_b32 s37, s47, s50
	s_cselect_b32 s36, s61, s35
	s_waitcnt vmcnt(6)
	s_barrier
	s_setprio 1
	v_mfma_f32_16x16x32_bf16 v[50:53], v[226:229], v[194:197], v[50:53]
	ds_read_b128 v[164:167], v249
	ds_read_b128 v[182:185], v249 offset:1024
	v_mfma_f32_16x16x32_bf16 v[50:53], v[230:233], v[198:201], v[50:53]
	ds_read_b128 v[186:189], v249 offset:2048
	ds_read_b128 v[190:193], v249 offset:3072
	v_mfma_f32_16x16x32_bf16 v[42:45], v[234:237], v[194:197], v[42:45]
	ds_read_b128 v[194:197], v162
	v_mfma_f32_16x16x32_bf16 v[42:45], v[238:241], v[198:201], v[42:45]
	ds_read_b128 v[198:201], v162 offset:1024
	v_mfma_f32_16x16x32_bf16 v[34:37], v[226:229], v[202:205], v[34:37]
	v_mfma_f32_16x16x32_bf16 v[34:37], v[230:233], v[206:209], v[34:37]
	v_mfma_f32_16x16x32_bf16 v[26:29], v[234:237], v[202:205], v[26:29]
	ds_read_b128 v[202:205], v162 offset:2048
	v_mfma_f32_16x16x32_bf16 v[26:29], v[238:241], v[206:209], v[26:29]
	ds_read_b128 v[206:209], v162 offset:3072
	v_mfma_f32_16x16x32_bf16 v[18:21], v[226:229], v[210:213], v[18:21]
	v_mfma_f32_16x16x32_bf16 v[18:21], v[230:233], v[214:217], v[18:21]
	v_mfma_f32_16x16x32_bf16 v[10:13], v[234:237], v[210:213], v[10:13]
	ds_read_b128 v[210:213], v162 offset:4096
	v_mfma_f32_16x16x32_bf16 v[10:13], v[238:241], v[214:217], v[10:13]
	ds_read_b128 v[214:217], v162 offset:5120
	v_mfma_f32_16x16x32_bf16 v[6:9], v[226:229], v[218:221], v[6:9]
	v_mfma_f32_16x16x32_bf16 v[6:9], v[230:233], v[222:225], v[6:9]
	v_mfma_f32_16x16x32_bf16 v[2:5], v[234:237], v[218:221], v[2:5]
	s_barrier
	v_mfma_f32_16x16x32_bf16 v[2:5], v[238:241], v[222:225], v[2:5]
	s_setprio 0
	s_cmp_gt_u32 s38, 13
.LBB0_416:
	s_add_i32 m0, s93, 0xc000
	ds_read_b128 v[218:221], v162 offset:6144
	ds_read_b128 v[222:225], v162 offset:7168
	global_load_lds_dwordx4 v140, s[0:1]
	s_add_i32 m0, s93, 0xe000
	s_nop 0
	global_load_lds_dwordx4 v138, s[0:1]
	s_waitcnt lgkmcnt(8)
	s_barrier
	s_waitcnt lgkmcnt(0)
	s_setprio 1
	s_waitcnt lgkmcnt(0)
	v_mfma_f32_16x16x32_bf16 v[126:129], v[164:167], v[194:197], v[126:129]
	v_mfma_f32_16x16x32_bf16 v[126:129], v[182:185], v[198:201], v[126:129]
	v_mfma_f32_16x16x32_bf16 v[122:125], v[186:189], v[194:197], v[122:125]
	v_mfma_f32_16x16x32_bf16 v[122:125], v[190:193], v[198:201], v[122:125]
	v_mfma_f32_16x16x32_bf16 v[118:121], v[164:167], v[202:205], v[118:121]
	v_mfma_f32_16x16x32_bf16 v[118:121], v[182:185], v[206:209], v[118:121]
	v_mfma_f32_16x16x32_bf16 v[110:113], v[186:189], v[202:205], v[110:113]
	v_mfma_f32_16x16x32_bf16 v[110:113], v[190:193], v[206:209], v[110:113]
	v_mfma_f32_16x16x32_bf16 v[102:105], v[164:167], v[210:213], v[102:105]
	v_mfma_f32_16x16x32_bf16 v[102:105], v[182:185], v[214:217], v[102:105]
	v_mfma_f32_16x16x32_bf16 v[94:97], v[186:189], v[210:213], v[94:97]
	v_mfma_f32_16x16x32_bf16 v[94:97], v[190:193], v[214:217], v[94:97]
	v_mfma_f32_16x16x32_bf16 v[86:89], v[164:167], v[218:221], v[86:89]
	v_mfma_f32_16x16x32_bf16 v[86:89], v[182:185], v[222:225], v[86:89]
	v_mfma_f32_16x16x32_bf16 v[78:81], v[186:189], v[218:221], v[78:81]
	s_barrier
	v_mfma_f32_16x16x32_bf16 v[78:81], v[190:193], v[222:225], v[78:81]
	s_setprio 0
	s_add_i32 s51, 0, 0x14000
	s_add_i32 s24, s39, s86
	ds_read_b128 v[226:229], v249 offset:16384
	ds_read_b128 v[230:233], v249 offset:17408
	ds_read_b128 v[234:237], v249 offset:18432
	ds_read_b128 v[238:241], v249 offset:19456
	s_mov_b32 m0, s24
	global_load_lds_dwordx4 v134, s[36:37]
	s_add_i32 m0, s24, 0x2000
	s_nop 0
	global_load_lds_dwordx4 v130, s[36:37]
	s_barrier
; #define PG8_STAGE(bufoff, gbase, voff) do { _Pragma("unroll") for (int _i = 0; _i < 2; ++_i) \
;         __builtin_amdgcn_global_load_lds((const unsigned*)((const char*)(gbase) + (voff)[_i]), (LAS unsigned*)(lds + (bufoff) + ldsw + _i * 8192), 16, 0, 0); } while (0)
; #define PG8_LDA(dst, b, h) do { _Pragma("unroll") for (int m = 0; m < 4; ++m) _Pragma("unroll") for (int k = 0; k < 2; ++k) dst[m][k] = *(const LAS bf16x8*)(lds + PG8_SA(b, h) + aoff + m * 2048 + k * 1024); } while (0)
; #define PG8_LDB(dst, b, h) do { _Pragma("unroll") for (int n = 0; n < 2; ++n) _Pragma("unroll") for (int k = 0; k < 2; ++k) dst[n][k] = *(const LAS bf16x8*)(lds + PG8_SB(b, h) + boff + n * 2048 + k * 1024); } while (0)
; #define PG8_MMA(ai, bj, At, Bt) do { __builtin_amdgcn_s_setprio(1); _Pragma("unroll") for (int m = 0; m < 4; ++m) _Pragma("unroll") for (int n = 0; n < 2; ++n) _Pragma("unroll") for (int k = 0; k < 2; ++k) \
;         acc[ai][bj][m][n] = __builtin_amdgcn_mfma_f32_16x16x32_bf16(Bt[n][k], At[m][k], acc[ai][bj][m][n], 0, 0, 0); __builtin_amdgcn_s_setprio(0); } while (0)
; #define PG8_WAIT_V(n) asm volatile("s_waitcnt vmcnt(" #n ")" ::: "memory")
; #define PG8_WAIT_L(n) asm volatile("s_waitcnt lgkmcnt(" #n ")" ::: "memory")
; #define PG8_BAR __builtin_amdgcn_s_barrier()
; #define PG8_SCHED __builtin_amdgcn_sched_barrier(0)
; template <class Epi, class Sched>
; __device__ __forceinline__ void gemm_phase(LAS unsigned char* lds, const Gemm g, const Sched& S, const Epi& E) {
;     ...
;             PG8_BAR; PG8_WAIT_L(0); PG8_MMA(0, 1, At, B1); PG8_BAR;
;             PG8_LDA(At, 0, 1); PG8_STAGE(PG8_SA(0, 0), a2, voffA);
;             PG8_BAR; PG8_WAIT_L(0); PG8_MMA(1, 0, At, B0); PG8_BAR; PG8_SCHED;
;             PG8_STAGE(PG8_SB(0, 1), b2 + hstep, voffB);
;             PG8_WAIT_V(6); PG8_BAR; PG8_MMA(1, 1, At, B1); PG8_BAR;
;             PG8_LDB(B0, 1, 0); PG8_SCHED; PG8_LDA(At, 1, 0); PG8_STAGE(PG8_SA(0, 1), a2 + hstep, voffA);
;             PG8_WAIT_L(8); PG8_BAR; PG8_WAIT_L(0); PG8_MMA(0, 0, At, B0); PG8_BAR; PG8_SCHED;
	s_waitcnt lgkmcnt(0)
	s_setprio 1
	s_waitcnt lgkmcnt(0)
	v_mfma_f32_16x16x32_bf16 v[114:117], v[226:229], v[194:197], v[114:117]
	v_mfma_f32_16x16x32_bf16 v[114:117], v[230:233], v[198:201], v[114:117]
	v_mfma_f32_16x16x32_bf16 v[106:109], v[234:237], v[194:197], v[106:109]
	v_mfma_f32_16x16x32_bf16 v[106:109], v[238:241], v[198:201], v[106:109]
	v_mfma_f32_16x16x32_bf16 v[98:101], v[226:229], v[202:205], v[98:101]
	v_mfma_f32_16x16x32_bf16 v[98:101], v[230:233], v[206:209], v[98:101]
	v_mfma_f32_16x16x32_bf16 v[90:93], v[234:237], v[202:205], v[90:93]
	v_mfma_f32_16x16x32_bf16 v[90:93], v[238:241], v[206:209], v[90:93]
	v_mfma_f32_16x16x32_bf16 v[82:85], v[226:229], v[210:213], v[82:85]
	v_mfma_f32_16x16x32_bf16 v[82:85], v[230:233], v[214:217], v[82:85]
	v_mfma_f32_16x16x32_bf16 v[74:77], v[234:237], v[210:213], v[74:77]
	v_mfma_f32_16x16x32_bf16 v[74:77], v[238:241], v[214:217], v[74:77]
	v_mfma_f32_16x16x32_bf16 v[70:73], v[226:229], v[218:221], v[70:73]
	v_mfma_f32_16x16x32_bf16 v[70:73], v[230:233], v[222:225], v[70:73]
	v_mfma_f32_16x16x32_bf16 v[66:69], v[234:237], v[218:221], v[66:69]
	s_barrier
	v_mfma_f32_16x16x32_bf16 v[66:69], v[238:241], v[222:225], v[66:69]
	s_setprio 0
	s_mov_b32 m0, s93
	ds_read_b128 v[194:197], v162 offset:16384
	ds_read_b128 v[198:201], v162 offset:17408
	ds_read_b128 v[202:205], v162 offset:18432
	ds_read_b128 v[206:209], v162 offset:19456
	ds_read_b128 v[210:213], v162 offset:20480
	ds_read_b128 v[214:217], v162 offset:21504
	ds_read_b128 v[218:221], v162 offset:22528
	ds_read_b128 v[222:225], v162 offset:23552
	global_load_lds_dwordx4 v136, vcc
	s_mov_b32 m0, s94
	s_nop 0
	global_load_lds_dwordx4 v132, vcc
	s_waitcnt vmcnt(8)
	s_barrier
	s_waitcnt lgkmcnt(0)
	s_setprio 1
	s_waitcnt lgkmcnt(0)
	v_mfma_f32_16x16x32_bf16 v[62:65], v[164:167], v[194:197], v[62:65]
	v_mfma_f32_16x16x32_bf16 v[62:65], v[182:185], v[198:201], v[62:65]
	v_mfma_f32_16x16x32_bf16 v[58:61], v[186:189], v[194:197], v[58:61]
	v_mfma_f32_16x16x32_bf16 v[58:61], v[190:193], v[198:201], v[58:61]
	v_mfma_f32_16x16x32_bf16 v[54:57], v[164:167], v[202:205], v[54:57]
	v_mfma_f32_16x16x32_bf16 v[54:57], v[182:185], v[206:209], v[54:57]
	v_mfma_f32_16x16x32_bf16 v[46:49], v[186:189], v[202:205], v[46:49]
	v_mfma_f32_16x16x32_bf16 v[46:49], v[190:193], v[206:209], v[46:49]
	v_mfma_f32_16x16x32_bf16 v[38:41], v[164:167], v[210:213], v[38:41]
	v_mfma_f32_16x16x32_bf16 v[38:41], v[182:185], v[214:217], v[38:41]
	v_mfma_f32_16x16x32_bf16 v[30:33], v[186:189], v[210:213], v[30:33]
	v_mfma_f32_16x16x32_bf16 v[30:33], v[190:193], v[214:217], v[30:33]
	v_mfma_f32_16x16x32_bf16 v[22:25], v[164:167], v[218:221], v[22:25]
	v_mfma_f32_16x16x32_bf16 v[22:25], v[182:185], v[222:225], v[22:25]
	v_mfma_f32_16x16x32_bf16 v[14:17], v[186:189], v[218:221], v[14:17]
	s_barrier
	v_mfma_f32_16x16x32_bf16 v[14:17], v[190:193], v[222:225], v[14:17]
	s_setprio 0
	s_add_u32 s24, s36, 0x40000
	s_addc_u32 s25, s37, 0
	s_add_i32 s39, s51, s86
	s_mov_b32 m0, s39
	s_nop 0
	global_load_lds_dwordx4 v134, s[24:25]
	s_add_i32 m0, s39, 0x2000
	s_nop 0
	global_load_lds_dwordx4 v130, s[24:25]
	s_waitcnt vmcnt(6)
	s_barrier
	s_setprio 1
	v_mfma_f32_16x16x32_bf16 v[50:53], v[226:229], v[194:197], v[50:53]
	ds_read_b128 v[164:167], v249 offset:32768
	ds_read_b128 v[182:185], v249 offset:33792
	v_mfma_f32_16x16x32_bf16 v[50:53], v[230:233], v[198:201], v[50:53]
	ds_read_b128 v[186:189], v249 offset:34816
	ds_read_b128 v[190:193], v249 offset:35840
	v_mfma_f32_16x16x32_bf16 v[42:45], v[234:237], v[194:197], v[42:45]
	ds_read_b128 v[194:197], v162 offset:32768
	v_mfma_f32_16x16x32_bf16 v[42:45], v[238:241], v[198:201], v[42:45]
	ds_read_b128 v[198:201], v162 offset:33792
	v_mfma_f32_16x16x32_bf16 v[34:37], v[226:229], v[202:205], v[34:37]
	v_mfma_f32_16x16x32_bf16 v[34:37], v[230:233], v[206:209], v[34:37]
	v_mfma_f32_16x16x32_bf16 v[26:29], v[234:237], v[202:205], v[26:29]
	ds_read_b128 v[202:205], v162 offset:34816
	v_mfma_f32_16x16x32_bf16 v[26:29], v[238:241], v[206:209], v[26:29]
	ds_read_b128 v[206:209], v162 offset:35840
	v_mfma_f32_16x16x32_bf16 v[18:21], v[226:229], v[210:213], v[18:21]
	v_mfma_f32_16x16x32_bf16 v[18:21], v[230:233], v[214:217], v[18:21]
	v_mfma_f32_16x16x32_bf16 v[10:13], v[234:237], v[210:213], v[10:13]
	ds_read_b128 v[210:213], v162 offset:36864
	v_mfma_f32_16x16x32_bf16 v[10:13], v[238:241], v[214:217], v[10:13]
	ds_read_b128 v[214:217], v162 offset:37888
	v_mfma_f32_16x16x32_bf16 v[6:9], v[226:229], v[218:221], v[6:9]
	v_mfma_f32_16x16x32_bf16 v[6:9], v[230:233], v[222:225], v[6:9]
	v_mfma_f32_16x16x32_bf16 v[2:5], v[234:237], v[218:221], v[2:5]
	s_barrier
	v_mfma_f32_16x16x32_bf16 v[2:5], v[238:241], v[222:225], v[2:5]
	s_setprio 0
	s_add_i32 s39, 0, 0x18000
	s_add_u32 s24, vcc_lo, 0x40000
	s_addc_u32 s25, vcc_hi, 0
	s_mov_b32 m0, s95
	ds_read_b128 v[218:221], v162 offset:38912
	ds_read_b128 v[222:225], v162 offset:39936
	global_load_lds_dwordx4 v136, s[24:25]
	s_mov_b32 m0, s96
	s_nop 0
	global_load_lds_dwordx4 v132, s[24:25]
	s_waitcnt lgkmcnt(8)
	s_barrier
	s_waitcnt lgkmcnt(0)
	s_setprio 1
	s_waitcnt lgkmcnt(0)
	v_mfma_f32_16x16x32_bf16 v[126:129], v[164:167], v[194:197], v[126:129]
	v_mfma_f32_16x16x32_bf16 v[126:129], v[182:185], v[198:201], v[126:129]
	v_mfma_f32_16x16x32_bf16 v[122:125], v[186:189], v[194:197], v[122:125]
	v_mfma_f32_16x16x32_bf16 v[122:125], v[190:193], v[198:201], v[122:125]
	v_mfma_f32_16x16x32_bf16 v[118:121], v[164:167], v[202:205], v[118:121]
	v_mfma_f32_16x16x32_bf16 v[118:121], v[182:185], v[206:209], v[118:121]
	v_mfma_f32_16x16x32_bf16 v[110:113], v[186:189], v[202:205], v[110:113]
	v_mfma_f32_16x16x32_bf16 v[110:113], v[190:193], v[206:209], v[110:113]
	v_mfma_f32_16x16x32_bf16 v[102:105], v[164:167], v[210:213], v[102:105]
	v_mfma_f32_16x16x32_bf16 v[102:105], v[182:185], v[214:217], v[102:105]
	v_mfma_f32_16x16x32_bf16 v[94:97], v[186:189], v[210:213], v[94:97]
	v_mfma_f32_16x16x32_bf16 v[94:97], v[190:193], v[214:217], v[94:97]
	v_mfma_f32_16x16x32_bf16 v[86:89], v[164:167], v[218:221], v[86:89]
	v_mfma_f32_16x16x32_bf16 v[86:89], v[182:185], v[222:225], v[86:89]
	v_mfma_f32_16x16x32_bf16 v[78:81], v[186:189], v[218:221], v[78:81]
	s_barrier
; #define PG8_STAGE(bufoff, gbase, voff) do { _Pragma("unroll") for (int _i = 0; _i < 2; ++_i) \
;         __builtin_amdgcn_global_load_lds((const unsigned*)((const char*)(gbase) + (voff)[_i]), (LAS unsigned*)(lds + (bufoff) + ldsw + _i * 8192), 16, 0, 0); } while (0)
; #define PG8_LDA(dst, b, h) do { _Pragma("unroll") for (int m = 0; m < 4; ++m) _Pragma("unroll") for (int k = 0; k < 2; ++k) dst[m][k] = *(const LAS bf16x8*)(lds + PG8_SA(b, h) + aoff + m * 2048 + k * 1024); } while (0)
; #define PG8_LDB(dst, b, h) do { _Pragma("unroll") for (int n = 0; n < 2; ++n) _Pragma("unroll") for (int k = 0; k < 2; ++k) dst[n][k] = *(const LAS bf16x8*)(lds + PG8_SB(b, h) + boff + n * 2048 + k * 1024); } while (0)
; #define PG8_MMA(ai, bj, At, Bt) do { __builtin_amdgcn_s_setprio(1); _Pragma("unroll") for (int m = 0; m < 4; ++m) _Pragma("unroll") for (int n = 0; n < 2; ++n) _Pragma("unroll") for (int k = 0; k < 2; ++k) \
;         acc[ai][bj][m][n] = __builtin_amdgcn_mfma_f32_16x16x32_bf16(Bt[n][k], At[m][k], acc[ai][bj][m][n], 0, 0, 0); __builtin_amdgcn_s_setprio(0); } while (0)
; #define PG8_WAIT_V(n) asm volatile("s_waitcnt vmcnt(" #n ")" ::: "memory")
; #define PG8_WAIT_L(n) asm volatile("s_waitcnt lgkmcnt(" #n ")" ::: "memory")
; #define PG8_BAR __builtin_amdgcn_s_barrier()
; #define PG8_SCHED __builtin_amdgcn_sched_barrier(0)
; template <class Epi, class Sched>
; __device__ __forceinline__ void gemm_phase(LAS unsigned char* lds, const Gemm g, const Sched& S, const Epi& E) {
;     ...
;             PG8_LDB(B1, 1, 1); PG8_STAGE(PG8_SB(1, 0), b3, voffB);
;             PG8_BAR; PG8_WAIT_L(0); PG8_MMA(0, 1, At, B1); PG8_BAR;
;             PG8_LDA(At, 1, 1); PG8_STAGE(PG8_SA(1, 0), a3, voffA);
;             PG8_BAR; PG8_WAIT_L(0); PG8_MMA(1, 0, At, B0); PG8_BAR; PG8_SCHED;
;             PG8_STAGE(PG8_SB(1, 1), b3 + hstep, voffB);
;             PG8_WAIT_V(6); PG8_BAR; PG8_MMA(1, 1, At, B1); PG8_BAR;
;         }
;         if (wr == 0) PG8_BAR;
	v_mfma_f32_16x16x32_bf16 v[78:81], v[190:193], v[222:225], v[78:81]
	s_setprio 0
	s_add_i32 s51, 0, 0x1c000
	s_add_i32 s24, s39, s86
	s_add_i32 m0, s24, 0xffffff80
	ds_read_b128 v[226:229], v249 offset:49152
	ds_read_b128 v[230:233], v249 offset:50176
	ds_read_b128 v[234:237], v249 offset:51200
	ds_read_b128 v[238:241], v249 offset:52224
	global_load_lds_dwordx4 v134, s[36:37] offset:128
	s_add_i32 m0, s24, 0x1f80
	s_nop 0
	global_load_lds_dwordx4 v130, s[36:37] offset:128
	s_barrier
	s_waitcnt lgkmcnt(0)
	s_setprio 1
	s_waitcnt lgkmcnt(0)
	v_mfma_f32_16x16x32_bf16 v[114:117], v[226:229], v[194:197], v[114:117]
	v_mfma_f32_16x16x32_bf16 v[114:117], v[230:233], v[198:201], v[114:117]
	v_mfma_f32_16x16x32_bf16 v[106:109], v[234:237], v[194:197], v[106:109]
	v_mfma_f32_16x16x32_bf16 v[106:109], v[238:241], v[198:201], v[106:109]
	v_mfma_f32_16x16x32_bf16 v[98:101], v[226:229], v[202:205], v[98:101]
	v_mfma_f32_16x16x32_bf16 v[98:101], v[230:233], v[206:209], v[98:101]
	v_mfma_f32_16x16x32_bf16 v[90:93], v[234:237], v[202:205], v[90:93]
	v_mfma_f32_16x16x32_bf16 v[90:93], v[238:241], v[206:209], v[90:93]
	v_mfma_f32_16x16x32_bf16 v[82:85], v[226:229], v[210:213], v[82:85]
	v_mfma_f32_16x16x32_bf16 v[82:85], v[230:233], v[214:217], v[82:85]
	v_mfma_f32_16x16x32_bf16 v[74:77], v[234:237], v[210:213], v[74:77]
	v_mfma_f32_16x16x32_bf16 v[74:77], v[238:241], v[214:217], v[74:77]
	v_mfma_f32_16x16x32_bf16 v[70:73], v[226:229], v[218:221], v[70:73]
	v_mfma_f32_16x16x32_bf16 v[70:73], v[230:233], v[222:225], v[70:73]
	v_mfma_f32_16x16x32_bf16 v[66:69], v[234:237], v[218:221], v[66:69]
	s_barrier
	v_mfma_f32_16x16x32_bf16 v[66:69], v[238:241], v[222:225], v[66:69]
	s_setprio 0
	s_add_i32 m0, s97, 0xffffff80
	ds_read_b128 v[194:197], v162 offset:49152
	ds_read_b128 v[198:201], v162 offset:50176
	ds_read_b128 v[202:205], v162 offset:51200
	ds_read_b128 v[206:209], v162 offset:52224
	ds_read_b128 v[210:213], v162 offset:53248
	ds_read_b128 v[214:217], v162 offset:54272
	ds_read_b128 v[218:221], v162 offset:55296
	ds_read_b128 v[222:225], v162 offset:56320
	global_load_lds_dwordx4 v136, vcc offset:128
	s_add_i32 m0, s98, 0xffffff80
	s_nop 0
	global_load_lds_dwordx4 v132, vcc offset:128
	s_waitcnt vmcnt(8)
	s_barrier
	s_waitcnt lgkmcnt(0)
	s_setprio 1
	s_waitcnt lgkmcnt(0)
	v_mfma_f32_16x16x32_bf16 v[62:65], v[164:167], v[194:197], v[62:65]
	v_mfma_f32_16x16x32_bf16 v[62:65], v[182:185], v[198:201], v[62:65]
	v_mfma_f32_16x16x32_bf16 v[58:61], v[186:189], v[194:197], v[58:61]
	v_mfma_f32_16x16x32_bf16 v[58:61], v[190:193], v[198:201], v[58:61]
	v_mfma_f32_16x16x32_bf16 v[54:57], v[164:167], v[202:205], v[54:57]
	v_mfma_f32_16x16x32_bf16 v[54:57], v[182:185], v[206:209], v[54:57]
	v_mfma_f32_16x16x32_bf16 v[46:49], v[186:189], v[202:205], v[46:49]
	v_mfma_f32_16x16x32_bf16 v[46:49], v[190:193], v[206:209], v[46:49]
	v_mfma_f32_16x16x32_bf16 v[38:41], v[164:167], v[210:213], v[38:41]
	v_mfma_f32_16x16x32_bf16 v[38:41], v[182:185], v[214:217], v[38:41]
	v_mfma_f32_16x16x32_bf16 v[30:33], v[186:189], v[210:213], v[30:33]
	v_mfma_f32_16x16x32_bf16 v[30:33], v[190:193], v[214:217], v[30:33]
	v_mfma_f32_16x16x32_bf16 v[22:25], v[164:167], v[218:221], v[22:25]
	v_mfma_f32_16x16x32_bf16 v[22:25], v[182:185], v[222:225], v[22:25]
	v_mfma_f32_16x16x32_bf16 v[14:17], v[186:189], v[218:221], v[14:17]
	s_barrier
	v_mfma_f32_16x16x32_bf16 v[14:17], v[190:193], v[222:225], v[14:17]
	s_setprio 0
	s_add_u32 s24, s36, 0x40080
	s_addc_u32 s25, s37, 0
	s_add_i32 s36, s51, s86
	s_mov_b32 m0, s36
	s_nop 0
	global_load_lds_dwordx4 v134, s[24:25]
	s_add_i32 m0, s36, 0x2000
	s_nop 0
	global_load_lds_dwordx4 v130, s[24:25]
	s_add_i32 s38, s38, 2
	s_add_u32 s35, s35, 0x100
	s_addc_u32 s50, s50, 0
	s_add_u32 s0, s0, 0x100
	s_addc_u32 s1, s1, 0
	s_add_u32 s24, s0, 0xfffc0080
	s_addc_u32 s25, s1, -1
	s_add_i32 s39, 0, 0x10000
	s_cmp_eq_u32 s38, 12
	s_cselect_b32 vcc_hi, s77, s25
	s_cselect_b32 vcc_lo, s76, s24
	s_cselect_b32 s37, s47, s50
	s_cselect_b32 s36, s61, s35
	s_waitcnt vmcnt(6)
	s_barrier
	s_setprio 1
	v_mfma_f32_16x16x32_bf16 v[50:53], v[226:229], v[194:197], v[50:53]
	ds_read_b128 v[164:167], v249
	ds_read_b128 v[182:185], v249 offset:1024
	v_mfma_f32_16x16x32_bf16 v[50:53], v[230:233], v[198:201], v[50:53]
	ds_read_b128 v[186:189], v249 offset:2048
	ds_read_b128 v[190:193], v249 offset:3072
	v_mfma_f32_16x16x32_bf16 v[42:45], v[234:237], v[194:197], v[42:45]
	ds_read_b128 v[194:197], v162
	v_mfma_f32_16x16x32_bf16 v[42:45], v[238:241], v[198:201], v[42:45]
	ds_read_b128 v[198:201], v162 offset:1024
	v_mfma_f32_16x16x32_bf16 v[34:37], v[226:229], v[202:205], v[34:37]
	v_mfma_f32_16x16x32_bf16 v[34:37], v[230:233], v[206:209], v[34:37]
	v_mfma_f32_16x16x32_bf16 v[26:29], v[234:237], v[202:205], v[26:29]
	ds_read_b128 v[202:205], v162 offset:2048
	v_mfma_f32_16x16x32_bf16 v[26:29], v[238:241], v[206:209], v[26:29]
	ds_read_b128 v[206:209], v162 offset:3072
	v_mfma_f32_16x16x32_bf16 v[18:21], v[226:229], v[210:213], v[18:21]
	v_mfma_f32_16x16x32_bf16 v[18:21], v[230:233], v[214:217], v[18:21]
	v_mfma_f32_16x16x32_bf16 v[10:13], v[234:237], v[210:213], v[10:13]
	ds_read_b128 v[210:213], v162 offset:4096
	v_mfma_f32_16x16x32_bf16 v[10:13], v[238:241], v[214:217], v[10:13]
	ds_read_b128 v[214:217], v162 offset:5120
	v_mfma_f32_16x16x32_bf16 v[6:9], v[226:229], v[218:221], v[6:9]
	v_mfma_f32_16x16x32_bf16 v[6:9], v[230:233], v[222:225], v[6:9]
	v_mfma_f32_16x16x32_bf16 v[2:5], v[234:237], v[218:221], v[2:5]
	s_barrier
	v_mfma_f32_16x16x32_bf16 v[2:5], v[238:241], v[222:225], v[2:5]
	s_setprio 0
	s_cmp_gt_u32 s38, 13
	s_cbranch_scc0 .LBB0_416
	s_waitcnt lgkmcnt(0)
	s_and_b64 vcc, exec, s[44:45]
	s_cbranch_vccz .LBB0_419
	s_barrier

; #define PG8_STAGE(bufoff, gbase, voff) do { _Pragma("unroll") for (int _i = 0; _i < 2; ++_i) \
;         __builtin_amdgcn_global_load_lds((const unsigned*)((const char*)(gbase) + (voff)[_i]), (LAS unsigned*)(lds + (bufoff) + ldsw + _i * 8192), 16, 0, 0); } while (0)
; #define PG8_LDA(dst, b, h) do { _Pragma("unroll") for (int m = 0; m < 4; ++m) _Pragma("unroll") for (int k = 0; k < 2; ++k) dst[m][k] = *(const LAS bf16x8*)(lds + PG8_SA(b, h) + aoff + m * 2048 + k * 1024); } while (0)
; #define PG8_LDB(dst, b, h) do { _Pragma("unroll") for (int n = 0; n < 2; ++n) _Pragma("unroll") for (int k = 0; k < 2; ++k) dst[n][k] = *(const LAS bf16x8*)(lds + PG8_SB(b, h) + boff + n * 2048 + k * 1024); } while (0)
; #define PG8_MMA(ai, bj, At, Bt) do { __builtin_amdgcn_s_setprio(1); _Pragma("unroll") for (int m = 0; m < 4; ++m) _Pragma("unroll") for (int n = 0; n < 2; ++n) _Pragma("unroll") for (int k = 0; k < 2; ++k) \
;         acc[ai][bj][m][n] = __builtin_amdgcn_mfma_f32_16x16x32_bf16(Bt[n][k], At[m][k], acc[ai][bj][m][n], 0, 0, 0); __builtin_amdgcn_s_setprio(0); } while (0)
; #define PG8_WAIT_L(n) asm volatile("s_waitcnt lgkmcnt(" #n ")" ::: "memory")
; template <class Epi, class Sched>
; __device__ __forceinline__ void gemm_phase(LAS unsigned char* lds, const Gemm g, const Sched& S, const Epi& E) {
;     ...
;         const bool has_next = S.next(ui + 1, nxt);
;         const char* nA = has_next ? PG8_APANEL(nxt.pm) : cA; const char* nB = has_next ? (const char*)g.Bt + (size_t)nxt.pn * tstep : cB;
;         for (int t = 0; t < nt; t += 2) {
;             const bool last = (t == nt - 2);
;             const char* a1 = cA + (size_t)(t + 1) * kstep;
;             const char* a2 = last ? nA : cA + (size_t)(t + 2) * kstep; const char* b2 = last ? nB : cB + (size_t)(t + 2) * kstep;
;             const char* a3 = a2 + kstep; const char* b3 = b2 + kstep;
;             PG8_LDB(B0, 0, 0); PG8_SCHED; PG8_LDA(At, 0, 0); PG8_STAGE(PG8_SA(1, 1), a1 + hstep, voffA);
;             PG8_WAIT_L(8); PG8_BAR; PG8_WAIT_L(0); PG8_MMA(0, 0, At, B0); PG8_BAR; PG8_SCHED;
;             PG8_LDB(B1, 0, 1); PG8_STAGE(PG8_SB(0, 0), b2, voffB);
;             PG8_BAR; PG8_WAIT_L(0); PG8_MMA(0, 1, At, B1); PG8_BAR;
;             PG8_LDA(At, 0, 1); PG8_STAGE(PG8_SA(0, 0), a2, voffA);
;             PG8_BAR; PG8_WAIT_L(0); PG8_MMA(1, 0, At, B0); PG8_BAR; PG8_SCHED;
.LBB0_556:
	s_ashr_i32 s45, s44, 31
	s_lshl_b64 s[24:25], s[44:45], 19
	s_add_u32 s60, s86, s24
	s_addc_u32 s61, s93, s25
	s_and_b64 s[0:1], s[0:1], exec
	s_cselect_b32 s45, s61, s49
	s_cselect_b32 s47, s60, s48
	s_add_u32 s35, s48, 0x100
	s_addc_u32 s50, s49, 0
	s_add_u32 s0, s38, 0x40080
	s_addc_u32 s1, s39, 0
	s_mov_b32 s38, -2
	v_add_u32_e32 v249, 0x10000, v164
	ds_read_b128 v[142:145], v249
	ds_read_b128 v[182:185], v249 offset:1024
	ds_read_b128 v[186:189], v249 offset:2048
	ds_read_b128 v[190:193], v249 offset:3072
	ds_read_b128 v[194:197], v166
	ds_read_b128 v[198:201], v166 offset:1024
	ds_read_b128 v[202:205], v166 offset:2048
	ds_read_b128 v[206:209], v166 offset:3072
	ds_read_b128 v[210:213], v166 offset:4096
	ds_read_b128 v[214:217], v166 offset:5120
	s_add_u32 s24, s0, 0xfffc0080
	s_addc_u32 s25, s1, -1
	s_add_i32 s39, 0, 0x10000
	s_cmp_eq_u32 s38, 12
	s_cselect_b32 vcc_hi, s77, s25
	s_cselect_b32 vcc_lo, s76, s24
	s_cselect_b32 s49, s45, s50
	s_cselect_b32 s48, s47, s35
	s_add_i32 m0, s95, 0xc000
	ds_read_b128 v[218:221], v166 offset:6144
	ds_read_b128 v[222:225], v166 offset:7168
	global_load_lds_dwordx4 v140, s[0:1]
	s_add_i32 m0, s95, 0xe000
	s_nop 0
	global_load_lds_dwordx4 v138, s[0:1]
	s_waitcnt lgkmcnt(8)
	s_barrier
	s_waitcnt lgkmcnt(0)
	s_setprio 1
	s_waitcnt lgkmcnt(0)
	v_mfma_f32_16x16x32_bf16 v[126:129], v[142:145], v[194:197], 0
	v_mfma_f32_16x16x32_bf16 v[126:129], v[182:185], v[198:201], v[126:129]
	v_mfma_f32_16x16x32_bf16 v[122:125], v[186:189], v[194:197], 0
	v_mfma_f32_16x16x32_bf16 v[122:125], v[190:193], v[198:201], v[122:125]
	v_mfma_f32_16x16x32_bf16 v[110:113], v[142:145], v[202:205], 0
	v_mfma_f32_16x16x32_bf16 v[110:113], v[182:185], v[206:209], v[110:113]
	v_mfma_f32_16x16x32_bf16 v[106:109], v[186:189], v[202:205], 0
	v_mfma_f32_16x16x32_bf16 v[106:109], v[190:193], v[206:209], v[106:109]
	v_mfma_f32_16x16x32_bf16 v[94:97], v[142:145], v[210:213], 0
	v_mfma_f32_16x16x32_bf16 v[94:97], v[182:185], v[214:217], v[94:97]
	v_mfma_f32_16x16x32_bf16 v[90:93], v[186:189], v[210:213], 0
	v_mfma_f32_16x16x32_bf16 v[90:93], v[190:193], v[214:217], v[90:93]
	v_mfma_f32_16x16x32_bf16 v[78:81], v[142:145], v[218:221], 0
	v_mfma_f32_16x16x32_bf16 v[78:81], v[182:185], v[222:225], v[78:81]
	v_mfma_f32_16x16x32_bf16 v[74:77], v[186:189], v[218:221], 0
	s_barrier
	v_mfma_f32_16x16x32_bf16 v[74:77], v[190:193], v[222:225], v[74:77]
	s_setprio 0
	s_add_i32 s51, 0, 0x14000
	s_add_i32 s24, s39, s94
	ds_read_b128 v[226:229], v249 offset:16384
	ds_read_b128 v[230:233], v249 offset:17408
	ds_read_b128 v[234:237], v249 offset:18432
	ds_read_b128 v[238:241], v249 offset:19456
	s_mov_b32 m0, s24
	global_load_lds_dwordx4 v134, s[48:49]
	s_add_i32 m0, s24, 0x2000
	s_nop 0
	global_load_lds_dwordx4 v130, s[48:49]
	s_barrier
	s_waitcnt lgkmcnt(0)
	s_setprio 1
	s_waitcnt lgkmcnt(0)
	v_mfma_f32_16x16x32_bf16 v[118:121], v[226:229], v[194:197], 0
	v_mfma_f32_16x16x32_bf16 v[118:121], v[230:233], v[198:201], v[118:121]
	v_mfma_f32_16x16x32_bf16 v[114:117], v[234:237], v[194:197], 0
	v_mfma_f32_16x16x32_bf16 v[114:117], v[238:241], v[198:201], v[114:117]
	v_mfma_f32_16x16x32_bf16 v[102:105], v[226:229], v[202:205], 0
	v_mfma_f32_16x16x32_bf16 v[102:105], v[230:233], v[206:209], v[102:105]
	v_mfma_f32_16x16x32_bf16 v[98:101], v[234:237], v[202:205], 0
	v_mfma_f32_16x16x32_bf16 v[98:101], v[238:241], v[206:209], v[98:101]
	v_mfma_f32_16x16x32_bf16 v[86:89], v[226:229], v[210:213], 0
	v_mfma_f32_16x16x32_bf16 v[86:89], v[230:233], v[214:217], v[86:89]
	v_mfma_f32_16x16x32_bf16 v[82:85], v[234:237], v[210:213], 0
	v_mfma_f32_16x16x32_bf16 v[82:85], v[238:241], v[214:217], v[82:85]
	v_mfma_f32_16x16x32_bf16 v[70:73], v[226:229], v[218:221], 0
	v_mfma_f32_16x16x32_bf16 v[70:73], v[230:233], v[222:225], v[70:73]
	v_mfma_f32_16x16x32_bf16 v[66:69], v[234:237], v[218:221], 0
	s_barrier
	v_mfma_f32_16x16x32_bf16 v[66:69], v[238:241], v[222:225], v[66:69]
	s_setprio 0
	s_mov_b32 m0, s95
	ds_read_b128 v[194:197], v166 offset:16384
	ds_read_b128 v[198:201], v166 offset:17408
	ds_read_b128 v[202:205], v166 offset:18432
	ds_read_b128 v[206:209], v166 offset:19456
	ds_read_b128 v[210:213], v166 offset:20480
	ds_read_b128 v[214:217], v166 offset:21504
	ds_read_b128 v[218:221], v166 offset:22528
	ds_read_b128 v[222:225], v166 offset:23552
	global_load_lds_dwordx4 v136, vcc
	s_mov_b32 m0, s96
	s_nop 0
	global_load_lds_dwordx4 v132, vcc
	s_waitcnt vmcnt(8)
	s_barrier
	s_waitcnt lgkmcnt(0)
	s_setprio 1
	s_waitcnt lgkmcnt(0)
	v_mfma_f32_16x16x32_bf16 v[62:65], v[142:145], v[194:197], 0
	v_mfma_f32_16x16x32_bf16 v[62:65], v[182:185], v[198:201], v[62:65]
	v_mfma_f32_16x16x32_bf16 v[58:61], v[186:189], v[194:197], 0
	v_mfma_f32_16x16x32_bf16 v[58:61], v[190:193], v[198:201], v[58:61]
	v_mfma_f32_16x16x32_bf16 v[46:49], v[142:145], v[202:205], 0
	v_mfma_f32_16x16x32_bf16 v[46:49], v[182:185], v[206:209], v[46:49]
	v_mfma_f32_16x16x32_bf16 v[42:45], v[186:189], v[202:205], 0
	v_mfma_f32_16x16x32_bf16 v[42:45], v[190:193], v[206:209], v[42:45]
	v_mfma_f32_16x16x32_bf16 v[30:33], v[142:145], v[210:213], 0
	v_mfma_f32_16x16x32_bf16 v[30:33], v[182:185], v[214:217], v[30:33]
	v_mfma_f32_16x16x32_bf16 v[26:29], v[186:189], v[210:213], 0
	v_mfma_f32_16x16x32_bf16 v[26:29], v[190:193], v[214:217], v[26:29]
	v_mfma_f32_16x16x32_bf16 v[14:17], v[142:145], v[218:221], 0
	v_mfma_f32_16x16x32_bf16 v[14:17], v[182:185], v[222:225], v[14:17]
	v_mfma_f32_16x16x32_bf16 v[10:13], v[186:189], v[218:221], 0
	s_barrier
; #define PG8_STAGE(bufoff, gbase, voff) do { _Pragma("unroll") for (int _i = 0; _i < 2; ++_i) \
;         __builtin_amdgcn_global_load_lds((const unsigned*)((const char*)(gbase) + (voff)[_i]), (LAS unsigned*)(lds + (bufoff) + ldsw + _i * 8192), 16, 0, 0); } while (0)
; #define PG8_LDA(dst, b, h) do { _Pragma("unroll") for (int m = 0; m < 4; ++m) _Pragma("unroll") for (int k = 0; k < 2; ++k) dst[m][k] = *(const LAS bf16x8*)(lds + PG8_SA(b, h) + aoff + m * 2048 + k * 1024); } while (0)
; #define PG8_LDB(dst, b, h) do { _Pragma("unroll") for (int n = 0; n < 2; ++n) _Pragma("unroll") for (int k = 0; k < 2; ++k) dst[n][k] = *(const LAS bf16x8*)(lds + PG8_SB(b, h) + boff + n * 2048 + k * 1024); } while (0)
; #define PG8_MMA(ai, bj, At, Bt) do { __builtin_amdgcn_s_setprio(1); _Pragma("unroll") for (int m = 0; m < 4; ++m) _Pragma("unroll") for (int n = 0; n < 2; ++n) _Pragma("unroll") for (int k = 0; k < 2; ++k) \
;         acc[ai][bj][m][n] = __builtin_amdgcn_mfma_f32_16x16x32_bf16(Bt[n][k], At[m][k], acc[ai][bj][m][n], 0, 0, 0); __builtin_amdgcn_s_setprio(0); } while (0)
; #define PG8_WAIT_V(n) asm volatile("s_waitcnt vmcnt(" #n ")" ::: "memory")
; #define PG8_WAIT_L(n) asm volatile("s_waitcnt lgkmcnt(" #n ")" ::: "memory")
; #define PG8_BAR __builtin_amdgcn_s_barrier()
; #define PG8_SCHED __builtin_amdgcn_sched_barrier(0)
; template <class Epi, class Sched>
; __device__ __forceinline__ void gemm_phase(LAS unsigned char* lds, const Gemm g, const Sched& S, const Epi& E) {
;     ...
;             PG8_STAGE(PG8_SB(0, 1), b2 + hstep, voffB);
;             PG8_WAIT_V(6); PG8_BAR; PG8_MMA(1, 1, At, B1); PG8_BAR;
;             PG8_LDB(B0, 1, 0); PG8_SCHED; PG8_LDA(At, 1, 0); PG8_STAGE(PG8_SA(0, 1), a2 + hstep, voffA);
;             PG8_WAIT_L(8); PG8_BAR; PG8_WAIT_L(0); PG8_MMA(0, 0, At, B0); PG8_BAR; PG8_SCHED;
;             PG8_LDB(B1, 1, 1); PG8_STAGE(PG8_SB(1, 0), b3, voffB);
;             PG8_BAR; PG8_WAIT_L(0); PG8_MMA(0, 1, At, B1); PG8_BAR;
;             PG8_LDA(At, 1, 1); PG8_STAGE(PG8_SA(1, 0), a3, voffA);
;             PG8_BAR; PG8_WAIT_L(0); PG8_MMA(1, 0, At, B0); PG8_BAR; PG8_SCHED;
	v_mfma_f32_16x16x32_bf16 v[10:13], v[190:193], v[222:225], v[10:13]
	s_setprio 0
	s_add_u32 s24, s48, 0x40000
	s_addc_u32 s25, s49, 0
	s_add_i32 s39, s51, s94
	s_mov_b32 m0, s39
	s_nop 0
	global_load_lds_dwordx4 v134, s[24:25]
	s_add_i32 m0, s39, 0x2000
	s_nop 0
	global_load_lds_dwordx4 v130, s[24:25]
	s_waitcnt vmcnt(6)
	s_barrier
	s_setprio 1
	v_mfma_f32_16x16x32_bf16 v[54:57], v[226:229], v[194:197], 0
	ds_read_b128 v[142:145], v249 offset:32768
	ds_read_b128 v[182:185], v249 offset:33792
	v_mfma_f32_16x16x32_bf16 v[54:57], v[230:233], v[198:201], v[54:57]
	ds_read_b128 v[186:189], v249 offset:34816
	ds_read_b128 v[190:193], v249 offset:35840
	v_mfma_f32_16x16x32_bf16 v[50:53], v[234:237], v[194:197], 0
	ds_read_b128 v[194:197], v166 offset:32768
	v_mfma_f32_16x16x32_bf16 v[50:53], v[238:241], v[198:201], v[50:53]
	ds_read_b128 v[198:201], v166 offset:33792
	v_mfma_f32_16x16x32_bf16 v[38:41], v[226:229], v[202:205], 0
	v_mfma_f32_16x16x32_bf16 v[38:41], v[230:233], v[206:209], v[38:41]
	v_mfma_f32_16x16x32_bf16 v[34:37], v[234:237], v[202:205], 0
	ds_read_b128 v[202:205], v166 offset:34816
	v_mfma_f32_16x16x32_bf16 v[34:37], v[238:241], v[206:209], v[34:37]
	ds_read_b128 v[206:209], v166 offset:35840
	v_mfma_f32_16x16x32_bf16 v[22:25], v[226:229], v[210:213], 0
	v_mfma_f32_16x16x32_bf16 v[22:25], v[230:233], v[214:217], v[22:25]
	v_mfma_f32_16x16x32_bf16 v[18:21], v[234:237], v[210:213], 0
	ds_read_b128 v[210:213], v166 offset:36864
	v_mfma_f32_16x16x32_bf16 v[18:21], v[238:241], v[214:217], v[18:21]
	ds_read_b128 v[214:217], v166 offset:37888
	v_mfma_f32_16x16x32_bf16 v[6:9], v[226:229], v[218:221], 0
	v_mfma_f32_16x16x32_bf16 v[6:9], v[230:233], v[222:225], v[6:9]
	v_mfma_f32_16x16x32_bf16 v[2:5], v[234:237], v[218:221], 0
	s_barrier
	v_mfma_f32_16x16x32_bf16 v[2:5], v[238:241], v[222:225], v[2:5]
	s_setprio 0
	s_add_i32 s39, 0, 0x18000
	s_add_u32 s24, vcc_lo, 0x40000
	s_addc_u32 s25, vcc_hi, 0
	s_mov_b32 m0, s97
	ds_read_b128 v[218:221], v166 offset:38912
	ds_read_b128 v[222:225], v166 offset:39936
	global_load_lds_dwordx4 v136, s[24:25]
	s_mov_b32 m0, s98
	s_nop 0
	global_load_lds_dwordx4 v132, s[24:25]
	s_waitcnt lgkmcnt(8)
	s_barrier
	s_waitcnt lgkmcnt(0)
	s_setprio 1
	s_waitcnt lgkmcnt(0)
	v_mfma_f32_16x16x32_bf16 v[126:129], v[142:145], v[194:197], v[126:129]
	v_mfma_f32_16x16x32_bf16 v[126:129], v[182:185], v[198:201], v[126:129]
	v_mfma_f32_16x16x32_bf16 v[122:125], v[186:189], v[194:197], v[122:125]
	v_mfma_f32_16x16x32_bf16 v[122:125], v[190:193], v[198:201], v[122:125]
	v_mfma_f32_16x16x32_bf16 v[110:113], v[142:145], v[202:205], v[110:113]
	v_mfma_f32_16x16x32_bf16 v[110:113], v[182:185], v[206:209], v[110:113]
	v_mfma_f32_16x16x32_bf16 v[106:109], v[186:189], v[202:205], v[106:109]
	v_mfma_f32_16x16x32_bf16 v[106:109], v[190:193], v[206:209], v[106:109]
	v_mfma_f32_16x16x32_bf16 v[94:97], v[142:145], v[210:213], v[94:97]
	v_mfma_f32_16x16x32_bf16 v[94:97], v[182:185], v[214:217], v[94:97]
	v_mfma_f32_16x16x32_bf16 v[90:93], v[186:189], v[210:213], v[90:93]
	v_mfma_f32_16x16x32_bf16 v[90:93], v[190:193], v[214:217], v[90:93]
	v_mfma_f32_16x16x32_bf16 v[78:81], v[142:145], v[218:221], v[78:81]
	v_mfma_f32_16x16x32_bf16 v[78:81], v[182:185], v[222:225], v[78:81]
	v_mfma_f32_16x16x32_bf16 v[74:77], v[186:189], v[218:221], v[74:77]
	s_barrier
	v_mfma_f32_16x16x32_bf16 v[74:77], v[190:193], v[222:225], v[74:77]
	s_setprio 0
	s_add_i32 s51, 0, 0x1c000
	s_add_i32 s24, s39, s94
	s_add_i32 m0, s24, 0xffffff80
	ds_read_b128 v[226:229], v249 offset:49152
	ds_read_b128 v[230:233], v249 offset:50176
	ds_read_b128 v[234:237], v249 offset:51200
	ds_read_b128 v[238:241], v249 offset:52224
	global_load_lds_dwordx4 v134, s[48:49] offset:128
	s_add_i32 m0, s24, 0x1f80
	s_nop 0
	global_load_lds_dwordx4 v130, s[48:49] offset:128
	s_barrier
	s_waitcnt lgkmcnt(0)
	s_setprio 1
	s_waitcnt lgkmcnt(0)
	v_mfma_f32_16x16x32_bf16 v[118:121], v[226:229], v[194:197], v[118:121]
	v_mfma_f32_16x16x32_bf16 v[118:121], v[230:233], v[198:201], v[118:121]
	v_mfma_f32_16x16x32_bf16 v[114:117], v[234:237], v[194:197], v[114:117]
	v_mfma_f32_16x16x32_bf16 v[114:117], v[238:241], v[198:201], v[114:117]
	v_mfma_f32_16x16x32_bf16 v[102:105], v[226:229], v[202:205], v[102:105]
	v_mfma_f32_16x16x32_bf16 v[102:105], v[230:233], v[206:209], v[102:105]
	v_mfma_f32_16x16x32_bf16 v[98:101], v[234:237], v[202:205], v[98:101]
	v_mfma_f32_16x16x32_bf16 v[98:101], v[238:241], v[206:209], v[98:101]
	v_mfma_f32_16x16x32_bf16 v[86:89], v[226:229], v[210:213], v[86:89]
	v_mfma_f32_16x16x32_bf16 v[86:89], v[230:233], v[214:217], v[86:89]
	v_mfma_f32_16x16x32_bf16 v[82:85], v[234:237], v[210:213], v[82:85]
	v_mfma_f32_16x16x32_bf16 v[82:85], v[238:241], v[214:217], v[82:85]
	v_mfma_f32_16x16x32_bf16 v[70:73], v[226:229], v[218:221], v[70:73]
	v_mfma_f32_16x16x32_bf16 v[70:73], v[230:233], v[222:225], v[70:73]
	v_mfma_f32_16x16x32_bf16 v[66:69], v[234:237], v[218:221], v[66:69]
	s_barrier
	v_mfma_f32_16x16x32_bf16 v[66:69], v[238:241], v[222:225], v[66:69]
	s_setprio 0
	s_add_i32 m0, s99, 0xffffff80
	ds_read_b128 v[194:197], v166 offset:49152
	ds_read_b128 v[198:201], v166 offset:50176
	ds_read_b128 v[202:205], v166 offset:51200
	ds_read_b128 v[206:209], v166 offset:52224
	ds_read_b128 v[210:213], v166 offset:53248
	ds_read_b128 v[214:217], v166 offset:54272
	ds_read_b128 v[218:221], v166 offset:55296
	ds_read_b128 v[222:225], v166 offset:56320
	global_load_lds_dwordx4 v136, vcc offset:128
	s_add_i32 m0, s82, 0xffffff80
	s_nop 0
	global_load_lds_dwordx4 v132, vcc offset:128
	s_waitcnt vmcnt(8)
	s_barrier
; #define PG8_STAGE(bufoff, gbase, voff) do { _Pragma("unroll") for (int _i = 0; _i < 2; ++_i) \
;         __builtin_amdgcn_global_load_lds((const unsigned*)((const char*)(gbase) + (voff)[_i]), (LAS unsigned*)(lds + (bufoff) + ldsw + _i * 8192), 16, 0, 0); } while (0)
; #define PG8_LDA(dst, b, h) do { _Pragma("unroll") for (int m = 0; m < 4; ++m) _Pragma("unroll") for (int k = 0; k < 2; ++k) dst[m][k] = *(const LAS bf16x8*)(lds + PG8_SA(b, h) + aoff + m * 2048 + k * 1024); } while (0)
; #define PG8_LDB(dst, b, h) do { _Pragma("unroll") for (int n = 0; n < 2; ++n) _Pragma("unroll") for (int k = 0; k < 2; ++k) dst[n][k] = *(const LAS bf16x8*)(lds + PG8_SB(b, h) + boff + n * 2048 + k * 1024); } while (0)
; #define PG8_MMA(ai, bj, At, Bt) do { __builtin_amdgcn_s_setprio(1); _Pragma("unroll") for (int m = 0; m < 4; ++m) _Pragma("unroll") for (int n = 0; n < 2; ++n) _Pragma("unroll") for (int k = 0; k < 2; ++k) \
;         acc[ai][bj][m][n] = __builtin_amdgcn_mfma_f32_16x16x32_bf16(Bt[n][k], At[m][k], acc[ai][bj][m][n], 0, 0, 0); __builtin_amdgcn_s_setprio(0); } while (0)
; #define PG8_WAIT_V(n) asm volatile("s_waitcnt vmcnt(" #n ")" ::: "memory")
; #define PG8_WAIT_L(n) asm volatile("s_waitcnt lgkmcnt(" #n ")" ::: "memory")
; #define PG8_BAR __builtin_amdgcn_s_barrier()
; #define PG8_SCHED __builtin_amdgcn_sched_barrier(0)
; template <class Epi, class Sched>
; __device__ __forceinline__ void gemm_phase(LAS unsigned char* lds, const Gemm g, const Sched& S, const Epi& E) {
;     ...
;             PG8_LDB(B0, 0, 0); PG8_SCHED; PG8_LDA(At, 0, 0); PG8_STAGE(PG8_SA(1, 1), a1 + hstep, voffA);
;             PG8_WAIT_L(8); PG8_BAR; PG8_WAIT_L(0); PG8_MMA(0, 0, At, B0); PG8_BAR; PG8_SCHED;
;             PG8_LDB(B1, 0, 1); PG8_STAGE(PG8_SB(0, 0), b2, voffB);
;             PG8_BAR; PG8_WAIT_L(0); PG8_MMA(0, 1, At, B1); PG8_BAR;
;     ...
;             PG8_LDA(At, 1, 1); PG8_STAGE(PG8_SA(1, 0), a3, voffA);
;             PG8_BAR; PG8_WAIT_L(0); PG8_MMA(1, 0, At, B0); PG8_BAR; PG8_SCHED;
;             PG8_STAGE(PG8_SB(1, 1), b3 + hstep, voffB);
;             PG8_WAIT_V(6); PG8_BAR; PG8_MMA(1, 1, At, B1); PG8_BAR;
	s_waitcnt lgkmcnt(0)
	s_setprio 1
	s_waitcnt lgkmcnt(0)
	v_mfma_f32_16x16x32_bf16 v[62:65], v[142:145], v[194:197], v[62:65]
	v_mfma_f32_16x16x32_bf16 v[62:65], v[182:185], v[198:201], v[62:65]
	v_mfma_f32_16x16x32_bf16 v[58:61], v[186:189], v[194:197], v[58:61]
	v_mfma_f32_16x16x32_bf16 v[58:61], v[190:193], v[198:201], v[58:61]
	v_mfma_f32_16x16x32_bf16 v[46:49], v[142:145], v[202:205], v[46:49]
	v_mfma_f32_16x16x32_bf16 v[46:49], v[182:185], v[206:209], v[46:49]
	v_mfma_f32_16x16x32_bf16 v[42:45], v[186:189], v[202:205], v[42:45]
	v_mfma_f32_16x16x32_bf16 v[42:45], v[190:193], v[206:209], v[42:45]
	v_mfma_f32_16x16x32_bf16 v[30:33], v[142:145], v[210:213], v[30:33]
	v_mfma_f32_16x16x32_bf16 v[30:33], v[182:185], v[214:217], v[30:33]
	v_mfma_f32_16x16x32_bf16 v[26:29], v[186:189], v[210:213], v[26:29]
	v_mfma_f32_16x16x32_bf16 v[26:29], v[190:193], v[214:217], v[26:29]
	v_mfma_f32_16x16x32_bf16 v[14:17], v[142:145], v[218:221], v[14:17]
	v_mfma_f32_16x16x32_bf16 v[14:17], v[182:185], v[222:225], v[14:17]
	v_mfma_f32_16x16x32_bf16 v[10:13], v[186:189], v[218:221], v[10:13]
	s_barrier
	v_mfma_f32_16x16x32_bf16 v[10:13], v[190:193], v[222:225], v[10:13]
	s_setprio 0
	s_add_u32 s24, s48, 0x40080
	s_addc_u32 s25, s49, 0
	s_add_i32 s39, s51, s94
	s_mov_b32 m0, s39
	s_nop 0
	global_load_lds_dwordx4 v134, s[24:25]
	s_add_i32 m0, s39, 0x2000
	s_nop 0
	global_load_lds_dwordx4 v130, s[24:25]
	s_add_i32 s38, s38, 2
	s_add_u32 s35, s35, 0x100
	s_addc_u32 s50, s50, 0
	s_add_u32 s0, s0, 0x100
	s_addc_u32 s1, s1, 0
	s_add_u32 s24, s0, 0xfffc0080
	s_addc_u32 s25, s1, -1
	s_add_i32 s39, 0, 0x10000
	s_cmp_eq_u32 s38, 12
	s_cselect_b32 vcc_hi, s77, s25
	s_cselect_b32 vcc_lo, s76, s24
	s_cselect_b32 s49, s45, s50
	s_cselect_b32 s48, s47, s35
	s_waitcnt vmcnt(6)
	s_barrier
	s_setprio 1
	v_mfma_f32_16x16x32_bf16 v[54:57], v[226:229], v[194:197], v[54:57]
	ds_read_b128 v[142:145], v249
	ds_read_b128 v[182:185], v249 offset:1024
	v_mfma_f32_16x16x32_bf16 v[54:57], v[230:233], v[198:201], v[54:57]
	ds_read_b128 v[186:189], v249 offset:2048
	ds_read_b128 v[190:193], v249 offset:3072
	v_mfma_f32_16x16x32_bf16 v[50:53], v[234:237], v[194:197], v[50:53]
	ds_read_b128 v[194:197], v166
	v_mfma_f32_16x16x32_bf16 v[50:53], v[238:241], v[198:201], v[50:53]
	ds_read_b128 v[198:201], v166 offset:1024
	v_mfma_f32_16x16x32_bf16 v[38:41], v[226:229], v[202:205], v[38:41]
	v_mfma_f32_16x16x32_bf16 v[38:41], v[230:233], v[206:209], v[38:41]
	v_mfma_f32_16x16x32_bf16 v[34:37], v[234:237], v[202:205], v[34:37]
	ds_read_b128 v[202:205], v166 offset:2048
	v_mfma_f32_16x16x32_bf16 v[34:37], v[238:241], v[206:209], v[34:37]
	ds_read_b128 v[206:209], v166 offset:3072
	v_mfma_f32_16x16x32_bf16 v[22:25], v[226:229], v[210:213], v[22:25]
	v_mfma_f32_16x16x32_bf16 v[22:25], v[230:233], v[214:217], v[22:25]
	v_mfma_f32_16x16x32_bf16 v[18:21], v[234:237], v[210:213], v[18:21]
	ds_read_b128 v[210:213], v166 offset:4096
	v_mfma_f32_16x16x32_bf16 v[18:21], v[238:241], v[214:217], v[18:21]
	ds_read_b128 v[214:217], v166 offset:5120
	v_mfma_f32_16x16x32_bf16 v[6:9], v[226:229], v[218:221], v[6:9]
	v_mfma_f32_16x16x32_bf16 v[6:9], v[230:233], v[222:225], v[6:9]
	v_mfma_f32_16x16x32_bf16 v[2:5], v[234:237], v[218:221], v[2:5]
	s_barrier
	v_mfma_f32_16x16x32_bf16 v[2:5], v[238:241], v[222:225], v[2:5]
	s_setprio 0
	s_cmp_gt_u32 s38, 13
.LBB0_557:
	s_add_i32 m0, s95, 0xc000
	ds_read_b128 v[218:221], v166 offset:6144
	ds_read_b128 v[222:225], v166 offset:7168
	global_load_lds_dwordx4 v140, s[0:1]
	s_add_i32 m0, s95, 0xe000
	s_nop 0
	global_load_lds_dwordx4 v138, s[0:1]
	s_waitcnt lgkmcnt(8)
	s_barrier
	s_waitcnt lgkmcnt(0)
	s_setprio 1
	s_waitcnt lgkmcnt(0)
	v_mfma_f32_16x16x32_bf16 v[126:129], v[142:145], v[194:197], v[126:129]
	v_mfma_f32_16x16x32_bf16 v[126:129], v[182:185], v[198:201], v[126:129]
	v_mfma_f32_16x16x32_bf16 v[122:125], v[186:189], v[194:197], v[122:125]
	v_mfma_f32_16x16x32_bf16 v[122:125], v[190:193], v[198:201], v[122:125]
	v_mfma_f32_16x16x32_bf16 v[110:113], v[142:145], v[202:205], v[110:113]
	v_mfma_f32_16x16x32_bf16 v[110:113], v[182:185], v[206:209], v[110:113]
	v_mfma_f32_16x16x32_bf16 v[106:109], v[186:189], v[202:205], v[106:109]
	v_mfma_f32_16x16x32_bf16 v[106:109], v[190:193], v[206:209], v[106:109]
	v_mfma_f32_16x16x32_bf16 v[94:97], v[142:145], v[210:213], v[94:97]
	v_mfma_f32_16x16x32_bf16 v[94:97], v[182:185], v[214:217], v[94:97]
	v_mfma_f32_16x16x32_bf16 v[90:93], v[186:189], v[210:213], v[90:93]
	v_mfma_f32_16x16x32_bf16 v[90:93], v[190:193], v[214:217], v[90:93]
	v_mfma_f32_16x16x32_bf16 v[78:81], v[142:145], v[218:221], v[78:81]
	v_mfma_f32_16x16x32_bf16 v[78:81], v[182:185], v[222:225], v[78:81]
	v_mfma_f32_16x16x32_bf16 v[74:77], v[186:189], v[218:221], v[74:77]
	s_barrier
	v_mfma_f32_16x16x32_bf16 v[74:77], v[190:193], v[222:225], v[74:77]
	s_setprio 0
	s_add_i32 s51, 0, 0x14000
	s_add_i32 s24, s39, s94
	ds_read_b128 v[226:229], v249 offset:16384
	ds_read_b128 v[230:233], v249 offset:17408
	ds_read_b128 v[234:237], v249 offset:18432
	ds_read_b128 v[238:241], v249 offset:19456
	s_mov_b32 m0, s24
	global_load_lds_dwordx4 v134, s[48:49]
	s_add_i32 m0, s24, 0x2000
	s_nop 0
	global_load_lds_dwordx4 v130, s[48:49]
	s_barrier
; #define PG8_STAGE(bufoff, gbase, voff) do { _Pragma("unroll") for (int _i = 0; _i < 2; ++_i) \
;         __builtin_amdgcn_global_load_lds((const unsigned*)((const char*)(gbase) + (voff)[_i]), (LAS unsigned*)(lds + (bufoff) + ldsw + _i * 8192), 16, 0, 0); } while (0)
; #define PG8_LDA(dst, b, h) do { _Pragma("unroll") for (int m = 0; m < 4; ++m) _Pragma("unroll") for (int k = 0; k < 2; ++k) dst[m][k] = *(const LAS bf16x8*)(lds + PG8_SA(b, h) + aoff + m * 2048 + k * 1024); } while (0)
; #define PG8_LDB(dst, b, h) do { _Pragma("unroll") for (int n = 0; n < 2; ++n) _Pragma("unroll") for (int k = 0; k < 2; ++k) dst[n][k] = *(const LAS bf16x8*)(lds + PG8_SB(b, h) + boff + n * 2048 + k * 1024); } while (0)
; #define PG8_MMA(ai, bj, At, Bt) do { __builtin_amdgcn_s_setprio(1); _Pragma("unroll") for (int m = 0; m < 4; ++m) _Pragma("unroll") for (int n = 0; n < 2; ++n) _Pragma("unroll") for (int k = 0; k < 2; ++k) \
;         acc[ai][bj][m][n] = __builtin_amdgcn_mfma_f32_16x16x32_bf16(Bt[n][k], At[m][k], acc[ai][bj][m][n], 0, 0, 0); __builtin_amdgcn_s_setprio(0); } while (0)
; #define PG8_WAIT_V(n) asm volatile("s_waitcnt vmcnt(" #n ")" ::: "memory")
; #define PG8_WAIT_L(n) asm volatile("s_waitcnt lgkmcnt(" #n ")" ::: "memory")
; #define PG8_BAR __builtin_amdgcn_s_barrier()
; #define PG8_SCHED __builtin_amdgcn_sched_barrier(0)
; template <class Epi, class Sched>
; __device__ __forceinline__ void gemm_phase(LAS unsigned char* lds, const Gemm g, const Sched& S, const Epi& E) {
;     ...
;             PG8_BAR; PG8_WAIT_L(0); PG8_MMA(0, 1, At, B1); PG8_BAR;
;             PG8_LDA(At, 0, 1); PG8_STAGE(PG8_SA(0, 0), a2, voffA);
;             PG8_BAR; PG8_WAIT_L(0); PG8_MMA(1, 0, At, B0); PG8_BAR; PG8_SCHED;
;             PG8_STAGE(PG8_SB(0, 1), b2 + hstep, voffB);
;             PG8_WAIT_V(6); PG8_BAR; PG8_MMA(1, 1, At, B1); PG8_BAR;
;             PG8_LDB(B0, 1, 0); PG8_SCHED; PG8_LDA(At, 1, 0); PG8_STAGE(PG8_SA(0, 1), a2 + hstep, voffA);
;             PG8_WAIT_L(8); PG8_BAR; PG8_WAIT_L(0); PG8_MMA(0, 0, At, B0); PG8_BAR; PG8_SCHED;
	s_waitcnt lgkmcnt(0)
	s_setprio 1
	s_waitcnt lgkmcnt(0)
	v_mfma_f32_16x16x32_bf16 v[118:121], v[226:229], v[194:197], v[118:121]
	v_mfma_f32_16x16x32_bf16 v[118:121], v[230:233], v[198:201], v[118:121]
	v_mfma_f32_16x16x32_bf16 v[114:117], v[234:237], v[194:197], v[114:117]
	v_mfma_f32_16x16x32_bf16 v[114:117], v[238:241], v[198:201], v[114:117]
	v_mfma_f32_16x16x32_bf16 v[102:105], v[226:229], v[202:205], v[102:105]
	v_mfma_f32_16x16x32_bf16 v[102:105], v[230:233], v[206:209], v[102:105]
	v_mfma_f32_16x16x32_bf16 v[98:101], v[234:237], v[202:205], v[98:101]
	v_mfma_f32_16x16x32_bf16 v[98:101], v[238:241], v[206:209], v[98:101]
	v_mfma_f32_16x16x32_bf16 v[86:89], v[226:229], v[210:213], v[86:89]
	v_mfma_f32_16x16x32_bf16 v[86:89], v[230:233], v[214:217], v[86:89]
	v_mfma_f32_16x16x32_bf16 v[82:85], v[234:237], v[210:213], v[82:85]
	v_mfma_f32_16x16x32_bf16 v[82:85], v[238:241], v[214:217], v[82:85]
	v_mfma_f32_16x16x32_bf16 v[70:73], v[226:229], v[218:221], v[70:73]
	v_mfma_f32_16x16x32_bf16 v[70:73], v[230:233], v[222:225], v[70:73]
	v_mfma_f32_16x16x32_bf16 v[66:69], v[234:237], v[218:221], v[66:69]
	s_barrier
	v_mfma_f32_16x16x32_bf16 v[66:69], v[238:241], v[222:225], v[66:69]
	s_setprio 0
	s_mov_b32 m0, s95
	ds_read_b128 v[194:197], v166 offset:16384
	ds_read_b128 v[198:201], v166 offset:17408
	ds_read_b128 v[202:205], v166 offset:18432
	ds_read_b128 v[206:209], v166 offset:19456
	ds_read_b128 v[210:213], v166 offset:20480
	ds_read_b128 v[214:217], v166 offset:21504
	ds_read_b128 v[218:221], v166 offset:22528
	ds_read_b128 v[222:225], v166 offset:23552
	global_load_lds_dwordx4 v136, vcc
	s_mov_b32 m0, s96
	s_nop 0
	global_load_lds_dwordx4 v132, vcc
	s_waitcnt vmcnt(8)
	s_barrier
	s_waitcnt lgkmcnt(0)
	s_setprio 1
	s_waitcnt lgkmcnt(0)
	v_mfma_f32_16x16x32_bf16 v[62:65], v[142:145], v[194:197], v[62:65]
	v_mfma_f32_16x16x32_bf16 v[62:65], v[182:185], v[198:201], v[62:65]
	v_mfma_f32_16x16x32_bf16 v[58:61], v[186:189], v[194:197], v[58:61]
	v_mfma_f32_16x16x32_bf16 v[58:61], v[190:193], v[198:201], v[58:61]
	v_mfma_f32_16x16x32_bf16 v[46:49], v[142:145], v[202:205], v[46:49]
	v_mfma_f32_16x16x32_bf16 v[46:49], v[182:185], v[206:209], v[46:49]
	v_mfma_f32_16x16x32_bf16 v[42:45], v[186:189], v[202:205], v[42:45]
	v_mfma_f32_16x16x32_bf16 v[42:45], v[190:193], v[206:209], v[42:45]
	v_mfma_f32_16x16x32_bf16 v[30:33], v[142:145], v[210:213], v[30:33]
	v_mfma_f32_16x16x32_bf16 v[30:33], v[182:185], v[214:217], v[30:33]
	v_mfma_f32_16x16x32_bf16 v[26:29], v[186:189], v[210:213], v[26:29]
	v_mfma_f32_16x16x32_bf16 v[26:29], v[190:193], v[214:217], v[26:29]
	v_mfma_f32_16x16x32_bf16 v[14:17], v[142:145], v[218:221], v[14:17]
	v_mfma_f32_16x16x32_bf16 v[14:17], v[182:185], v[222:225], v[14:17]
	v_mfma_f32_16x16x32_bf16 v[10:13], v[186:189], v[218:221], v[10:13]
	s_barrier
	v_mfma_f32_16x16x32_bf16 v[10:13], v[190:193], v[222:225], v[10:13]
	s_setprio 0
	s_add_u32 s24, s48, 0x40000
	s_addc_u32 s25, s49, 0
	s_add_i32 s39, s51, s94
	s_mov_b32 m0, s39
	s_nop 0
	global_load_lds_dwordx4 v134, s[24:25]
	s_add_i32 m0, s39, 0x2000
	s_nop 0
	global_load_lds_dwordx4 v130, s[24:25]
	s_waitcnt vmcnt(6)
	s_barrier
	s_setprio 1
	v_mfma_f32_16x16x32_bf16 v[54:57], v[226:229], v[194:197], v[54:57]
	ds_read_b128 v[142:145], v249 offset:32768
	ds_read_b128 v[182:185], v249 offset:33792
	v_mfma_f32_16x16x32_bf16 v[54:57], v[230:233], v[198:201], v[54:57]
	ds_read_b128 v[186:189], v249 offset:34816
	ds_read_b128 v[190:193], v249 offset:35840
	v_mfma_f32_16x16x32_bf16 v[50:53], v[234:237], v[194:197], v[50:53]
	ds_read_b128 v[194:197], v166 offset:32768
	v_mfma_f32_16x16x32_bf16 v[50:53], v[238:241], v[198:201], v[50:53]
	ds_read_b128 v[198:201], v166 offset:33792
	v_mfma_f32_16x16x32_bf16 v[38:41], v[226:229], v[202:205], v[38:41]
	v_mfma_f32_16x16x32_bf16 v[38:41], v[230:233], v[206:209], v[38:41]
	v_mfma_f32_16x16x32_bf16 v[34:37], v[234:237], v[202:205], v[34:37]
	ds_read_b128 v[202:205], v166 offset:34816
	v_mfma_f32_16x16x32_bf16 v[34:37], v[238:241], v[206:209], v[34:37]
	ds_read_b128 v[206:209], v166 offset:35840
	v_mfma_f32_16x16x32_bf16 v[22:25], v[226:229], v[210:213], v[22:25]
	v_mfma_f32_16x16x32_bf16 v[22:25], v[230:233], v[214:217], v[22:25]
	v_mfma_f32_16x16x32_bf16 v[18:21], v[234:237], v[210:213], v[18:21]
	ds_read_b128 v[210:213], v166 offset:36864
	v_mfma_f32_16x16x32_bf16 v[18:21], v[238:241], v[214:217], v[18:21]
	ds_read_b128 v[214:217], v166 offset:37888
	v_mfma_f32_16x16x32_bf16 v[6:9], v[226:229], v[218:221], v[6:9]
	v_mfma_f32_16x16x32_bf16 v[6:9], v[230:233], v[222:225], v[6:9]
	v_mfma_f32_16x16x32_bf16 v[2:5], v[234:237], v[218:221], v[2:5]
	s_barrier
	v_mfma_f32_16x16x32_bf16 v[2:5], v[238:241], v[222:225], v[2:5]
	s_setprio 0
	s_add_i32 s39, 0, 0x18000
	s_add_u32 s24, vcc_lo, 0x40000
	s_addc_u32 s25, vcc_hi, 0
	s_mov_b32 m0, s97
	ds_read_b128 v[218:221], v166 offset:38912
	ds_read_b128 v[222:225], v166 offset:39936
	global_load_lds_dwordx4 v136, s[24:25]
	s_mov_b32 m0, s98
	s_nop 0
	global_load_lds_dwordx4 v132, s[24:25]
	s_waitcnt lgkmcnt(8)
	s_barrier
	s_waitcnt lgkmcnt(0)
	s_setprio 1
	s_waitcnt lgkmcnt(0)
	v_mfma_f32_16x16x32_bf16 v[126:129], v[142:145], v[194:197], v[126:129]
	v_mfma_f32_16x16x32_bf16 v[126:129], v[182:185], v[198:201], v[126:129]
	v_mfma_f32_16x16x32_bf16 v[122:125], v[186:189], v[194:197], v[122:125]
	v_mfma_f32_16x16x32_bf16 v[122:125], v[190:193], v[198:201], v[122:125]
	v_mfma_f32_16x16x32_bf16 v[110:113], v[142:145], v[202:205], v[110:113]
	v_mfma_f32_16x16x32_bf16 v[110:113], v[182:185], v[206:209], v[110:113]
	v_mfma_f32_16x16x32_bf16 v[106:109], v[186:189], v[202:205], v[106:109]
	v_mfma_f32_16x16x32_bf16 v[106:109], v[190:193], v[206:209], v[106:109]
	v_mfma_f32_16x16x32_bf16 v[94:97], v[142:145], v[210:213], v[94:97]
	v_mfma_f32_16x16x32_bf16 v[94:97], v[182:185], v[214:217], v[94:97]
	v_mfma_f32_16x16x32_bf16 v[90:93], v[186:189], v[210:213], v[90:93]
	v_mfma_f32_16x16x32_bf16 v[90:93], v[190:193], v[214:217], v[90:93]
	v_mfma_f32_16x16x32_bf16 v[78:81], v[142:145], v[218:221], v[78:81]
	v_mfma_f32_16x16x32_bf16 v[78:81], v[182:185], v[222:225], v[78:81]
	v_mfma_f32_16x16x32_bf16 v[74:77], v[186:189], v[218:221], v[74:77]
	s_barrier
; #define PG8_STAGE(bufoff, gbase, voff) do { _Pragma("unroll") for (int _i = 0; _i < 2; ++_i) \
;         __builtin_amdgcn_global_load_lds((const unsigned*)((const char*)(gbase) + (voff)[_i]), (LAS unsigned*)(lds + (bufoff) + ldsw + _i * 8192), 16, 0, 0); } while (0)
; #define PG8_LDA(dst, b, h) do { _Pragma("unroll") for (int m = 0; m < 4; ++m) _Pragma("unroll") for (int k = 0; k < 2; ++k) dst[m][k] = *(const LAS bf16x8*)(lds + PG8_SA(b, h) + aoff + m * 2048 + k * 1024); } while (0)
; #define PG8_LDB(dst, b, h) do { _Pragma("unroll") for (int n = 0; n < 2; ++n) _Pragma("unroll") for (int k = 0; k < 2; ++k) dst[n][k] = *(const LAS bf16x8*)(lds + PG8_SB(b, h) + boff + n * 2048 + k * 1024); } while (0)
; #define PG8_MMA(ai, bj, At, Bt) do { __builtin_amdgcn_s_setprio(1); _Pragma("unroll") for (int m = 0; m < 4; ++m) _Pragma("unroll") for (int n = 0; n < 2; ++n) _Pragma("unroll") for (int k = 0; k < 2; ++k) \
;         acc[ai][bj][m][n] = __builtin_amdgcn_mfma_f32_16x16x32_bf16(Bt[n][k], At[m][k], acc[ai][bj][m][n], 0, 0, 0); __builtin_amdgcn_s_setprio(0); } while (0)
; #define PG8_WAIT_V(n) asm volatile("s_waitcnt vmcnt(" #n ")" ::: "memory")
; #define PG8_WAIT_L(n) asm volatile("s_waitcnt lgkmcnt(" #n ")" ::: "memory")
; #define PG8_BAR __builtin_amdgcn_s_barrier()
; #define PG8_SCHED __builtin_amdgcn_sched_barrier(0)
; template <class Epi, class Sched>
; __device__ __forceinline__ void gemm_phase(LAS unsigned char* lds, const Gemm g, const Sched& S, const Epi& E) {
;     ...
;             PG8_LDB(B1, 1, 1); PG8_STAGE(PG8_SB(1, 0), b3, voffB);
;             PG8_BAR; PG8_WAIT_L(0); PG8_MMA(0, 1, At, B1); PG8_BAR;
;             PG8_LDA(At, 1, 1); PG8_STAGE(PG8_SA(1, 0), a3, voffA);
;             PG8_BAR; PG8_WAIT_L(0); PG8_MMA(1, 0, At, B0); PG8_BAR; PG8_SCHED;
;             PG8_STAGE(PG8_SB(1, 1), b3 + hstep, voffB);
;             PG8_WAIT_V(6); PG8_BAR; PG8_MMA(1, 1, At, B1); PG8_BAR;
;         }
;         if (wr == 0) PG8_BAR;
	v_mfma_f32_16x16x32_bf16 v[74:77], v[190:193], v[222:225], v[74:77]
	s_setprio 0
	s_add_i32 s51, 0, 0x1c000
	s_add_i32 s24, s39, s94
	s_add_i32 m0, s24, 0xffffff80
	ds_read_b128 v[226:229], v249 offset:49152
	ds_read_b128 v[230:233], v249 offset:50176
	ds_read_b128 v[234:237], v249 offset:51200
	ds_read_b128 v[238:241], v249 offset:52224
	global_load_lds_dwordx4 v134, s[48:49] offset:128
	s_add_i32 m0, s24, 0x1f80
	s_nop 0
	global_load_lds_dwordx4 v130, s[48:49] offset:128
	s_barrier
	s_waitcnt lgkmcnt(0)
	s_setprio 1
	s_waitcnt lgkmcnt(0)
	v_mfma_f32_16x16x32_bf16 v[118:121], v[226:229], v[194:197], v[118:121]
	v_mfma_f32_16x16x32_bf16 v[118:121], v[230:233], v[198:201], v[118:121]
	v_mfma_f32_16x16x32_bf16 v[114:117], v[234:237], v[194:197], v[114:117]
	v_mfma_f32_16x16x32_bf16 v[114:117], v[238:241], v[198:201], v[114:117]
	v_mfma_f32_16x16x32_bf16 v[102:105], v[226:229], v[202:205], v[102:105]
	v_mfma_f32_16x16x32_bf16 v[102:105], v[230:233], v[206:209], v[102:105]
	v_mfma_f32_16x16x32_bf16 v[98:101], v[234:237], v[202:205], v[98:101]
	v_mfma_f32_16x16x32_bf16 v[98:101], v[238:241], v[206:209], v[98:101]
	v_mfma_f32_16x16x32_bf16 v[86:89], v[226:229], v[210:213], v[86:89]
	v_mfma_f32_16x16x32_bf16 v[86:89], v[230:233], v[214:217], v[86:89]
	v_mfma_f32_16x16x32_bf16 v[82:85], v[234:237], v[210:213], v[82:85]
	v_mfma_f32_16x16x32_bf16 v[82:85], v[238:241], v[214:217], v[82:85]
	v_mfma_f32_16x16x32_bf16 v[70:73], v[226:229], v[218:221], v[70:73]
	v_mfma_f32_16x16x32_bf16 v[70:73], v[230:233], v[222:225], v[70:73]
	v_mfma_f32_16x16x32_bf16 v[66:69], v[234:237], v[218:221], v[66:69]
	s_barrier
	v_mfma_f32_16x16x32_bf16 v[66:69], v[238:241], v[222:225], v[66:69]
	s_setprio 0
	s_add_i32 m0, s99, 0xffffff80
	ds_read_b128 v[194:197], v166 offset:49152
	ds_read_b128 v[198:201], v166 offset:50176
	ds_read_b128 v[202:205], v166 offset:51200
	ds_read_b128 v[206:209], v166 offset:52224
	ds_read_b128 v[210:213], v166 offset:53248
	ds_read_b128 v[214:217], v166 offset:54272
	ds_read_b128 v[218:221], v166 offset:55296
	ds_read_b128 v[222:225], v166 offset:56320
	global_load_lds_dwordx4 v136, vcc offset:128
	s_add_i32 m0, s82, 0xffffff80
	s_nop 0
	global_load_lds_dwordx4 v132, vcc offset:128
	s_waitcnt vmcnt(8)
	s_barrier
	s_waitcnt lgkmcnt(0)
	s_setprio 1
	s_waitcnt lgkmcnt(0)
	v_mfma_f32_16x16x32_bf16 v[62:65], v[142:145], v[194:197], v[62:65]
	v_mfma_f32_16x16x32_bf16 v[62:65], v[182:185], v[198:201], v[62:65]
	v_mfma_f32_16x16x32_bf16 v[58:61], v[186:189], v[194:197], v[58:61]
	v_mfma_f32_16x16x32_bf16 v[58:61], v[190:193], v[198:201], v[58:61]
	v_mfma_f32_16x16x32_bf16 v[46:49], v[142:145], v[202:205], v[46:49]
	v_mfma_f32_16x16x32_bf16 v[46:49], v[182:185], v[206:209], v[46:49]
	v_mfma_f32_16x16x32_bf16 v[42:45], v[186:189], v[202:205], v[42:45]
	v_mfma_f32_16x16x32_bf16 v[42:45], v[190:193], v[206:209], v[42:45]
	v_mfma_f32_16x16x32_bf16 v[30:33], v[142:145], v[210:213], v[30:33]
	v_mfma_f32_16x16x32_bf16 v[30:33], v[182:185], v[214:217], v[30:33]
	v_mfma_f32_16x16x32_bf16 v[26:29], v[186:189], v[210:213], v[26:29]
	v_mfma_f32_16x16x32_bf16 v[26:29], v[190:193], v[214:217], v[26:29]
	v_mfma_f32_16x16x32_bf16 v[14:17], v[142:145], v[218:221], v[14:17]
	v_mfma_f32_16x16x32_bf16 v[14:17], v[182:185], v[222:225], v[14:17]
	v_mfma_f32_16x16x32_bf16 v[10:13], v[186:189], v[218:221], v[10:13]
	s_barrier
	v_mfma_f32_16x16x32_bf16 v[10:13], v[190:193], v[222:225], v[10:13]
	s_setprio 0
	s_add_u32 s24, s48, 0x40080
	s_addc_u32 s25, s49, 0
	s_add_i32 s39, s51, s94
	s_mov_b32 m0, s39
	s_nop 0
	global_load_lds_dwordx4 v134, s[24:25]
	s_add_i32 m0, s39, 0x2000
	s_nop 0
	global_load_lds_dwordx4 v130, s[24:25]
	s_add_i32 s38, s38, 2
	s_add_u32 s35, s35, 0x100
	s_addc_u32 s50, s50, 0
	s_add_u32 s0, s0, 0x100
	s_addc_u32 s1, s1, 0
	s_add_u32 s24, s0, 0xfffc0080
	s_addc_u32 s25, s1, -1
	s_add_i32 s39, 0, 0x10000
	s_cmp_eq_u32 s38, 12
	s_cselect_b32 vcc_hi, s77, s25
	s_cselect_b32 vcc_lo, s76, s24
	s_cselect_b32 s49, s45, s50
	s_cselect_b32 s48, s47, s35
	s_waitcnt vmcnt(6)
	s_barrier
	s_setprio 1
	v_mfma_f32_16x16x32_bf16 v[54:57], v[226:229], v[194:197], v[54:57]
	ds_read_b128 v[142:145], v249
	ds_read_b128 v[182:185], v249 offset:1024
	v_mfma_f32_16x16x32_bf16 v[54:57], v[230:233], v[198:201], v[54:57]
	ds_read_b128 v[186:189], v249 offset:2048
	ds_read_b128 v[190:193], v249 offset:3072
	v_mfma_f32_16x16x32_bf16 v[50:53], v[234:237], v[194:197], v[50:53]
	ds_read_b128 v[194:197], v166
	v_mfma_f32_16x16x32_bf16 v[50:53], v[238:241], v[198:201], v[50:53]
	ds_read_b128 v[198:201], v166 offset:1024
	v_mfma_f32_16x16x32_bf16 v[38:41], v[226:229], v[202:205], v[38:41]
	v_mfma_f32_16x16x32_bf16 v[38:41], v[230:233], v[206:209], v[38:41]
	v_mfma_f32_16x16x32_bf16 v[34:37], v[234:237], v[202:205], v[34:37]
	ds_read_b128 v[202:205], v166 offset:2048
	v_mfma_f32_16x16x32_bf16 v[34:37], v[238:241], v[206:209], v[34:37]
	ds_read_b128 v[206:209], v166 offset:3072
	v_mfma_f32_16x16x32_bf16 v[22:25], v[226:229], v[210:213], v[22:25]
	v_mfma_f32_16x16x32_bf16 v[22:25], v[230:233], v[214:217], v[22:25]
	v_mfma_f32_16x16x32_bf16 v[18:21], v[234:237], v[210:213], v[18:21]
	ds_read_b128 v[210:213], v166 offset:4096
	v_mfma_f32_16x16x32_bf16 v[18:21], v[238:241], v[214:217], v[18:21]
	ds_read_b128 v[214:217], v166 offset:5120
	v_mfma_f32_16x16x32_bf16 v[6:9], v[226:229], v[218:221], v[6:9]
	v_mfma_f32_16x16x32_bf16 v[6:9], v[230:233], v[222:225], v[6:9]
	v_mfma_f32_16x16x32_bf16 v[2:5], v[234:237], v[218:221], v[2:5]
	s_barrier
	v_mfma_f32_16x16x32_bf16 v[2:5], v[238:241], v[222:225], v[2:5]
	s_setprio 0
	s_cmp_gt_u32 s38, 13
	s_cbranch_scc0 .LBB0_557
	s_waitcnt lgkmcnt(0)
	s_and_b64 vcc, exec, s[42:43]
	s_cbranch_vccz .LBB0_560
	s_barrier

; #define PG8_STAGE(bufoff, gbase, voff) do { _Pragma("unroll") for (int _i = 0; _i < 2; ++_i) \
;         __builtin_amdgcn_global_load_lds((const unsigned*)((const char*)(gbase) + (voff)[_i]), (LAS unsigned*)(lds + (bufoff) + ldsw + _i * 8192), 16, 0, 0); } while (0)
; #define PG8_LDA(dst, b, h) do { _Pragma("unroll") for (int m = 0; m < 4; ++m) _Pragma("unroll") for (int k = 0; k < 2; ++k) dst[m][k] = *(const LAS bf16x8*)(lds + PG8_SA(b, h) + aoff + m * 2048 + k * 1024); } while (0)
; #define PG8_LDB(dst, b, h) do { _Pragma("unroll") for (int n = 0; n < 2; ++n) _Pragma("unroll") for (int k = 0; k < 2; ++k) dst[n][k] = *(const LAS bf16x8*)(lds + PG8_SB(b, h) + boff + n * 2048 + k * 1024); } while (0)
; #define PG8_MMA(ai, bj, At, Bt) do { __builtin_amdgcn_s_setprio(1); _Pragma("unroll") for (int m = 0; m < 4; ++m) _Pragma("unroll") for (int n = 0; n < 2; ++n) _Pragma("unroll") for (int k = 0; k < 2; ++k) \
;         acc[ai][bj][m][n] = __builtin_amdgcn_mfma_f32_16x16x32_bf16(Bt[n][k], At[m][k], acc[ai][bj][m][n], 0, 0, 0); __builtin_amdgcn_s_setprio(0); } while (0)
; #define PG8_WAIT_L(n) asm volatile("s_waitcnt lgkmcnt(" #n ")" ::: "memory")
; template <class Epi, class Sched>
; __device__ __forceinline__ void gemm_phase(LAS unsigned char* lds, const Gemm g, const Sched& S, const Epi& E) {
;     ...
;         const bool has_next = S.next(ui + 1, nxt);
;         const char* nA = has_next ? PG8_APANEL(nxt.pm) : cA; const char* nB = has_next ? (const char*)g.Bt + (size_t)nxt.pn * tstep : cB;
;         for (int t = 0; t < nt; t += 2) {
;             const bool last = (t == nt - 2);
;             const char* a1 = cA + (size_t)(t + 1) * kstep;
;             const char* a2 = last ? nA : cA + (size_t)(t + 2) * kstep; const char* b2 = last ? nB : cB + (size_t)(t + 2) * kstep;
;             const char* a3 = a2 + kstep; const char* b3 = b2 + kstep;
;             PG8_LDB(B0, 0, 0); PG8_SCHED; PG8_LDA(At, 0, 0); PG8_STAGE(PG8_SA(1, 1), a1 + hstep, voffA);
;             PG8_WAIT_L(8); PG8_BAR; PG8_WAIT_L(0); PG8_MMA(0, 0, At, B0); PG8_BAR; PG8_SCHED;
;             PG8_LDB(B1, 0, 1); PG8_STAGE(PG8_SB(0, 0), b2, voffB);
;             PG8_BAR; PG8_WAIT_L(0); PG8_MMA(0, 1, At, B1); PG8_BAR;
;             PG8_LDA(At, 0, 1); PG8_STAGE(PG8_SA(0, 0), a2, voffA);
;             PG8_BAR; PG8_WAIT_L(0); PG8_MMA(1, 0, At, B0); PG8_BAR; PG8_SCHED;
.LBB0_626:
	s_ashr_i32 s43, s42, 31
	s_lshl_b64 s[24:25], s[42:43], 21
	s_add_u32 s60, s55, s24
	s_addc_u32 s61, s82, s25
	s_and_b64 s[0:1], s[0:1], exec
	s_cselect_b32 s43, s61, s49
	s_cselect_b32 s45, s60, s48
	s_add_u32 s35, s48, 0x100
	s_addc_u32 s50, s49, 0
	s_add_u32 s0, s76, 0x100080
	s_addc_u32 s1, s77, 0
	s_mov_b32 s98, -2
	v_add_u32_e32 v249, 0x10000, v144
	ds_read_b128 v[164:167], v249
	ds_read_b128 v[182:185], v249 offset:1024
	ds_read_b128 v[186:189], v249 offset:2048
	ds_read_b128 v[190:193], v249 offset:3072
	ds_read_b128 v[194:197], v162
	ds_read_b128 v[198:201], v162 offset:1024
	ds_read_b128 v[202:205], v162 offset:2048
	ds_read_b128 v[206:209], v162 offset:3072
	ds_read_b128 v[210:213], v162 offset:4096
	ds_read_b128 v[214:217], v162 offset:5120
	s_add_u32 s24, s0, 0xfff00080
	s_addc_u32 s25, s1, -1
	s_add_i32 s51, 0, 0x10000
	s_cmp_eq_u32 s98, 60
	s_cselect_b32 s77, s47, s25
	s_cselect_b32 s76, s46, s24
	s_cselect_b32 s49, s43, s50
	s_cselect_b32 s48, s45, s35
	s_add_i32 m0, s86, 0xc000
	ds_read_b128 v[218:221], v162 offset:6144
	ds_read_b128 v[222:225], v162 offset:7168
	global_load_lds_dwordx4 v140, s[0:1]
	s_add_i32 m0, s86, 0xe000
	s_nop 0
	global_load_lds_dwordx4 v138, s[0:1]
	s_waitcnt lgkmcnt(8)
	s_barrier
	s_waitcnt lgkmcnt(0)
	s_setprio 1
	s_waitcnt lgkmcnt(0)
	v_mfma_f32_16x16x32_bf16 v[126:129], v[164:167], v[194:197], 0
	v_mfma_f32_16x16x32_bf16 v[126:129], v[182:185], v[198:201], v[126:129]
	v_mfma_f32_16x16x32_bf16 v[122:125], v[186:189], v[194:197], 0
	v_mfma_f32_16x16x32_bf16 v[122:125], v[190:193], v[198:201], v[122:125]
	v_mfma_f32_16x16x32_bf16 v[118:121], v[164:167], v[202:205], 0
	v_mfma_f32_16x16x32_bf16 v[118:121], v[182:185], v[206:209], v[118:121]
	v_mfma_f32_16x16x32_bf16 v[110:113], v[186:189], v[202:205], 0
	v_mfma_f32_16x16x32_bf16 v[110:113], v[190:193], v[206:209], v[110:113]
	v_mfma_f32_16x16x32_bf16 v[102:105], v[164:167], v[210:213], 0
	v_mfma_f32_16x16x32_bf16 v[102:105], v[182:185], v[214:217], v[102:105]
	v_mfma_f32_16x16x32_bf16 v[94:97], v[186:189], v[210:213], 0
	v_mfma_f32_16x16x32_bf16 v[94:97], v[190:193], v[214:217], v[94:97]
	v_mfma_f32_16x16x32_bf16 v[86:89], v[164:167], v[218:221], 0
	v_mfma_f32_16x16x32_bf16 v[86:89], v[182:185], v[222:225], v[86:89]
	v_mfma_f32_16x16x32_bf16 v[78:81], v[186:189], v[218:221], 0
	s_barrier
	v_mfma_f32_16x16x32_bf16 v[78:81], v[190:193], v[222:225], v[78:81]
	s_setprio 0
	s_add_i32 s99, 0, 0x14000
	s_add_i32 s24, s51, s83
	ds_read_b128 v[226:229], v249 offset:16384
	ds_read_b128 v[230:233], v249 offset:17408
	ds_read_b128 v[234:237], v249 offset:18432
	ds_read_b128 v[238:241], v249 offset:19456
	s_mov_b32 m0, s24
	global_load_lds_dwordx4 v134, s[48:49]
	s_add_i32 m0, s24, 0x2000
	s_nop 0
	global_load_lds_dwordx4 v130, s[48:49]
	s_barrier
	s_waitcnt lgkmcnt(0)
	s_setprio 1
	s_waitcnt lgkmcnt(0)
	v_mfma_f32_16x16x32_bf16 v[114:117], v[226:229], v[194:197], 0
	v_mfma_f32_16x16x32_bf16 v[114:117], v[230:233], v[198:201], v[114:117]
	v_mfma_f32_16x16x32_bf16 v[106:109], v[234:237], v[194:197], 0
	v_mfma_f32_16x16x32_bf16 v[106:109], v[238:241], v[198:201], v[106:109]
	v_mfma_f32_16x16x32_bf16 v[98:101], v[226:229], v[202:205], 0
	v_mfma_f32_16x16x32_bf16 v[98:101], v[230:233], v[206:209], v[98:101]
	v_mfma_f32_16x16x32_bf16 v[90:93], v[234:237], v[202:205], 0
	v_mfma_f32_16x16x32_bf16 v[90:93], v[238:241], v[206:209], v[90:93]
	v_mfma_f32_16x16x32_bf16 v[82:85], v[226:229], v[210:213], 0
	v_mfma_f32_16x16x32_bf16 v[82:85], v[230:233], v[214:217], v[82:85]
	v_mfma_f32_16x16x32_bf16 v[74:77], v[234:237], v[210:213], 0
	v_mfma_f32_16x16x32_bf16 v[74:77], v[238:241], v[214:217], v[74:77]
	v_mfma_f32_16x16x32_bf16 v[70:73], v[226:229], v[218:221], 0
	v_mfma_f32_16x16x32_bf16 v[70:73], v[230:233], v[222:225], v[70:73]
	v_mfma_f32_16x16x32_bf16 v[66:69], v[234:237], v[218:221], 0
	s_barrier
	v_mfma_f32_16x16x32_bf16 v[66:69], v[238:241], v[222:225], v[66:69]
	s_setprio 0
	s_mov_b32 m0, s86
	s_mov_b64 s[100:101], s[76:77]
	ds_read_b128 v[194:197], v162 offset:16384
	ds_read_b128 v[198:201], v162 offset:17408
	ds_read_b128 v[202:205], v162 offset:18432
	ds_read_b128 v[206:209], v162 offset:19456
	ds_read_b128 v[210:213], v162 offset:20480
	ds_read_b128 v[214:217], v162 offset:21504
	ds_read_b128 v[218:221], v162 offset:22528
	ds_read_b128 v[222:225], v162 offset:23552
	global_load_lds_dwordx4 v136, s[76:77]
	s_mov_b64 s[100:101], s[76:77]
	s_mov_b32 m0, s92
	s_nop 0
	global_load_lds_dwordx4 v132, s[76:77]
	s_waitcnt vmcnt(8)
	s_barrier
	s_waitcnt lgkmcnt(0)
	s_setprio 1
	s_waitcnt lgkmcnt(0)
	v_mfma_f32_16x16x32_bf16 v[62:65], v[164:167], v[194:197], 0
	v_mfma_f32_16x16x32_bf16 v[62:65], v[182:185], v[198:201], v[62:65]
	v_mfma_f32_16x16x32_bf16 v[58:61], v[186:189], v[194:197], 0
	v_mfma_f32_16x16x32_bf16 v[58:61], v[190:193], v[198:201], v[58:61]
	v_mfma_f32_16x16x32_bf16 v[54:57], v[164:167], v[202:205], 0
	v_mfma_f32_16x16x32_bf16 v[54:57], v[182:185], v[206:209], v[54:57]
	v_mfma_f32_16x16x32_bf16 v[46:49], v[186:189], v[202:205], 0
	v_mfma_f32_16x16x32_bf16 v[46:49], v[190:193], v[206:209], v[46:49]
	v_mfma_f32_16x16x32_bf16 v[38:41], v[164:167], v[210:213], 0
	v_mfma_f32_16x16x32_bf16 v[38:41], v[182:185], v[214:217], v[38:41]
	v_mfma_f32_16x16x32_bf16 v[30:33], v[186:189], v[210:213], 0
	v_mfma_f32_16x16x32_bf16 v[30:33], v[190:193], v[214:217], v[30:33]
	v_mfma_f32_16x16x32_bf16 v[22:25], v[164:167], v[218:221], 0
	v_mfma_f32_16x16x32_bf16 v[22:25], v[182:185], v[222:225], v[22:25]
	v_mfma_f32_16x16x32_bf16 v[14:17], v[186:189], v[218:221], 0
	s_barrier
; #define PG8_STAGE(bufoff, gbase, voff) do { _Pragma("unroll") for (int _i = 0; _i < 2; ++_i) \
;         __builtin_amdgcn_global_load_lds((const unsigned*)((const char*)(gbase) + (voff)[_i]), (LAS unsigned*)(lds + (bufoff) + ldsw + _i * 8192), 16, 0, 0); } while (0)
; #define PG8_LDA(dst, b, h) do { _Pragma("unroll") for (int m = 0; m < 4; ++m) _Pragma("unroll") for (int k = 0; k < 2; ++k) dst[m][k] = *(const LAS bf16x8*)(lds + PG8_SA(b, h) + aoff + m * 2048 + k * 1024); } while (0)
; #define PG8_LDB(dst, b, h) do { _Pragma("unroll") for (int n = 0; n < 2; ++n) _Pragma("unroll") for (int k = 0; k < 2; ++k) dst[n][k] = *(const LAS bf16x8*)(lds + PG8_SB(b, h) + boff + n * 2048 + k * 1024); } while (0)
; #define PG8_MMA(ai, bj, At, Bt) do { __builtin_amdgcn_s_setprio(1); _Pragma("unroll") for (int m = 0; m < 4; ++m) _Pragma("unroll") for (int n = 0; n < 2; ++n) _Pragma("unroll") for (int k = 0; k < 2; ++k) \
;         acc[ai][bj][m][n] = __builtin_amdgcn_mfma_f32_16x16x32_bf16(Bt[n][k], At[m][k], acc[ai][bj][m][n], 0, 0, 0); __builtin_amdgcn_s_setprio(0); } while (0)
; #define PG8_WAIT_V(n) asm volatile("s_waitcnt vmcnt(" #n ")" ::: "memory")
; #define PG8_WAIT_L(n) asm volatile("s_waitcnt lgkmcnt(" #n ")" ::: "memory")
; #define PG8_BAR __builtin_amdgcn_s_barrier()
; #define PG8_SCHED __builtin_amdgcn_sched_barrier(0)
; template <class Epi, class Sched>
; __device__ __forceinline__ void gemm_phase(LAS unsigned char* lds, const Gemm g, const Sched& S, const Epi& E) {
;     ...
;             PG8_STAGE(PG8_SB(0, 1), b2 + hstep, voffB);
;             PG8_WAIT_V(6); PG8_BAR; PG8_MMA(1, 1, At, B1); PG8_BAR;
;             PG8_LDB(B0, 1, 0); PG8_SCHED; PG8_LDA(At, 1, 0); PG8_STAGE(PG8_SA(0, 1), a2 + hstep, voffA);
;             PG8_WAIT_L(8); PG8_BAR; PG8_WAIT_L(0); PG8_MMA(0, 0, At, B0); PG8_BAR; PG8_SCHED;
;             PG8_LDB(B1, 1, 1); PG8_STAGE(PG8_SB(1, 0), b3, voffB);
;             PG8_BAR; PG8_WAIT_L(0); PG8_MMA(0, 1, At, B1); PG8_BAR;
;             PG8_LDA(At, 1, 1); PG8_STAGE(PG8_SA(1, 0), a3, voffA);
;             PG8_BAR; PG8_WAIT_L(0); PG8_MMA(1, 0, At, B0); PG8_BAR; PG8_SCHED;
	v_mfma_f32_16x16x32_bf16 v[14:17], v[190:193], v[222:225], v[14:17]
	s_setprio 0
	s_add_u32 s24, s48, 0x100000
	s_addc_u32 s25, s49, 0
	s_add_i32 s51, s99, s83
	s_mov_b32 m0, s51
	s_nop 0
	global_load_lds_dwordx4 v134, s[24:25]
	s_add_i32 m0, s51, 0x2000
	s_nop 0
	global_load_lds_dwordx4 v130, s[24:25]
	s_waitcnt vmcnt(6)
	s_barrier
	s_setprio 1
	v_mfma_f32_16x16x32_bf16 v[50:53], v[226:229], v[194:197], 0
	ds_read_b128 v[164:167], v249 offset:32768
	ds_read_b128 v[182:185], v249 offset:33792
	v_mfma_f32_16x16x32_bf16 v[50:53], v[230:233], v[198:201], v[50:53]
	ds_read_b128 v[186:189], v249 offset:34816
	ds_read_b128 v[190:193], v249 offset:35840
	v_mfma_f32_16x16x32_bf16 v[42:45], v[234:237], v[194:197], 0
	ds_read_b128 v[194:197], v162 offset:32768
	v_mfma_f32_16x16x32_bf16 v[42:45], v[238:241], v[198:201], v[42:45]
	ds_read_b128 v[198:201], v162 offset:33792
	v_mfma_f32_16x16x32_bf16 v[34:37], v[226:229], v[202:205], 0
	v_mfma_f32_16x16x32_bf16 v[34:37], v[230:233], v[206:209], v[34:37]
	v_mfma_f32_16x16x32_bf16 v[26:29], v[234:237], v[202:205], 0
	ds_read_b128 v[202:205], v162 offset:34816
	v_mfma_f32_16x16x32_bf16 v[26:29], v[238:241], v[206:209], v[26:29]
	ds_read_b128 v[206:209], v162 offset:35840
	v_mfma_f32_16x16x32_bf16 v[18:21], v[226:229], v[210:213], 0
	v_mfma_f32_16x16x32_bf16 v[18:21], v[230:233], v[214:217], v[18:21]
	v_mfma_f32_16x16x32_bf16 v[10:13], v[234:237], v[210:213], 0
	ds_read_b128 v[210:213], v162 offset:36864
	v_mfma_f32_16x16x32_bf16 v[10:13], v[238:241], v[214:217], v[10:13]
	ds_read_b128 v[214:217], v162 offset:37888
	v_mfma_f32_16x16x32_bf16 v[6:9], v[226:229], v[218:221], 0
	v_mfma_f32_16x16x32_bf16 v[6:9], v[230:233], v[222:225], v[6:9]
	v_mfma_f32_16x16x32_bf16 v[2:5], v[234:237], v[218:221], 0
	s_barrier
	v_mfma_f32_16x16x32_bf16 v[2:5], v[238:241], v[222:225], v[2:5]
	s_setprio 0
	s_add_i32 s51, 0, 0x18000
	s_add_u32 s24, s76, 0x100000
	s_addc_u32 s25, s77, 0
	s_mov_b32 m0, s93
	ds_read_b128 v[218:221], v162 offset:38912
	ds_read_b128 v[222:225], v162 offset:39936
	global_load_lds_dwordx4 v136, s[24:25]
	s_mov_b32 m0, s94
	s_nop 0
	global_load_lds_dwordx4 v132, s[24:25]
	s_waitcnt lgkmcnt(8)
	s_barrier
	s_waitcnt lgkmcnt(0)
	s_setprio 1
	s_waitcnt lgkmcnt(0)
	v_mfma_f32_16x16x32_bf16 v[126:129], v[164:167], v[194:197], v[126:129]
	v_mfma_f32_16x16x32_bf16 v[126:129], v[182:185], v[198:201], v[126:129]
	v_mfma_f32_16x16x32_bf16 v[122:125], v[186:189], v[194:197], v[122:125]
	v_mfma_f32_16x16x32_bf16 v[122:125], v[190:193], v[198:201], v[122:125]
	v_mfma_f32_16x16x32_bf16 v[118:121], v[164:167], v[202:205], v[118:121]
	v_mfma_f32_16x16x32_bf16 v[118:121], v[182:185], v[206:209], v[118:121]
	v_mfma_f32_16x16x32_bf16 v[110:113], v[186:189], v[202:205], v[110:113]
	v_mfma_f32_16x16x32_bf16 v[110:113], v[190:193], v[206:209], v[110:113]
	v_mfma_f32_16x16x32_bf16 v[102:105], v[164:167], v[210:213], v[102:105]
	v_mfma_f32_16x16x32_bf16 v[102:105], v[182:185], v[214:217], v[102:105]
	v_mfma_f32_16x16x32_bf16 v[94:97], v[186:189], v[210:213], v[94:97]
	v_mfma_f32_16x16x32_bf16 v[94:97], v[190:193], v[214:217], v[94:97]
	v_mfma_f32_16x16x32_bf16 v[86:89], v[164:167], v[218:221], v[86:89]
	v_mfma_f32_16x16x32_bf16 v[86:89], v[182:185], v[222:225], v[86:89]
	v_mfma_f32_16x16x32_bf16 v[78:81], v[186:189], v[218:221], v[78:81]
	s_barrier
	v_mfma_f32_16x16x32_bf16 v[78:81], v[190:193], v[222:225], v[78:81]
	s_setprio 0
	s_add_i32 s76, 0, 0x1c000
	s_add_i32 s24, s51, s83
	s_add_i32 m0, s24, 0xffffff80
	ds_read_b128 v[226:229], v249 offset:49152
	ds_read_b128 v[230:233], v249 offset:50176
	ds_read_b128 v[234:237], v249 offset:51200
	ds_read_b128 v[238:241], v249 offset:52224
	global_load_lds_dwordx4 v134, s[48:49] offset:128
	s_add_i32 m0, s24, 0x1f80
	s_nop 0
	global_load_lds_dwordx4 v130, s[48:49] offset:128
	s_barrier
	s_waitcnt lgkmcnt(0)
	s_setprio 1
	s_waitcnt lgkmcnt(0)
	v_mfma_f32_16x16x32_bf16 v[114:117], v[226:229], v[194:197], v[114:117]
	v_mfma_f32_16x16x32_bf16 v[114:117], v[230:233], v[198:201], v[114:117]
	v_mfma_f32_16x16x32_bf16 v[106:109], v[234:237], v[194:197], v[106:109]
	v_mfma_f32_16x16x32_bf16 v[106:109], v[238:241], v[198:201], v[106:109]
	v_mfma_f32_16x16x32_bf16 v[98:101], v[226:229], v[202:205], v[98:101]
	v_mfma_f32_16x16x32_bf16 v[98:101], v[230:233], v[206:209], v[98:101]
	v_mfma_f32_16x16x32_bf16 v[90:93], v[234:237], v[202:205], v[90:93]
	v_mfma_f32_16x16x32_bf16 v[90:93], v[238:241], v[206:209], v[90:93]
	v_mfma_f32_16x16x32_bf16 v[82:85], v[226:229], v[210:213], v[82:85]
	v_mfma_f32_16x16x32_bf16 v[82:85], v[230:233], v[214:217], v[82:85]
	v_mfma_f32_16x16x32_bf16 v[74:77], v[234:237], v[210:213], v[74:77]
	v_mfma_f32_16x16x32_bf16 v[74:77], v[238:241], v[214:217], v[74:77]
	v_mfma_f32_16x16x32_bf16 v[70:73], v[226:229], v[218:221], v[70:73]
	v_mfma_f32_16x16x32_bf16 v[70:73], v[230:233], v[222:225], v[70:73]
	v_mfma_f32_16x16x32_bf16 v[66:69], v[234:237], v[218:221], v[66:69]
	s_barrier
	v_mfma_f32_16x16x32_bf16 v[66:69], v[238:241], v[222:225], v[66:69]
	s_setprio 0
	s_add_i32 m0, s95, 0xffffff80
	ds_read_b128 v[194:197], v162 offset:49152
	ds_read_b128 v[198:201], v162 offset:50176
	ds_read_b128 v[202:205], v162 offset:51200
	ds_read_b128 v[206:209], v162 offset:52224
	ds_read_b128 v[210:213], v162 offset:53248
	ds_read_b128 v[214:217], v162 offset:54272
	ds_read_b128 v[218:221], v162 offset:55296
	ds_read_b128 v[222:225], v162 offset:56320
	global_load_lds_dwordx4 v136, s[100:101] offset:128
	s_add_i32 m0, s96, 0xffffff80
	s_nop 0
	global_load_lds_dwordx4 v132, s[100:101] offset:128
	s_waitcnt vmcnt(8)
	s_barrier
; #define PG8_STAGE(bufoff, gbase, voff) do { _Pragma("unroll") for (int _i = 0; _i < 2; ++_i) \
;         __builtin_amdgcn_global_load_lds((const unsigned*)((const char*)(gbase) + (voff)[_i]), (LAS unsigned*)(lds + (bufoff) + ldsw + _i * 8192), 16, 0, 0); } while (0)
; #define PG8_LDA(dst, b, h) do { _Pragma("unroll") for (int m = 0; m < 4; ++m) _Pragma("unroll") for (int k = 0; k < 2; ++k) dst[m][k] = *(const LAS bf16x8*)(lds + PG8_SA(b, h) + aoff + m * 2048 + k * 1024); } while (0)
; #define PG8_LDB(dst, b, h) do { _Pragma("unroll") for (int n = 0; n < 2; ++n) _Pragma("unroll") for (int k = 0; k < 2; ++k) dst[n][k] = *(const LAS bf16x8*)(lds + PG8_SB(b, h) + boff + n * 2048 + k * 1024); } while (0)
; #define PG8_MMA(ai, bj, At, Bt) do { __builtin_amdgcn_s_setprio(1); _Pragma("unroll") for (int m = 0; m < 4; ++m) _Pragma("unroll") for (int n = 0; n < 2; ++n) _Pragma("unroll") for (int k = 0; k < 2; ++k) \
;         acc[ai][bj][m][n] = __builtin_amdgcn_mfma_f32_16x16x32_bf16(Bt[n][k], At[m][k], acc[ai][bj][m][n], 0, 0, 0); __builtin_amdgcn_s_setprio(0); } while (0)
; #define PG8_WAIT_V(n) asm volatile("s_waitcnt vmcnt(" #n ")" ::: "memory")
; #define PG8_WAIT_L(n) asm volatile("s_waitcnt lgkmcnt(" #n ")" ::: "memory")
; #define PG8_BAR __builtin_amdgcn_s_barrier()
; #define PG8_SCHED __builtin_amdgcn_sched_barrier(0)
; template <class Epi, class Sched>
; __device__ __forceinline__ void gemm_phase(LAS unsigned char* lds, const Gemm g, const Sched& S, const Epi& E) {
;     ...
;             PG8_LDB(B0, 0, 0); PG8_SCHED; PG8_LDA(At, 0, 0); PG8_STAGE(PG8_SA(1, 1), a1 + hstep, voffA);
;             PG8_WAIT_L(8); PG8_BAR; PG8_WAIT_L(0); PG8_MMA(0, 0, At, B0); PG8_BAR; PG8_SCHED;
;             PG8_LDB(B1, 0, 1); PG8_STAGE(PG8_SB(0, 0), b2, voffB);
;             PG8_BAR; PG8_WAIT_L(0); PG8_MMA(0, 1, At, B1); PG8_BAR;
;     ...
;             PG8_LDA(At, 1, 1); PG8_STAGE(PG8_SA(1, 0), a3, voffA);
;             PG8_BAR; PG8_WAIT_L(0); PG8_MMA(1, 0, At, B0); PG8_BAR; PG8_SCHED;
;             PG8_STAGE(PG8_SB(1, 1), b3 + hstep, voffB);
;             PG8_WAIT_V(6); PG8_BAR; PG8_MMA(1, 1, At, B1); PG8_BAR;
	s_waitcnt lgkmcnt(0)
	s_setprio 1
	s_waitcnt lgkmcnt(0)
	v_mfma_f32_16x16x32_bf16 v[62:65], v[164:167], v[194:197], v[62:65]
	v_mfma_f32_16x16x32_bf16 v[62:65], v[182:185], v[198:201], v[62:65]
	v_mfma_f32_16x16x32_bf16 v[58:61], v[186:189], v[194:197], v[58:61]
	v_mfma_f32_16x16x32_bf16 v[58:61], v[190:193], v[198:201], v[58:61]
	v_mfma_f32_16x16x32_bf16 v[54:57], v[164:167], v[202:205], v[54:57]
	v_mfma_f32_16x16x32_bf16 v[54:57], v[182:185], v[206:209], v[54:57]
	v_mfma_f32_16x16x32_bf16 v[46:49], v[186:189], v[202:205], v[46:49]
	v_mfma_f32_16x16x32_bf16 v[46:49], v[190:193], v[206:209], v[46:49]
	v_mfma_f32_16x16x32_bf16 v[38:41], v[164:167], v[210:213], v[38:41]
	v_mfma_f32_16x16x32_bf16 v[38:41], v[182:185], v[214:217], v[38:41]
	v_mfma_f32_16x16x32_bf16 v[30:33], v[186:189], v[210:213], v[30:33]
	v_mfma_f32_16x16x32_bf16 v[30:33], v[190:193], v[214:217], v[30:33]
	v_mfma_f32_16x16x32_bf16 v[22:25], v[164:167], v[218:221], v[22:25]
	v_mfma_f32_16x16x32_bf16 v[22:25], v[182:185], v[222:225], v[22:25]
	v_mfma_f32_16x16x32_bf16 v[14:17], v[186:189], v[218:221], v[14:17]
	s_barrier
	v_mfma_f32_16x16x32_bf16 v[14:17], v[190:193], v[222:225], v[14:17]
	s_setprio 0
	s_add_u32 s24, s48, 0x100080
	s_addc_u32 s25, s49, 0
	s_add_i32 s48, s76, s83
	s_mov_b32 m0, s48
	s_nop 0
	global_load_lds_dwordx4 v134, s[24:25]
	s_add_i32 m0, s48, 0x2000
	s_nop 0
	global_load_lds_dwordx4 v130, s[24:25]
	s_add_i32 s98, s98, 2
	s_add_u32 s35, s35, 0x100
	s_addc_u32 s50, s50, 0
	s_add_u32 s0, s0, 0x100
	s_addc_u32 s1, s1, 0
	s_add_u32 s24, s0, 0xfff00080
	s_addc_u32 s25, s1, -1
	s_add_i32 s51, 0, 0x10000
	s_cmp_eq_u32 s98, 60
	s_cselect_b32 s77, s47, s25
	s_cselect_b32 s76, s46, s24
	s_cselect_b32 s49, s43, s50
	s_cselect_b32 s48, s45, s35
	s_waitcnt vmcnt(6)
	s_barrier
	s_setprio 1
	v_mfma_f32_16x16x32_bf16 v[50:53], v[226:229], v[194:197], v[50:53]
	ds_read_b128 v[164:167], v249
	ds_read_b128 v[182:185], v249 offset:1024
	v_mfma_f32_16x16x32_bf16 v[50:53], v[230:233], v[198:201], v[50:53]
	ds_read_b128 v[186:189], v249 offset:2048
	ds_read_b128 v[190:193], v249 offset:3072
	v_mfma_f32_16x16x32_bf16 v[42:45], v[234:237], v[194:197], v[42:45]
	ds_read_b128 v[194:197], v162
	v_mfma_f32_16x16x32_bf16 v[42:45], v[238:241], v[198:201], v[42:45]
	ds_read_b128 v[198:201], v162 offset:1024
	v_mfma_f32_16x16x32_bf16 v[34:37], v[226:229], v[202:205], v[34:37]
	v_mfma_f32_16x16x32_bf16 v[34:37], v[230:233], v[206:209], v[34:37]
	v_mfma_f32_16x16x32_bf16 v[26:29], v[234:237], v[202:205], v[26:29]
	ds_read_b128 v[202:205], v162 offset:2048
	v_mfma_f32_16x16x32_bf16 v[26:29], v[238:241], v[206:209], v[26:29]
	ds_read_b128 v[206:209], v162 offset:3072
	v_mfma_f32_16x16x32_bf16 v[18:21], v[226:229], v[210:213], v[18:21]
	v_mfma_f32_16x16x32_bf16 v[18:21], v[230:233], v[214:217], v[18:21]
	v_mfma_f32_16x16x32_bf16 v[10:13], v[234:237], v[210:213], v[10:13]
	ds_read_b128 v[210:213], v162 offset:4096
	v_mfma_f32_16x16x32_bf16 v[10:13], v[238:241], v[214:217], v[10:13]
	ds_read_b128 v[214:217], v162 offset:5120
	v_mfma_f32_16x16x32_bf16 v[6:9], v[226:229], v[218:221], v[6:9]
	v_mfma_f32_16x16x32_bf16 v[6:9], v[230:233], v[222:225], v[6:9]
	v_mfma_f32_16x16x32_bf16 v[2:5], v[234:237], v[218:221], v[2:5]
	s_barrier
	v_mfma_f32_16x16x32_bf16 v[2:5], v[238:241], v[222:225], v[2:5]
	s_setprio 0
	s_cmp_gt_u32 s98, 61
.LBB0_627:
	s_add_i32 m0, s86, 0xc000
	ds_read_b128 v[218:221], v162 offset:6144
	ds_read_b128 v[222:225], v162 offset:7168
	global_load_lds_dwordx4 v140, s[0:1]
	s_add_i32 m0, s86, 0xe000
	s_nop 0
	global_load_lds_dwordx4 v138, s[0:1]
	s_waitcnt lgkmcnt(8)
	s_barrier
	s_waitcnt lgkmcnt(0)
	s_setprio 1
	s_waitcnt lgkmcnt(0)
	v_mfma_f32_16x16x32_bf16 v[126:129], v[164:167], v[194:197], v[126:129]
	v_mfma_f32_16x16x32_bf16 v[126:129], v[182:185], v[198:201], v[126:129]
	v_mfma_f32_16x16x32_bf16 v[122:125], v[186:189], v[194:197], v[122:125]
	v_mfma_f32_16x16x32_bf16 v[122:125], v[190:193], v[198:201], v[122:125]
	v_mfma_f32_16x16x32_bf16 v[118:121], v[164:167], v[202:205], v[118:121]
	v_mfma_f32_16x16x32_bf16 v[118:121], v[182:185], v[206:209], v[118:121]
	v_mfma_f32_16x16x32_bf16 v[110:113], v[186:189], v[202:205], v[110:113]
	v_mfma_f32_16x16x32_bf16 v[110:113], v[190:193], v[206:209], v[110:113]
	v_mfma_f32_16x16x32_bf16 v[102:105], v[164:167], v[210:213], v[102:105]
	v_mfma_f32_16x16x32_bf16 v[102:105], v[182:185], v[214:217], v[102:105]
	v_mfma_f32_16x16x32_bf16 v[94:97], v[186:189], v[210:213], v[94:97]
	v_mfma_f32_16x16x32_bf16 v[94:97], v[190:193], v[214:217], v[94:97]
	v_mfma_f32_16x16x32_bf16 v[86:89], v[164:167], v[218:221], v[86:89]
	v_mfma_f32_16x16x32_bf16 v[86:89], v[182:185], v[222:225], v[86:89]
	v_mfma_f32_16x16x32_bf16 v[78:81], v[186:189], v[218:221], v[78:81]
	s_barrier
	v_mfma_f32_16x16x32_bf16 v[78:81], v[190:193], v[222:225], v[78:81]
	s_setprio 0
	s_add_i32 s99, 0, 0x14000
	s_add_i32 s24, s51, s83
	ds_read_b128 v[226:229], v249 offset:16384
	ds_read_b128 v[230:233], v249 offset:17408
	ds_read_b128 v[234:237], v249 offset:18432
	ds_read_b128 v[238:241], v249 offset:19456
	s_mov_b32 m0, s24
	global_load_lds_dwordx4 v134, s[48:49]
	s_add_i32 m0, s24, 0x2000
	s_nop 0
	global_load_lds_dwordx4 v130, s[48:49]
	s_barrier
; #define PG8_STAGE(bufoff, gbase, voff) do { _Pragma("unroll") for (int _i = 0; _i < 2; ++_i) \
;         __builtin_amdgcn_global_load_lds((const unsigned*)((const char*)(gbase) + (voff)[_i]), (LAS unsigned*)(lds + (bufoff) + ldsw + _i * 8192), 16, 0, 0); } while (0)
; #define PG8_LDA(dst, b, h) do { _Pragma("unroll") for (int m = 0; m < 4; ++m) _Pragma("unroll") for (int k = 0; k < 2; ++k) dst[m][k] = *(const LAS bf16x8*)(lds + PG8_SA(b, h) + aoff + m * 2048 + k * 1024); } while (0)
; #define PG8_LDB(dst, b, h) do { _Pragma("unroll") for (int n = 0; n < 2; ++n) _Pragma("unroll") for (int k = 0; k < 2; ++k) dst[n][k] = *(const LAS bf16x8*)(lds + PG8_SB(b, h) + boff + n * 2048 + k * 1024); } while (0)
; #define PG8_MMA(ai, bj, At, Bt) do { __builtin_amdgcn_s_setprio(1); _Pragma("unroll") for (int m = 0; m < 4; ++m) _Pragma("unroll") for (int n = 0; n < 2; ++n) _Pragma("unroll") for (int k = 0; k < 2; ++k) \
;         acc[ai][bj][m][n] = __builtin_amdgcn_mfma_f32_16x16x32_bf16(Bt[n][k], At[m][k], acc[ai][bj][m][n], 0, 0, 0); __builtin_amdgcn_s_setprio(0); } while (0)
; #define PG8_WAIT_V(n) asm volatile("s_waitcnt vmcnt(" #n ")" ::: "memory")
; #define PG8_WAIT_L(n) asm volatile("s_waitcnt lgkmcnt(" #n ")" ::: "memory")
; #define PG8_BAR __builtin_amdgcn_s_barrier()
; #define PG8_SCHED __builtin_amdgcn_sched_barrier(0)
; template <class Epi, class Sched>
; __device__ __forceinline__ void gemm_phase(LAS unsigned char* lds, const Gemm g, const Sched& S, const Epi& E) {
;     ...
;             PG8_BAR; PG8_WAIT_L(0); PG8_MMA(0, 1, At, B1); PG8_BAR;
;             PG8_LDA(At, 0, 1); PG8_STAGE(PG8_SA(0, 0), a2, voffA);
;             PG8_BAR; PG8_WAIT_L(0); PG8_MMA(1, 0, At, B0); PG8_BAR; PG8_SCHED;
;             PG8_STAGE(PG8_SB(0, 1), b2 + hstep, voffB);
;             PG8_WAIT_V(6); PG8_BAR; PG8_MMA(1, 1, At, B1); PG8_BAR;
;             PG8_LDB(B0, 1, 0); PG8_SCHED; PG8_LDA(At, 1, 0); PG8_STAGE(PG8_SA(0, 1), a2 + hstep, voffA);
;             PG8_WAIT_L(8); PG8_BAR; PG8_WAIT_L(0); PG8_MMA(0, 0, At, B0); PG8_BAR; PG8_SCHED;
	s_waitcnt lgkmcnt(0)
	s_setprio 1
	s_waitcnt lgkmcnt(0)
	v_mfma_f32_16x16x32_bf16 v[114:117], v[226:229], v[194:197], v[114:117]
	v_mfma_f32_16x16x32_bf16 v[114:117], v[230:233], v[198:201], v[114:117]
	v_mfma_f32_16x16x32_bf16 v[106:109], v[234:237], v[194:197], v[106:109]
	v_mfma_f32_16x16x32_bf16 v[106:109], v[238:241], v[198:201], v[106:109]
	v_mfma_f32_16x16x32_bf16 v[98:101], v[226:229], v[202:205], v[98:101]
	v_mfma_f32_16x16x32_bf16 v[98:101], v[230:233], v[206:209], v[98:101]
	v_mfma_f32_16x16x32_bf16 v[90:93], v[234:237], v[202:205], v[90:93]
	v_mfma_f32_16x16x32_bf16 v[90:93], v[238:241], v[206:209], v[90:93]
	v_mfma_f32_16x16x32_bf16 v[82:85], v[226:229], v[210:213], v[82:85]
	v_mfma_f32_16x16x32_bf16 v[82:85], v[230:233], v[214:217], v[82:85]
	v_mfma_f32_16x16x32_bf16 v[74:77], v[234:237], v[210:213], v[74:77]
	v_mfma_f32_16x16x32_bf16 v[74:77], v[238:241], v[214:217], v[74:77]
	v_mfma_f32_16x16x32_bf16 v[70:73], v[226:229], v[218:221], v[70:73]
	v_mfma_f32_16x16x32_bf16 v[70:73], v[230:233], v[222:225], v[70:73]
	v_mfma_f32_16x16x32_bf16 v[66:69], v[234:237], v[218:221], v[66:69]
	s_barrier
	v_mfma_f32_16x16x32_bf16 v[66:69], v[238:241], v[222:225], v[66:69]
	s_setprio 0
	s_mov_b32 m0, s86
	s_mov_b64 s[100:101], s[76:77]
	ds_read_b128 v[194:197], v162 offset:16384
	ds_read_b128 v[198:201], v162 offset:17408
	ds_read_b128 v[202:205], v162 offset:18432
	ds_read_b128 v[206:209], v162 offset:19456
	ds_read_b128 v[210:213], v162 offset:20480
	ds_read_b128 v[214:217], v162 offset:21504
	ds_read_b128 v[218:221], v162 offset:22528
	ds_read_b128 v[222:225], v162 offset:23552
	global_load_lds_dwordx4 v136, s[76:77]
	s_mov_b64 s[100:101], s[76:77]
	s_mov_b32 m0, s92
	s_nop 0
	global_load_lds_dwordx4 v132, s[76:77]
	s_waitcnt vmcnt(8)
	s_barrier
	s_waitcnt lgkmcnt(0)
	s_setprio 1
	s_waitcnt lgkmcnt(0)
	v_mfma_f32_16x16x32_bf16 v[62:65], v[164:167], v[194:197], v[62:65]
	v_mfma_f32_16x16x32_bf16 v[62:65], v[182:185], v[198:201], v[62:65]
	v_mfma_f32_16x16x32_bf16 v[58:61], v[186:189], v[194:197], v[58:61]
	v_mfma_f32_16x16x32_bf16 v[58:61], v[190:193], v[198:201], v[58:61]
	v_mfma_f32_16x16x32_bf16 v[54:57], v[164:167], v[202:205], v[54:57]
	v_mfma_f32_16x16x32_bf16 v[54:57], v[182:185], v[206:209], v[54:57]
	v_mfma_f32_16x16x32_bf16 v[46:49], v[186:189], v[202:205], v[46:49]
	v_mfma_f32_16x16x32_bf16 v[46:49], v[190:193], v[206:209], v[46:49]
	v_mfma_f32_16x16x32_bf16 v[38:41], v[164:167], v[210:213], v[38:41]
	v_mfma_f32_16x16x32_bf16 v[38:41], v[182:185], v[214:217], v[38:41]
	v_mfma_f32_16x16x32_bf16 v[30:33], v[186:189], v[210:213], v[30:33]
	v_mfma_f32_16x16x32_bf16 v[30:33], v[190:193], v[214:217], v[30:33]
	v_mfma_f32_16x16x32_bf16 v[22:25], v[164:167], v[218:221], v[22:25]
	v_mfma_f32_16x16x32_bf16 v[22:25], v[182:185], v[222:225], v[22:25]
	v_mfma_f32_16x16x32_bf16 v[14:17], v[186:189], v[218:221], v[14:17]
	s_barrier
	v_mfma_f32_16x16x32_bf16 v[14:17], v[190:193], v[222:225], v[14:17]
	s_setprio 0
	s_add_u32 s24, s48, 0x100000
	s_addc_u32 s25, s49, 0
	s_add_i32 s51, s99, s83
	s_mov_b32 m0, s51
	s_nop 0
	global_load_lds_dwordx4 v134, s[24:25]
	s_add_i32 m0, s51, 0x2000
	s_nop 0
	global_load_lds_dwordx4 v130, s[24:25]
	s_waitcnt vmcnt(6)
	s_barrier
	s_setprio 1
	v_mfma_f32_16x16x32_bf16 v[50:53], v[226:229], v[194:197], v[50:53]
	ds_read_b128 v[164:167], v249 offset:32768
	ds_read_b128 v[182:185], v249 offset:33792
	v_mfma_f32_16x16x32_bf16 v[50:53], v[230:233], v[198:201], v[50:53]
	ds_read_b128 v[186:189], v249 offset:34816
	ds_read_b128 v[190:193], v249 offset:35840
	v_mfma_f32_16x16x32_bf16 v[42:45], v[234:237], v[194:197], v[42:45]
	ds_read_b128 v[194:197], v162 offset:32768
	v_mfma_f32_16x16x32_bf16 v[42:45], v[238:241], v[198:201], v[42:45]
	ds_read_b128 v[198:201], v162 offset:33792
	v_mfma_f32_16x16x32_bf16 v[34:37], v[226:229], v[202:205], v[34:37]
	v_mfma_f32_16x16x32_bf16 v[34:37], v[230:233], v[206:209], v[34:37]
	v_mfma_f32_16x16x32_bf16 v[26:29], v[234:237], v[202:205], v[26:29]
	ds_read_b128 v[202:205], v162 offset:34816
	v_mfma_f32_16x16x32_bf16 v[26:29], v[238:241], v[206:209], v[26:29]
	ds_read_b128 v[206:209], v162 offset:35840
	v_mfma_f32_16x16x32_bf16 v[18:21], v[226:229], v[210:213], v[18:21]
	v_mfma_f32_16x16x32_bf16 v[18:21], v[230:233], v[214:217], v[18:21]
	v_mfma_f32_16x16x32_bf16 v[10:13], v[234:237], v[210:213], v[10:13]
	ds_read_b128 v[210:213], v162 offset:36864
	v_mfma_f32_16x16x32_bf16 v[10:13], v[238:241], v[214:217], v[10:13]
	ds_read_b128 v[214:217], v162 offset:37888
	v_mfma_f32_16x16x32_bf16 v[6:9], v[226:229], v[218:221], v[6:9]
	v_mfma_f32_16x16x32_bf16 v[6:9], v[230:233], v[222:225], v[6:9]
	v_mfma_f32_16x16x32_bf16 v[2:5], v[234:237], v[218:221], v[2:5]
	s_barrier
	v_mfma_f32_16x16x32_bf16 v[2:5], v[238:241], v[222:225], v[2:5]
	s_setprio 0
	s_add_i32 s51, 0, 0x18000
	s_add_u32 s24, s76, 0x100000
	s_addc_u32 s25, s77, 0
	s_mov_b32 m0, s93
	ds_read_b128 v[218:221], v162 offset:38912
	ds_read_b128 v[222:225], v162 offset:39936
	global_load_lds_dwordx4 v136, s[24:25]
	s_mov_b32 m0, s94
	s_nop 0
	global_load_lds_dwordx4 v132, s[24:25]
	s_waitcnt lgkmcnt(8)
	s_barrier
; #define PG8_STAGE(bufoff, gbase, voff) do { _Pragma("unroll") for (int _i = 0; _i < 2; ++_i) \
;         __builtin_amdgcn_global_load_lds((const unsigned*)((const char*)(gbase) + (voff)[_i]), (LAS unsigned*)(lds + (bufoff) + ldsw + _i * 8192), 16, 0, 0); } while (0)
; #define PG8_LDA(dst, b, h) do { _Pragma("unroll") for (int m = 0; m < 4; ++m) _Pragma("unroll") for (int k = 0; k < 2; ++k) dst[m][k] = *(const LAS bf16x8*)(lds + PG8_SA(b, h) + aoff + m * 2048 + k * 1024); } while (0)
; #define PG8_LDB(dst, b, h) do { _Pragma("unroll") for (int n = 0; n < 2; ++n) _Pragma("unroll") for (int k = 0; k < 2; ++k) dst[n][k] = *(const LAS bf16x8*)(lds + PG8_SB(b, h) + boff + n * 2048 + k * 1024); } while (0)
; #define PG8_MMA(ai, bj, At, Bt) do { __builtin_amdgcn_s_setprio(1); _Pragma("unroll") for (int m = 0; m < 4; ++m) _Pragma("unroll") for (int n = 0; n < 2; ++n) _Pragma("unroll") for (int k = 0; k < 2; ++k) \
;         acc[ai][bj][m][n] = __builtin_amdgcn_mfma_f32_16x16x32_bf16(Bt[n][k], At[m][k], acc[ai][bj][m][n], 0, 0, 0); __builtin_amdgcn_s_setprio(0); } while (0)
; #define PG8_WAIT_V(n) asm volatile("s_waitcnt vmcnt(" #n ")" ::: "memory")
; #define PG8_WAIT_L(n) asm volatile("s_waitcnt lgkmcnt(" #n ")" ::: "memory")
; #define PG8_BAR __builtin_amdgcn_s_barrier()
; #define PG8_SCHED __builtin_amdgcn_sched_barrier(0)
; template <class Epi, class Sched>
; __device__ __forceinline__ void gemm_phase(LAS unsigned char* lds, const Gemm g, const Sched& S, const Epi& E) {
;     ...
;             PG8_LDB(B1, 1, 1); PG8_STAGE(PG8_SB(1, 0), b3, voffB);
;             PG8_BAR; PG8_WAIT_L(0); PG8_MMA(0, 1, At, B1); PG8_BAR;
;             PG8_LDA(At, 1, 1); PG8_STAGE(PG8_SA(1, 0), a3, voffA);
;             PG8_BAR; PG8_WAIT_L(0); PG8_MMA(1, 0, At, B0); PG8_BAR; PG8_SCHED;
;             PG8_STAGE(PG8_SB(1, 1), b3 + hstep, voffB);
;             PG8_WAIT_V(6); PG8_BAR; PG8_MMA(1, 1, At, B1); PG8_BAR;
;         }
;         if (wr == 0) PG8_BAR;
	s_waitcnt lgkmcnt(0)
	s_setprio 1
	s_waitcnt lgkmcnt(0)
	v_mfma_f32_16x16x32_bf16 v[126:129], v[164:167], v[194:197], v[126:129]
	v_mfma_f32_16x16x32_bf16 v[126:129], v[182:185], v[198:201], v[126:129]
	v_mfma_f32_16x16x32_bf16 v[122:125], v[186:189], v[194:197], v[122:125]
	v_mfma_f32_16x16x32_bf16 v[122:125], v[190:193], v[198:201], v[122:125]
	v_mfma_f32_16x16x32_bf16 v[118:121], v[164:167], v[202:205], v[118:121]
	v_mfma_f32_16x16x32_bf16 v[118:121], v[182:185], v[206:209], v[118:121]
	v_mfma_f32_16x16x32_bf16 v[110:113], v[186:189], v[202:205], v[110:113]
	v_mfma_f32_16x16x32_bf16 v[110:113], v[190:193], v[206:209], v[110:113]
	v_mfma_f32_16x16x32_bf16 v[102:105], v[164:167], v[210:213], v[102:105]
	v_mfma_f32_16x16x32_bf16 v[102:105], v[182:185], v[214:217], v[102:105]
	v_mfma_f32_16x16x32_bf16 v[94:97], v[186:189], v[210:213], v[94:97]
	v_mfma_f32_16x16x32_bf16 v[94:97], v[190:193], v[214:217], v[94:97]
	v_mfma_f32_16x16x32_bf16 v[86:89], v[164:167], v[218:221], v[86:89]
	v_mfma_f32_16x16x32_bf16 v[86:89], v[182:185], v[222:225], v[86:89]
	v_mfma_f32_16x16x32_bf16 v[78:81], v[186:189], v[218:221], v[78:81]
	s_barrier
	v_mfma_f32_16x16x32_bf16 v[78:81], v[190:193], v[222:225], v[78:81]
	s_setprio 0
	s_add_i32 s76, 0, 0x1c000
	s_add_i32 s24, s51, s83
	s_add_i32 m0, s24, 0xffffff80
	ds_read_b128 v[226:229], v249 offset:49152
	ds_read_b128 v[230:233], v249 offset:50176
	ds_read_b128 v[234:237], v249 offset:51200
	ds_read_b128 v[238:241], v249 offset:52224
	global_load_lds_dwordx4 v134, s[48:49] offset:128
	s_add_i32 m0, s24, 0x1f80
	s_nop 0
	global_load_lds_dwordx4 v130, s[48:49] offset:128
	s_barrier
	s_waitcnt lgkmcnt(0)
	s_setprio 1
	s_waitcnt lgkmcnt(0)
	v_mfma_f32_16x16x32_bf16 v[114:117], v[226:229], v[194:197], v[114:117]
	v_mfma_f32_16x16x32_bf16 v[114:117], v[230:233], v[198:201], v[114:117]
	v_mfma_f32_16x16x32_bf16 v[106:109], v[234:237], v[194:197], v[106:109]
	v_mfma_f32_16x16x32_bf16 v[106:109], v[238:241], v[198:201], v[106:109]
	v_mfma_f32_16x16x32_bf16 v[98:101], v[226:229], v[202:205], v[98:101]
	v_mfma_f32_16x16x32_bf16 v[98:101], v[230:233], v[206:209], v[98:101]
	v_mfma_f32_16x16x32_bf16 v[90:93], v[234:237], v[202:205], v[90:93]
	v_mfma_f32_16x16x32_bf16 v[90:93], v[238:241], v[206:209], v[90:93]
	v_mfma_f32_16x16x32_bf16 v[82:85], v[226:229], v[210:213], v[82:85]
	v_mfma_f32_16x16x32_bf16 v[82:85], v[230:233], v[214:217], v[82:85]
	v_mfma_f32_16x16x32_bf16 v[74:77], v[234:237], v[210:213], v[74:77]
	v_mfma_f32_16x16x32_bf16 v[74:77], v[238:241], v[214:217], v[74:77]
	v_mfma_f32_16x16x32_bf16 v[70:73], v[226:229], v[218:221], v[70:73]
	v_mfma_f32_16x16x32_bf16 v[70:73], v[230:233], v[222:225], v[70:73]
	v_mfma_f32_16x16x32_bf16 v[66:69], v[234:237], v[218:221], v[66:69]
	s_barrier
	v_mfma_f32_16x16x32_bf16 v[66:69], v[238:241], v[222:225], v[66:69]
	s_setprio 0
	s_add_i32 m0, s95, 0xffffff80
	ds_read_b128 v[194:197], v162 offset:49152
	ds_read_b128 v[198:201], v162 offset:50176
	ds_read_b128 v[202:205], v162 offset:51200
	ds_read_b128 v[206:209], v162 offset:52224
	ds_read_b128 v[210:213], v162 offset:53248
	ds_read_b128 v[214:217], v162 offset:54272
	ds_read_b128 v[218:221], v162 offset:55296
	ds_read_b128 v[222:225], v162 offset:56320
	global_load_lds_dwordx4 v136, s[100:101] offset:128
	s_add_i32 m0, s96, 0xffffff80
	s_nop 0
	global_load_lds_dwordx4 v132, s[100:101] offset:128
	s_waitcnt vmcnt(8)
	s_barrier
	s_waitcnt lgkmcnt(0)
	s_setprio 1
	s_waitcnt lgkmcnt(0)
	v_mfma_f32_16x16x32_bf16 v[62:65], v[164:167], v[194:197], v[62:65]
	v_mfma_f32_16x16x32_bf16 v[62:65], v[182:185], v[198:201], v[62:65]
	v_mfma_f32_16x16x32_bf16 v[58:61], v[186:189], v[194:197], v[58:61]
	v_mfma_f32_16x16x32_bf16 v[58:61], v[190:193], v[198:201], v[58:61]
	v_mfma_f32_16x16x32_bf16 v[54:57], v[164:167], v[202:205], v[54:57]
	v_mfma_f32_16x16x32_bf16 v[54:57], v[182:185], v[206:209], v[54:57]
	v_mfma_f32_16x16x32_bf16 v[46:49], v[186:189], v[202:205], v[46:49]
	v_mfma_f32_16x16x32_bf16 v[46:49], v[190:193], v[206:209], v[46:49]
	v_mfma_f32_16x16x32_bf16 v[38:41], v[164:167], v[210:213], v[38:41]
	v_mfma_f32_16x16x32_bf16 v[38:41], v[182:185], v[214:217], v[38:41]
	v_mfma_f32_16x16x32_bf16 v[30:33], v[186:189], v[210:213], v[30:33]
	v_mfma_f32_16x16x32_bf16 v[30:33], v[190:193], v[214:217], v[30:33]
	v_mfma_f32_16x16x32_bf16 v[22:25], v[164:167], v[218:221], v[22:25]
	v_mfma_f32_16x16x32_bf16 v[22:25], v[182:185], v[222:225], v[22:25]
	v_mfma_f32_16x16x32_bf16 v[14:17], v[186:189], v[218:221], v[14:17]
	s_barrier
	v_mfma_f32_16x16x32_bf16 v[14:17], v[190:193], v[222:225], v[14:17]
	s_setprio 0
	s_add_u32 s24, s48, 0x100080
	s_addc_u32 s25, s49, 0
	s_add_i32 s48, s76, s83
	s_mov_b32 m0, s48
	s_nop 0
	global_load_lds_dwordx4 v134, s[24:25]
	s_add_i32 m0, s48, 0x2000
	s_nop 0
	global_load_lds_dwordx4 v130, s[24:25]
	s_add_i32 s98, s98, 2
	s_add_u32 s35, s35, 0x100
	s_addc_u32 s50, s50, 0
	s_add_u32 s0, s0, 0x100
	s_addc_u32 s1, s1, 0
	s_add_u32 s24, s0, 0xfff00080
	s_addc_u32 s25, s1, -1
	s_add_i32 s51, 0, 0x10000
	s_cmp_eq_u32 s98, 60
	s_cselect_b32 s77, s47, s25
	s_cselect_b32 s76, s46, s24
	s_cselect_b32 s49, s43, s50
	s_cselect_b32 s48, s45, s35
	s_waitcnt vmcnt(6)
	s_barrier
	s_setprio 1
	v_mfma_f32_16x16x32_bf16 v[50:53], v[226:229], v[194:197], v[50:53]
	ds_read_b128 v[164:167], v249
	ds_read_b128 v[182:185], v249 offset:1024
	v_mfma_f32_16x16x32_bf16 v[50:53], v[230:233], v[198:201], v[50:53]
	ds_read_b128 v[186:189], v249 offset:2048
	ds_read_b128 v[190:193], v249 offset:3072
	v_mfma_f32_16x16x32_bf16 v[42:45], v[234:237], v[194:197], v[42:45]
	ds_read_b128 v[194:197], v162
	v_mfma_f32_16x16x32_bf16 v[42:45], v[238:241], v[198:201], v[42:45]
	ds_read_b128 v[198:201], v162 offset:1024
	v_mfma_f32_16x16x32_bf16 v[34:37], v[226:229], v[202:205], v[34:37]
	v_mfma_f32_16x16x32_bf16 v[34:37], v[230:233], v[206:209], v[34:37]
	v_mfma_f32_16x16x32_bf16 v[26:29], v[234:237], v[202:205], v[26:29]
	ds_read_b128 v[202:205], v162 offset:2048
	v_mfma_f32_16x16x32_bf16 v[26:29], v[238:241], v[206:209], v[26:29]
	ds_read_b128 v[206:209], v162 offset:3072
	v_mfma_f32_16x16x32_bf16 v[18:21], v[226:229], v[210:213], v[18:21]
	v_mfma_f32_16x16x32_bf16 v[18:21], v[230:233], v[214:217], v[18:21]
	v_mfma_f32_16x16x32_bf16 v[10:13], v[234:237], v[210:213], v[10:13]
	ds_read_b128 v[210:213], v162 offset:4096
	v_mfma_f32_16x16x32_bf16 v[10:13], v[238:241], v[214:217], v[10:13]
	ds_read_b128 v[214:217], v162 offset:5120
	v_mfma_f32_16x16x32_bf16 v[6:9], v[226:229], v[218:221], v[6:9]
	v_mfma_f32_16x16x32_bf16 v[6:9], v[230:233], v[222:225], v[6:9]
	v_mfma_f32_16x16x32_bf16 v[2:5], v[234:237], v[218:221], v[2:5]
	s_barrier
	v_mfma_f32_16x16x32_bf16 v[2:5], v[238:241], v[222:225], v[2:5]
	s_setprio 0
	s_cmp_gt_u32 s98, 61
	s_cbranch_scc0 .LBB0_627
	s_waitcnt lgkmcnt(0)
	s_and_b64 vcc, exec, s[40:41]
	s_cbranch_vccz .LBB0_630
	s_barrier
